# norm phases keep two rows in flight per wave; conv start rotation; A2a next K tile prefetched to registers
# speedup vs baseline: 1.0271x; 1.0062x over previous
; DI unsigned cvtpk(float lo, float hi) { f32x2 v = {lo, hi}; bf16x2_t b = __builtin_convertvector(v, bf16x2_t); return __builtin_bit_cast(unsigned, b); }
; DI void norm_rows(const float* src, const float* gain, bf16_t* HN, int gw, int NGW, int lane) {
;     for (int mrow_ = gw; mrow_ < MTOK * REP_NORM; mrow_ += NGW) {
;         const int mrow = mrow_ & (MTOK - 1);
;         const f32x4* xr = (const f32x4*)(src + (size_t)mrow * DM) + lane;
;         f32x4 v[4]; float ss = 0.f;
; #pragma unroll
;         for (int j = 0; j < 4; ++j) { v[j] = xr[64 * j]; ss += (v[j].x * v[j].x + v[j].y * v[j].y) + (v[j].z * v[j].z + v[j].w * v[j].w); }
;         const float r = rsqrtf(wave_sum(ss) * (1.f / DM) + EPS);
;         u32x2* o8 = (u32x2*)(HN + (size_t)mrow * DM) + lane;
; #pragma unroll
;         for (int j = 0; j < 4; ++j) { const f32x4 gg = ((const f32x4*)gain)[lane + 64 * j]; u32x2 w; w.x = cvtpk(v[j].x * r * gg.x, v[j].y * r * gg.y); w.y = cvtpk(v[j].z * r * gg.z, v[j].w * r * gg.w); o8[64 * j] = w; }
;     }
.LBB0_36:
	s_mov_b32 s3, s5
	v_mbcnt_lo_u32_b32 v0, -1, v0
	s_add_i32 s3, s3, 0x20040
	v_mbcnt_hi_u32_b32 v10, -1, v0
	v_mov_b32_e32 v0, s3
	ds_read_b32 v2, v0 offset:8
	ds_read_b32 v0, v0 offset:12
	v_readlane_b32 s8, v254, 15
	v_readlane_b32 s9, v254, 16
	s_lshl_b32 s3, s2, 3
	s_lshl_b32 s8, s8, 10
	s_mov_b32 s9, s5
	s_lshl_b32 s20, s13, 3
	v_and_b32_e32 v11, 63, v10
	s_add_i32 s21, s3, s61
	v_writelane_b32 v254, s8, 25
	s_waitcnt lgkmcnt(0)
	v_readfirstlane_b32 s3, v2
	s_waitcnt lgkmcnt(0)
	v_readfirstlane_b32 s4, v0
	v_writelane_b32 v254, s9, 26
	s_cmpk_gt_i32 s21, 0x3fff
	v_lshlrev_b32_e32 v2, 3, v11
	s_cbranch_scc1 .LBB0_40
	v_readlane_b32 s8, v254, 25
	v_readlane_b32 s9, v254, 26
	s_lshl_b64 s[8:9], s[8:9], 2
	s_add_u32 s8, s3, s8
	s_addc_u32 s9, s4, s9
	v_lshlrev_b32_e32 v0, 4, v11
	v_mov_b32_e32 v3, v1
	v_lshl_add_u64 v[4:5], s[0:1], 0, v[0:1]
	v_lshl_add_u64 v[6:7], s[6:7], 0, v[2:3]
	s_mov_b64 s[0:1], 0x1c00000
	v_lshl_add_u64 v[8:9], s[8:9], 0, v[0:1]
	v_readlane_b32 s8, v254, 11
	v_lshl_add_u64 v[6:7], v[6:7], 0, s[0:1]
	s_lshl_b32 s0, s2, 13
	v_readlane_b32 s1, v254, 8
	v_readlane_b32 s9, v254, 12
	s_add_i32 s0, s1, s0
	s_lshl_b32 s1, s13, 13
	s_mov_b32 s2, s21
	s_mov_b32 s5, s9
	v_readlane_b32 s10, v254, 13
	v_readlane_b32 s11, v254, 14
	global_load_dwordx4 v[40:43], v[8:9], off
	global_load_dwordx4 v[44:47], v[8:9], off offset:1024
	global_load_dwordx4 v[48:51], v[8:9], off offset:2048
	global_load_dwordx4 v[52:55], v[8:9], off offset:3072
.LBB0_38:
	s_and_b32 s3, s0, 0xfffc00
	s_lshl_b32 s4, s3, 2
	v_lshl_add_u64 v[24:25], v[4:5], 0, s[4:5]
	global_load_dwordx4 v[12:15], v[24:25], off
	global_load_dwordx4 v[16:19], v[24:25], off offset:1024
	global_load_dwordx4 v[20:23], v[24:25], off offset:2048
	s_nop 0
	global_load_dwordx4 v[24:27], v[24:25], off offset:3072
.Ln1_top:
	s_lshl_b32 s4, s3, 1
	v_lshl_add_u64 v[32:33], v[6:7], 0, s[4:5]
	s_add_i32 s2, s2, s20
	s_add_i32 s0, s0, s1
	s_cmpk_lt_i32 s2, 0x4000
	s_cbranch_scc0 .Ln1_lastA
	s_and_b32 s3, s0, 0xfffc00
	s_lshl_b32 s4, s3, 2
	v_lshl_add_u64 v[68:69], v[4:5], 0, s[4:5]
	global_load_dwordx4 v[56:59], v[68:69], off
	global_load_dwordx4 v[60:63], v[68:69], off offset:1024
	global_load_dwordx4 v[64:67], v[68:69], off offset:2048
	s_nop 0
	global_load_dwordx4 v[68:71], v[68:69], off offset:3072
	s_waitcnt vmcnt(4)
	v_mul_f32_e32 v0, v13, v13
	v_mul_f32_e32 v3, v15, v15
	v_mul_f32_e32 v34, v17, v17
	v_mul_f32_e32 v35, v19, v19
	v_mul_f32_e32 v36, v21, v21
	v_mul_f32_e32 v37, v23, v23
	v_fmac_f32_e32 v0, v12, v12
	v_fmac_f32_e32 v3, v14, v14
	v_fmac_f32_e32 v34, v16, v16
	v_fmac_f32_e32 v35, v18, v18
	v_mul_f32_e32 v38, v25, v25
	v_mul_f32_e32 v39, v27, v27
	v_fmac_f32_e32 v36, v20, v20
	v_fmac_f32_e32 v37, v22, v22
	v_add_f32_e32 v0, v0, v3
	v_add_f32_e32 v3, v34, v35
	v_fmac_f32_e32 v38, v24, v24
	v_fmac_f32_e32 v39, v26, v26
	v_add_f32_e32 v34, v36, v37
	v_add_f32_e32 v0, v0, v3
	v_add_f32_e32 v35, v38, v39
	v_add_f32_e32 v0, v0, v34
	v_add_f32_e32 v0, v0, v35
	ds_swizzle_b32 v3, v0 offset:swizzle(SWAP,1)
	s_waitcnt lgkmcnt(0)
	v_add_f32_e32 v0, v0, v3
	ds_swizzle_b32 v3, v0 offset:swizzle(SWAP,2)
	s_waitcnt lgkmcnt(0)
	v_add_f32_e32 v0, v0, v3
	ds_swizzle_b32 v3, v0 offset:swizzle(SWAP,4)
	s_waitcnt lgkmcnt(0)
	v_add_f32_e32 v0, v0, v3
	ds_swizzle_b32 v3, v0 offset:swizzle(SWAP,8)
	s_waitcnt lgkmcnt(0)
	v_add_f32_e32 v0, v0, v3
	ds_swizzle_b32 v3, v0 offset:swizzle(SWAP,16)
	s_waitcnt lgkmcnt(0)
	v_add_f32_e32 v0, v0, v3
	v_mov_b32_e32 v3, v0
	s_nop 1
	v_permlane32_swap_b32_e32 v0, v3
	v_add_f32_e32 v0, v0, v3
	v_fmamk_f32 v0, v0, 0x3a800000, v156
	v_mul_f32_e32 v3, 0x4b800000, v0
	v_cmp_gt_f32_e32 vcc, s64, v0
	s_nop 1
	v_cndmask_b32_e32 v0, v0, v3, vcc
	v_rsq_f32_e32 v0, v0
	s_nop 0
	v_mul_f32_e32 v3, 0x45800000, v0
	v_cndmask_b32_e32 v0, v0, v3, vcc
	v_pk_mul_f32 v[12:13], v[12:13], v[0:1] op_sel_hi:[1,0]
	v_pk_mul_f32 v[14:15], v[14:15], v[0:1] op_sel_hi:[1,0]
	v_pk_mul_f32 v[12:13], v[40:41], v[12:13]
	v_pk_mul_f32 v[14:15], v[42:43], v[14:15]
	v_cvt_pk_bf16_f32 v12, v12, v13
	v_cvt_pk_bf16_f32 v13, v14, v15
	global_store_dwordx2 v[32:33], v[12:13], off
	v_pk_mul_f32 v[16:17], v[16:17], v[0:1] op_sel_hi:[1,0]
	v_pk_mul_f32 v[18:19], v[18:19], v[0:1] op_sel_hi:[1,0]
	v_pk_mul_f32 v[16:17], v[44:45], v[16:17]
	v_pk_mul_f32 v[18:19], v[46:47], v[18:19]
	v_cvt_pk_bf16_f32 v16, v16, v17
	v_cvt_pk_bf16_f32 v17, v18, v19
	global_store_dwordx2 v[32:33], v[16:17], off offset:512
	v_pk_mul_f32 v[20:21], v[20:21], v[0:1] op_sel_hi:[1,0]
	v_pk_mul_f32 v[22:23], v[22:23], v[0:1] op_sel_hi:[1,0]
	v_pk_mul_f32 v[20:21], v[48:49], v[20:21]
	v_pk_mul_f32 v[22:23], v[50:51], v[22:23]
	v_cvt_pk_bf16_f32 v20, v20, v21
	v_cvt_pk_bf16_f32 v21, v22, v23
	global_store_dwordx2 v[32:33], v[20:21], off offset:1024
	v_pk_mul_f32 v[24:25], v[24:25], v[0:1] op_sel_hi:[1,0]
	v_pk_mul_f32 v[26:27], v[26:27], v[0:1] op_sel_hi:[1,0]
	v_pk_mul_f32 v[24:25], v[52:53], v[24:25]
	v_pk_mul_f32 v[26:27], v[54:55], v[26:27]
	v_cvt_pk_bf16_f32 v24, v24, v25
	v_cvt_pk_bf16_f32 v25, v26, v27
	global_store_dwordx2 v[32:33], v[24:25], off offset:1536
	s_lshl_b32 s4, s3, 1
	v_lshl_add_u64 v[72:73], v[6:7], 0, s[4:5]
	s_add_i32 s2, s2, s20
	s_add_i32 s0, s0, s1
	s_cmpk_lt_i32 s2, 0x4000
	s_cbranch_scc0 .Ln1_lastB
; DI unsigned cvtpk(float lo, float hi) { f32x2 v = {lo, hi}; bf16x2_t b = __builtin_convertvector(v, bf16x2_t); return __builtin_bit_cast(unsigned, b); }
; DI void norm_rows(const float* src, const float* gain, bf16_t* HN, int gw, int NGW, int lane) {
;     for (int mrow_ = gw; mrow_ < MTOK * REP_NORM; mrow_ += NGW) {
;         const int mrow = mrow_ & (MTOK - 1);
;         const f32x4* xr = (const f32x4*)(src + (size_t)mrow * DM) + lane;
;         f32x4 v[4]; float ss = 0.f;
; #pragma unroll
;         for (int j = 0; j < 4; ++j) { v[j] = xr[64 * j]; ss += (v[j].x * v[j].x + v[j].y * v[j].y) + (v[j].z * v[j].z + v[j].w * v[j].w); }
;         const float r = rsqrtf(wave_sum(ss) * (1.f / DM) + EPS);
;         u32x2* o8 = (u32x2*)(HN + (size_t)mrow * DM) + lane;
; #pragma unroll
;         for (int j = 0; j < 4; ++j) { const f32x4 gg = ((const f32x4*)gain)[lane + 64 * j]; u32x2 w; w.x = cvtpk(v[j].x * r * gg.x, v[j].y * r * gg.y); w.y = cvtpk(v[j].z * r * gg.z, v[j].w * r * gg.w); o8[64 * j] = w; }
;     }
	s_and_b32 s3, s0, 0xfffc00
	s_lshl_b32 s4, s3, 2
	v_lshl_add_u64 v[24:25], v[4:5], 0, s[4:5]
	global_load_dwordx4 v[12:15], v[24:25], off
	global_load_dwordx4 v[16:19], v[24:25], off offset:1024
	global_load_dwordx4 v[20:23], v[24:25], off offset:2048
	s_nop 0
	global_load_dwordx4 v[24:27], v[24:25], off offset:3072
	s_waitcnt vmcnt(4)
	v_mul_f32_e32 v0, v57, v57
	v_mul_f32_e32 v3, v59, v59
	v_mul_f32_e32 v34, v61, v61
	v_mul_f32_e32 v35, v63, v63
	v_mul_f32_e32 v36, v65, v65
	v_mul_f32_e32 v37, v67, v67
	v_fmac_f32_e32 v0, v56, v56
	v_fmac_f32_e32 v3, v58, v58
	v_fmac_f32_e32 v34, v60, v60
	v_fmac_f32_e32 v35, v62, v62
	v_mul_f32_e32 v38, v69, v69
	v_mul_f32_e32 v39, v71, v71
	v_fmac_f32_e32 v36, v64, v64
	v_fmac_f32_e32 v37, v66, v66
	v_add_f32_e32 v0, v0, v3
	v_add_f32_e32 v3, v34, v35
	v_fmac_f32_e32 v38, v68, v68
	v_fmac_f32_e32 v39, v70, v70
	v_add_f32_e32 v34, v36, v37
	v_add_f32_e32 v0, v0, v3
	v_add_f32_e32 v35, v38, v39
	v_add_f32_e32 v0, v0, v34
	v_add_f32_e32 v0, v0, v35
	ds_swizzle_b32 v3, v0 offset:swizzle(SWAP,1)
	s_waitcnt lgkmcnt(0)
	v_add_f32_e32 v0, v0, v3
	ds_swizzle_b32 v3, v0 offset:swizzle(SWAP,2)
	s_waitcnt lgkmcnt(0)
	v_add_f32_e32 v0, v0, v3
	ds_swizzle_b32 v3, v0 offset:swizzle(SWAP,4)
	s_waitcnt lgkmcnt(0)
	v_add_f32_e32 v0, v0, v3
	ds_swizzle_b32 v3, v0 offset:swizzle(SWAP,8)
	s_waitcnt lgkmcnt(0)
	v_add_f32_e32 v0, v0, v3
	ds_swizzle_b32 v3, v0 offset:swizzle(SWAP,16)
	s_waitcnt lgkmcnt(0)
	v_add_f32_e32 v0, v0, v3
	v_mov_b32_e32 v3, v0
	s_nop 1
	v_permlane32_swap_b32_e32 v0, v3
	v_add_f32_e32 v0, v0, v3
	v_fmamk_f32 v0, v0, 0x3a800000, v156
	v_mul_f32_e32 v3, 0x4b800000, v0
	v_cmp_gt_f32_e32 vcc, s64, v0
	s_nop 1
	v_cndmask_b32_e32 v0, v0, v3, vcc
	v_rsq_f32_e32 v0, v0
	s_nop 0
	v_mul_f32_e32 v3, 0x45800000, v0
	v_cndmask_b32_e32 v0, v0, v3, vcc
	v_pk_mul_f32 v[56:57], v[56:57], v[0:1] op_sel_hi:[1,0]
	v_pk_mul_f32 v[58:59], v[58:59], v[0:1] op_sel_hi:[1,0]
	v_pk_mul_f32 v[56:57], v[40:41], v[56:57]
	v_pk_mul_f32 v[58:59], v[42:43], v[58:59]
	v_cvt_pk_bf16_f32 v56, v56, v57
	v_cvt_pk_bf16_f32 v57, v58, v59
	global_store_dwordx2 v[72:73], v[56:57], off
	v_pk_mul_f32 v[60:61], v[60:61], v[0:1] op_sel_hi:[1,0]
	v_pk_mul_f32 v[62:63], v[62:63], v[0:1] op_sel_hi:[1,0]
	v_pk_mul_f32 v[60:61], v[44:45], v[60:61]
	v_pk_mul_f32 v[62:63], v[46:47], v[62:63]
	v_cvt_pk_bf16_f32 v60, v60, v61
	v_cvt_pk_bf16_f32 v61, v62, v63
	global_store_dwordx2 v[72:73], v[60:61], off offset:512
	v_pk_mul_f32 v[64:65], v[64:65], v[0:1] op_sel_hi:[1,0]
	v_pk_mul_f32 v[66:67], v[66:67], v[0:1] op_sel_hi:[1,0]
	v_pk_mul_f32 v[64:65], v[48:49], v[64:65]
	v_pk_mul_f32 v[66:67], v[50:51], v[66:67]
	v_cvt_pk_bf16_f32 v64, v64, v65
	v_cvt_pk_bf16_f32 v65, v66, v67
	global_store_dwordx2 v[72:73], v[64:65], off offset:1024
	v_pk_mul_f32 v[68:69], v[68:69], v[0:1] op_sel_hi:[1,0]
	v_pk_mul_f32 v[70:71], v[70:71], v[0:1] op_sel_hi:[1,0]
	v_pk_mul_f32 v[68:69], v[52:53], v[68:69]
	v_pk_mul_f32 v[70:71], v[54:55], v[70:71]
	v_cvt_pk_bf16_f32 v68, v68, v69
	v_cvt_pk_bf16_f32 v69, v70, v71
	global_store_dwordx2 v[72:73], v[68:69], off offset:1536
	s_branch .Ln1_top
; DI unsigned cvtpk(float lo, float hi) { f32x2 v = {lo, hi}; bf16x2_t b = __builtin_convertvector(v, bf16x2_t); return __builtin_bit_cast(unsigned, b); }
; DI void norm_rows(const float* src, const float* gain, bf16_t* HN, int gw, int NGW, int lane) {
;     for (int mrow_ = gw; mrow_ < MTOK * REP_NORM; mrow_ += NGW) {
;         const int mrow = mrow_ & (MTOK - 1);
;         const f32x4* xr = (const f32x4*)(src + (size_t)mrow * DM) + lane;
;         f32x4 v[4]; float ss = 0.f;
; #pragma unroll
;         for (int j = 0; j < 4; ++j) { v[j] = xr[64 * j]; ss += (v[j].x * v[j].x + v[j].y * v[j].y) + (v[j].z * v[j].z + v[j].w * v[j].w); }
;         const float r = rsqrtf(wave_sum(ss) * (1.f / DM) + EPS);
;         u32x2* o8 = (u32x2*)(HN + (size_t)mrow * DM) + lane;
; #pragma unroll
;         for (int j = 0; j < 4; ++j) { const f32x4 gg = ((const f32x4*)gain)[lane + 64 * j]; u32x2 w; w.x = cvtpk(v[j].x * r * gg.x, v[j].y * r * gg.y); w.y = cvtpk(v[j].z * r * gg.z, v[j].w * r * gg.w); o8[64 * j] = w; }
;     }
.Ln1_lastA:
	s_waitcnt vmcnt(0)
	v_mul_f32_e32 v0, v13, v13
	v_mul_f32_e32 v3, v15, v15
	v_mul_f32_e32 v34, v17, v17
	v_mul_f32_e32 v35, v19, v19
	v_mul_f32_e32 v36, v21, v21
	v_mul_f32_e32 v37, v23, v23
	v_fmac_f32_e32 v0, v12, v12
	v_fmac_f32_e32 v3, v14, v14
	v_fmac_f32_e32 v34, v16, v16
	v_fmac_f32_e32 v35, v18, v18
	v_mul_f32_e32 v38, v25, v25
	v_mul_f32_e32 v39, v27, v27
	v_fmac_f32_e32 v36, v20, v20
	v_fmac_f32_e32 v37, v22, v22
	v_add_f32_e32 v0, v0, v3
	v_add_f32_e32 v3, v34, v35
	v_fmac_f32_e32 v38, v24, v24
	v_fmac_f32_e32 v39, v26, v26
	v_add_f32_e32 v34, v36, v37
	v_add_f32_e32 v0, v0, v3
	v_add_f32_e32 v35, v38, v39
	v_add_f32_e32 v0, v0, v34
	v_add_f32_e32 v0, v0, v35
	ds_swizzle_b32 v3, v0 offset:swizzle(SWAP,1)
	s_waitcnt lgkmcnt(0)
	v_add_f32_e32 v0, v0, v3
	ds_swizzle_b32 v3, v0 offset:swizzle(SWAP,2)
	s_waitcnt lgkmcnt(0)
	v_add_f32_e32 v0, v0, v3
	ds_swizzle_b32 v3, v0 offset:swizzle(SWAP,4)
	s_waitcnt lgkmcnt(0)
	v_add_f32_e32 v0, v0, v3
	ds_swizzle_b32 v3, v0 offset:swizzle(SWAP,8)
	s_waitcnt lgkmcnt(0)
	v_add_f32_e32 v0, v0, v3
	ds_swizzle_b32 v3, v0 offset:swizzle(SWAP,16)
	s_waitcnt lgkmcnt(0)
	v_add_f32_e32 v0, v0, v3
	v_mov_b32_e32 v3, v0
	s_nop 1
	v_permlane32_swap_b32_e32 v0, v3
	v_add_f32_e32 v0, v0, v3
	v_fmamk_f32 v0, v0, 0x3a800000, v156
	v_mul_f32_e32 v3, 0x4b800000, v0
	v_cmp_gt_f32_e32 vcc, s64, v0
	s_nop 1
	v_cndmask_b32_e32 v0, v0, v3, vcc
	v_rsq_f32_e32 v0, v0
	s_nop 0
	v_mul_f32_e32 v3, 0x45800000, v0
	v_cndmask_b32_e32 v0, v0, v3, vcc
	v_pk_mul_f32 v[12:13], v[12:13], v[0:1] op_sel_hi:[1,0]
	v_pk_mul_f32 v[14:15], v[14:15], v[0:1] op_sel_hi:[1,0]
	v_pk_mul_f32 v[12:13], v[40:41], v[12:13]
	v_pk_mul_f32 v[14:15], v[42:43], v[14:15]
	v_cvt_pk_bf16_f32 v12, v12, v13
	v_cvt_pk_bf16_f32 v13, v14, v15
	global_store_dwordx2 v[32:33], v[12:13], off
	v_pk_mul_f32 v[16:17], v[16:17], v[0:1] op_sel_hi:[1,0]
	v_pk_mul_f32 v[18:19], v[18:19], v[0:1] op_sel_hi:[1,0]
	v_pk_mul_f32 v[16:17], v[44:45], v[16:17]
	v_pk_mul_f32 v[18:19], v[46:47], v[18:19]
	v_cvt_pk_bf16_f32 v16, v16, v17
	v_cvt_pk_bf16_f32 v17, v18, v19
	global_store_dwordx2 v[32:33], v[16:17], off offset:512
	v_pk_mul_f32 v[20:21], v[20:21], v[0:1] op_sel_hi:[1,0]
	v_pk_mul_f32 v[22:23], v[22:23], v[0:1] op_sel_hi:[1,0]
	v_pk_mul_f32 v[20:21], v[48:49], v[20:21]
	v_pk_mul_f32 v[22:23], v[50:51], v[22:23]
	v_cvt_pk_bf16_f32 v20, v20, v21
	v_cvt_pk_bf16_f32 v21, v22, v23
	global_store_dwordx2 v[32:33], v[20:21], off offset:1024
	v_pk_mul_f32 v[24:25], v[24:25], v[0:1] op_sel_hi:[1,0]
	v_pk_mul_f32 v[26:27], v[26:27], v[0:1] op_sel_hi:[1,0]
	v_pk_mul_f32 v[24:25], v[52:53], v[24:25]
	v_pk_mul_f32 v[26:27], v[54:55], v[26:27]
	v_cvt_pk_bf16_f32 v24, v24, v25
	v_cvt_pk_bf16_f32 v25, v26, v27
	global_store_dwordx2 v[32:33], v[24:25], off offset:1536
	s_branch .Ln1_done
.Ln1_lastB:
	s_waitcnt vmcnt(0)
	v_mul_f32_e32 v0, v57, v57
	v_mul_f32_e32 v3, v59, v59
	v_mul_f32_e32 v34, v61, v61
	v_mul_f32_e32 v35, v63, v63
	v_mul_f32_e32 v36, v65, v65
	v_mul_f32_e32 v37, v67, v67
	v_fmac_f32_e32 v0, v56, v56
	v_fmac_f32_e32 v3, v58, v58
	v_fmac_f32_e32 v34, v60, v60
	v_fmac_f32_e32 v35, v62, v62
	v_mul_f32_e32 v38, v69, v69
	v_mul_f32_e32 v39, v71, v71
	v_fmac_f32_e32 v36, v64, v64
	v_fmac_f32_e32 v37, v66, v66
	v_add_f32_e32 v0, v0, v3
	v_add_f32_e32 v3, v34, v35
	v_fmac_f32_e32 v38, v68, v68
	v_fmac_f32_e32 v39, v70, v70
	v_add_f32_e32 v34, v36, v37
	v_add_f32_e32 v0, v0, v3
	v_add_f32_e32 v35, v38, v39
	v_add_f32_e32 v0, v0, v34
	v_add_f32_e32 v0, v0, v35
	ds_swizzle_b32 v3, v0 offset:swizzle(SWAP,1)
	s_waitcnt lgkmcnt(0)
	v_add_f32_e32 v0, v0, v3
	ds_swizzle_b32 v3, v0 offset:swizzle(SWAP,2)
	s_waitcnt lgkmcnt(0)
	v_add_f32_e32 v0, v0, v3
	ds_swizzle_b32 v3, v0 offset:swizzle(SWAP,4)
	s_waitcnt lgkmcnt(0)
	v_add_f32_e32 v0, v0, v3
	ds_swizzle_b32 v3, v0 offset:swizzle(SWAP,8)
	s_waitcnt lgkmcnt(0)
	v_add_f32_e32 v0, v0, v3
	ds_swizzle_b32 v3, v0 offset:swizzle(SWAP,16)
	s_waitcnt lgkmcnt(0)
	v_add_f32_e32 v0, v0, v3
	v_mov_b32_e32 v3, v0
	s_nop 1
	v_permlane32_swap_b32_e32 v0, v3
	v_add_f32_e32 v0, v0, v3
	v_fmamk_f32 v0, v0, 0x3a800000, v156
	v_mul_f32_e32 v3, 0x4b800000, v0
	v_cmp_gt_f32_e32 vcc, s64, v0
	s_nop 1
	v_cndmask_b32_e32 v0, v0, v3, vcc
	v_rsq_f32_e32 v0, v0
	s_nop 0
	v_mul_f32_e32 v3, 0x45800000, v0
	v_cndmask_b32_e32 v0, v0, v3, vcc
	v_pk_mul_f32 v[56:57], v[56:57], v[0:1] op_sel_hi:[1,0]
	v_pk_mul_f32 v[58:59], v[58:59], v[0:1] op_sel_hi:[1,0]
	v_pk_mul_f32 v[56:57], v[40:41], v[56:57]
	v_pk_mul_f32 v[58:59], v[42:43], v[58:59]
	v_cvt_pk_bf16_f32 v56, v56, v57
	v_cvt_pk_bf16_f32 v57, v58, v59
	global_store_dwordx2 v[72:73], v[56:57], off
	v_pk_mul_f32 v[60:61], v[60:61], v[0:1] op_sel_hi:[1,0]
	v_pk_mul_f32 v[62:63], v[62:63], v[0:1] op_sel_hi:[1,0]
	v_pk_mul_f32 v[60:61], v[44:45], v[60:61]
	v_pk_mul_f32 v[62:63], v[46:47], v[62:63]
	v_cvt_pk_bf16_f32 v60, v60, v61
	v_cvt_pk_bf16_f32 v61, v62, v63
	global_store_dwordx2 v[72:73], v[60:61], off offset:512
	v_pk_mul_f32 v[64:65], v[64:65], v[0:1] op_sel_hi:[1,0]
	v_pk_mul_f32 v[66:67], v[66:67], v[0:1] op_sel_hi:[1,0]
	v_pk_mul_f32 v[64:65], v[48:49], v[64:65]
	v_pk_mul_f32 v[66:67], v[50:51], v[66:67]
	v_cvt_pk_bf16_f32 v64, v64, v65
	v_cvt_pk_bf16_f32 v65, v66, v67
	global_store_dwordx2 v[72:73], v[64:65], off offset:1024
	v_pk_mul_f32 v[68:69], v[68:69], v[0:1] op_sel_hi:[1,0]
	v_pk_mul_f32 v[70:71], v[70:71], v[0:1] op_sel_hi:[1,0]
	v_pk_mul_f32 v[68:69], v[52:53], v[68:69]
	v_pk_mul_f32 v[70:71], v[54:55], v[70:71]
	v_cvt_pk_bf16_f32 v68, v68, v69
	v_cvt_pk_bf16_f32 v69, v70, v71
	global_store_dwordx2 v[72:73], v[68:69], off offset:1536
.Ln1_done:
	v_writelane_b32 v254, s4, 11
	s_nop 1
	v_writelane_b32 v254, s5, 12
	v_writelane_b32 v254, s6, 13
	v_writelane_b32 v254, s7, 14

; #define LAS __attribute__((address_space(3)))
; template <class F>
; DI void conv_matrix(const F& f, int K, int Nd, bf16_t* dst, LAS float* scr, int gw, int NGW, int lane) {
;     const int nblk = Nd / 32, items = (K / 64) * nblk;
;     for (int it = gw; it < items; it += NGW) {
;         const int kb = it / nblk, nb = it % nblk, k0 = 64 * kb, n0 = 32 * nb;
; DI void conv_ffn(const float* wg, const float* wu, const float* wd, bf16_t* Wgu, bf16_t* Wd, LAS float* scr, int gw, int NGW, int lane) {
;     conv_matrix(FGU{wg, wu}, DM, 2 * DFF, Wgu, scr, gw, NGW, lane);
;     conv_matrix(FPlain{wd, DM}, DFF, DM, Wd, scr, gw, NGW, lane);
.LBB0_51:
	s_sub_i32 s100, s21, 768
	s_cmp_lt_i32 s100, 0
	s_cselect_b32 s101, s20, 0
	s_add_i32 s100, s100, s101
	s_cmp_lt_i32 s100, 0
	s_cselect_b32 s100, s21, s100
	s_cmpk_gt_i32 s100, 0x57f
	s_cbranch_scc1 .LBB0_54
	v_mov_b32_e32 v3, v1
	v_lshl_add_u64 v[4:5], s[6:7], 0, v[2:3]
	s_mov_b64 s[0:1], 0xc00000
	v_lshl_add_u64 v[4:5], v[4:5], 0, s[0:1]
	v_readlane_b32 s0, v254, 27
	s_mul_i32 s2, s100, 0x16000
	s_add_u32 s0, s4, s0
	v_mov_b32_e32 v0, s2
	s_movk_i32 s2, 0xb00
	s_addc_u32 s1, s5, 0
	v_mad_u32_u24 v0, v14, s2, v0
	s_mul_i32 s4, s20, 0x16000
	v_lshl_or_b32 v3, s100, 5, v12
	s_lshl_b32 s5, s20, 5
	s_mov_b32 s8, s100

; #define LAS __attribute__((address_space(3)))
; #define PIN(i) gptr(lds, (i))
; template <class F>
; DI void conv_matrix(const F& f, int K, int Nd, bf16_t* dst, LAS float* scr, int gw, int NGW, int lane) {
;     const int nblk = Nd / 32, items = (K / 64) * nblk;
;     for (int it = gw; it < items; it += NGW) {
;         const int kb = it / nblk, nb = it % nblk, k0 = 64 * kb, n0 = 32 * nb;
; __global__ void __launch_bounds__(512) mega_fwd(Params P) {
;     ...
;         conv_matrix(FWin{PIN(6) + (size_t)L * DM * DIN}, DM, NPROJ, Win, scr, gw, NGW, lane);
.LBB0_54:
	v_readlane_b32 s0, v254, 11
	v_readlane_b32 s1, v254, 12
	s_mov_b32 s0, s1
	s_add_i32 s0, s0, 0x20040
	v_mov_b32_e32 v0, s0
	ds_read_b32 v3, v0 offset:48
	ds_read_b32 v0, v0 offset:52
	s_sub_i32 s100, s21, 128
	s_cmp_lt_i32 s100, 0
	s_cselect_b32 s101, s20, 0
	s_add_i32 s100, s100, s101
	s_cmp_lt_i32 s100, 0
	s_cselect_b32 s100, s21, s100
	s_cmpk_gt_i32 s100, 0x4ff
	v_readlane_b32 s2, v254, 13
	v_readlane_b32 s3, v254, 14
	s_waitcnt lgkmcnt(0)
	v_readfirstlane_b32 s0, v3
	v_readfirstlane_b32 s1, v0
	s_cbranch_scc1 .LBB0_121
	v_readlane_b32 s2, v254, 15
	v_readlane_b32 s3, v254, 16
	s_mul_i32 s2, s2, 0x932000
	v_mov_b32_e32 v3, v1
	s_add_u32 s0, s0, s2
	v_lshl_add_u64 v[4:5], s[6:7], 0, v[2:3]
	s_mov_b64 s[2:3], 0x1200000
	s_addc_u32 s1, s1, 0
	v_lshl_add_u64 v[4:5], v[4:5], 0, s[2:3]
	s_lshl_b32 s2, s100, 5
	s_add_i32 s3, s2, 0xfffffe80
	s_add_i32 s10, s2, 0xfffff9e0
	v_or_b32_e32 v0, s3, v12
	s_addk_i32 s2, 0xfe60
	v_lshlrev_b32_e32 v3, 4, v0
	v_or_b32_e32 v0, s2, v12
	s_lshl_b32 s11, s20, 5
	s_lshl_b32 s12, s20, 9
	v_lshlrev_b32_e32 v6, 3, v0
	s_lshl_b32 s13, s20, 8
	s_mov_b32 s14, s100
	s_branch .LBB0_57

; #define LAS __attribute__((address_space(3)))
; #define PIN(i) gptr(lds, (i))
; template <class F>
; DI void conv_matrix(const F& f, int K, int Nd, bf16_t* dst, LAS float* scr, int gw, int NGW, int lane) {
;     const int nblk = Nd / 32, items = (K / 64) * nblk;
;     for (int it = gw; it < items; it += NGW) {
;         const int kb = it / nblk, nb = it % nblk, k0 = 64 * kb, n0 = 32 * nb;
; __global__ void __launch_bounds__(512) mega_fwd(Params P) {
;     ...
;         conv_matrix(FPlain{PIN(18) + (size_t)L * DM * DM, DM}, DM, DM, Wout, scr, gw, NGW, lane);
.LBB0_121:
	v_readlane_b32 s0, v254, 11
	v_readlane_b32 s1, v254, 12
	s_mov_b32 s0, s1
	s_add_i32 s0, s0, 0x20040
	v_mov_b32_e32 v0, s0
	v_readlane_b32 s2, v254, 13
	v_readlane_b32 s3, v254, 14
	ds_read_b32 v3, v0 offset:144
	ds_read_b32 v0, v0 offset:148
	v_readlane_b32 s2, v254, 15
	v_readlane_b32 s3, v254, 16
	s_mov_b32 s3, s1
	v_writelane_b32 v254, s2, 15
	s_sub_i32 s100, s21, 1408
	s_cmp_lt_i32 s100, 0
	s_cselect_b32 s101, s20, 0
	s_add_i32 s100, s100, s101
	s_cmp_lt_i32 s100, 0
	s_cselect_b32 s100, s21, s100
	s_cmpk_gt_i32 s100, 0x1ff
	s_waitcnt lgkmcnt(0)
	v_readfirstlane_b32 s0, v3
	v_writelane_b32 v254, s3, 16
	v_readfirstlane_b32 s1, v0
	s_cbranch_scc1 .LBB0_124
	v_readlane_b32 s2, v254, 15
	v_readlane_b32 s3, v254, 16
	s_lshl_b64 s[2:3], s[2:3], 22
	s_add_u32 s0, s0, s2
	v_mov_b32_e32 v3, v1
	s_addc_u32 s1, s1, s3
	v_lshl_add_u64 v[4:5], s[6:7], 0, v[2:3]
	s_mov_b64 s[2:3], 0x1700000
	v_lshl_add_u64 v[4:5], v[4:5], 0, s[2:3]
	s_lshl_b32 s4, s100, 5
	s_lshl_b32 s5, s20, 5
	s_mov_b32 s8, s100

; #define LAS __attribute__((address_space(3)))
; #define PIN(i) gptr(lds, (i))
; template <class F>
; DI void conv_matrix(const F& f, int K, int Nd, bf16_t* dst, LAS float* scr, int gw, int NGW, int lane) {
;     const int nblk = Nd / 32, items = (K / 64) * nblk;
;     for (int it = gw; it < items; it += NGW) {
;         const int kb = it / nblk, nb = it % nblk, k0 = 64 * kb, n0 = 32 * nb;
; __global__ void __launch_bounds__(512) mega_fwd(Params P) {
;     ...
;         conv_matrix(FUq{PIN(8) + (size_t)L * 256 * 576}, 256, 768, Wuq, scr, gw, NGW, lane);
.LBB0_124:
	v_readlane_b32 s0, v254, 11
	v_readlane_b32 s1, v254, 12
	s_mov_b32 s0, s1
	s_add_i32 s0, s0, 0x20040
	v_mov_b32_e32 v0, s0
	ds_read_b32 v3, v0 offset:64
	ds_read_b32 v0, v0 offset:68
	s_sub_i32 s100, s21, 1920
	s_cmp_lt_i32 s100, 0
	s_cselect_b32 s101, s20, 0
	s_add_i32 s100, s100, s101
	s_cmp_lt_i32 s100, 0
	s_cselect_b32 s100, s21, s100
	s_cmpk_gt_i32 s100, 0x5f
	v_readlane_b32 s2, v254, 13
	v_readlane_b32 s3, v254, 14
	s_waitcnt lgkmcnt(0)
	v_readfirstlane_b32 s0, v3
	v_readfirstlane_b32 s1, v0
	s_cbranch_scc1 .LBB0_191
	v_readlane_b32 s2, v254, 15
	v_readlane_b32 s3, v254, 16
	s_mul_i32 s2, s2, 0x90000
	v_mov_b32_e32 v3, v1
	s_add_u32 s0, s0, s2
	v_lshl_add_u64 v[4:5], s[6:7], 0, v[2:3]
	s_mov_b64 s[2:3], 0x1a00000
	s_addc_u32 s1, s1, 0
	v_lshl_add_u64 v[4:5], v[4:5], 0, s[2:3]
	s_lshl_b32 s8, s100, 5
	s_lshl_b32 s9, s20, 5
	v_mov_b32_e32 v0, v12
	v_mov_b32_e32 v3, v14
	s_mov_b32 s10, s100
	s_branch .LBB0_127

; #define LAS __attribute__((address_space(3)))
; #define PIN(i) gptr(lds, (i))
; template <class F>
; DI void conv_matrix(const F& f, int K, int Nd, bf16_t* dst, LAS float* scr, int gw, int NGW, int lane) {
;     const int nblk = Nd / 32, items = (K / 64) * nblk;
;     for (int it = gw; it < items; it += NGW) {
;         const int kb = it / nblk, nb = it % nblk, k0 = 64 * kb, n0 = 32 * nb;
; __global__ void __launch_bounds__(512) mega_fwd(Params P) {
;     ...
;         conv_matrix(FUkv{PIN(10) + (size_t)L * 128 * 768}, 128, 768, Wukv, scr, gw, NGW, lane);
.LBB0_191:
	v_readlane_b32 s0, v254, 11
	v_readlane_b32 s1, v254, 12
	s_mov_b32 s0, s1
	s_add_i32 s0, s0, 0x20040
	v_mov_b32_e32 v0, s0
	ds_read_b32 v3, v0 offset:80
	ds_read_b32 v0, v0 offset:84
	s_sub_i32 s100, s21, 128
	s_cmp_lt_i32 s100, 0
	s_cselect_b32 s101, s20, 0
	s_add_i32 s100, s100, s101
	s_cmp_lt_i32 s100, 0
	s_cselect_b32 s100, s21, s100
	s_cmp_gt_i32 s100, 47
	v_readlane_b32 s2, v254, 13
	v_readlane_b32 s3, v254, 14
	s_waitcnt lgkmcnt(0)
	v_readfirstlane_b32 s0, v3
	v_readfirstlane_b32 s1, v0
	s_cbranch_scc1 .LBB0_194
	v_readlane_b32 s2, v254, 15
	v_readlane_b32 s3, v254, 16
	s_mul_i32 s2, s2, 0x60000
	v_mov_b32_e32 v3, v1
	s_add_u32 s0, s0, s2
	v_lshl_add_u64 v[4:5], s[6:7], 0, v[2:3]
	s_mov_b64 s[2:3], 0x1a80000
	v_lshlrev_b32_e32 v0, 1, v12
	s_addc_u32 s1, s1, 0
	v_lshl_add_u64 v[4:5], v[4:5], 0, s[2:3]
	s_lshl_b32 s4, s100, 5
	s_lshl_b32 s5, s20, 5
	v_lshl_or_b32 v0, s100, 6, v0
	s_lshl_b32 s8, s20, 6
	s_mov_b32 s9, s100

; #define LAS __attribute__((address_space(3)))
; #define PIN(i) gptr(lds, (i))
; template <class F>
; DI void conv_matrix(const F& f, int K, int Nd, bf16_t* dst, LAS float* scr, int gw, int NGW, int lane) {
;     const int nblk = Nd / 32, items = (K / 64) * nblk;
;     for (int it = gw; it < items; it += NGW) {
;         const int kb = it / nblk, nb = it % nblk, k0 = 64 * kb, n0 = 32 * nb;
; float tmp_[32];
; #pragma unroll
;         for (int i = 0; i < 32; ++i) tmp_[i] = f(n0 + (lane & 31), k0 + 2 * i + (lane >> 5));
; __global__ void __launch_bounds__(512) mega_fwd(Params P) {
;     ...
;         conv_matrix(FC1{PIN(13) + (size_t)L * 2048 * 128, PIN(16) + (size_t)L * 2048 * 128}, 2048, 256, Wc1, scr, gw, NGW, lane);
.LBB0_194:
	v_readlane_b32 s0, v254, 11
	v_readlane_b32 s1, v254, 12
	s_mov_b32 s0, s1
	s_add_i32 s0, s0, 0x20040
	v_mov_b32_e32 v0, s0
	s_mov_b32 s0, 0
	ds_read_b32 v3, v0 offset:104
	ds_read_b32 v0, v0 offset:108
	s_add_i32 s0, s0, 0x20040
	v_mov_b32_e32 v4, s0
	ds_read_b32 v5, v4 offset:128
	ds_read_b32 v4, v4 offset:132
	v_readlane_b32 s2, v254, 13
	v_readlane_b32 s3, v254, 14
	s_sub_i32 s100, s21, 1792
	s_cmp_lt_i32 s100, 0
	s_cselect_b32 s101, s20, 0
	s_add_i32 s100, s100, s101
	s_cmp_lt_i32 s100, 0
	s_cselect_b32 s100, s21, s100
	s_cmpk_gt_i32 s100, 0xff
	s_waitcnt lgkmcnt(0)
	v_readfirstlane_b32 s0, v3
	v_readfirstlane_b32 s1, v0
	v_readfirstlane_b32 s3, v5
	v_readfirstlane_b32 s2, v4
	s_movk_i32 s68, 0x7f
	s_movk_i32 s69, 0x80
	s_cbranch_scc1 .LBB0_229
	v_readlane_b32 s4, v254, 15
	v_readlane_b32 s5, v254, 16
	s_lshl_b64 s[4:5], s[4:5], 20
	s_add_u32 s0, s0, s4
	s_addc_u32 s1, s1, s5
	s_add_u32 s3, s4, s3
	s_addc_u32 s4, s5, 0
	s_sub_u32 s3, s3, s0
	v_mov_b32_e32 v3, v1
	s_subb_u32 s5, s4, s1
	v_lshl_add_u64 v[4:5], s[6:7], 0, v[2:3]
	v_or_b32_e32 v3, 2, v13
	s_add_u32 s4, s3, 0
	v_lshlrev_b32_e32 v17, 3, v13
	s_mov_b64 s[8:9], 0x1900000
	v_mul_u32_u24_e32 v0, 0x84, v3
	s_addc_u32 s5, s5, s2
	v_lshl_add_u64 v[4:5], v[4:5], 0, s[8:9]
	v_or_b32_e32 v18, 4, v13
	v_or_b32_e32 v19, 6, v13
	v_or_b32_e32 v20, 8, v13
	v_or_b32_e32 v21, 10, v13
	v_or_b32_e32 v22, 12, v13
	v_or_b32_e32 v23, 14, v13
	v_or_b32_e32 v24, 16, v13
	v_or_b32_e32 v25, 18, v13
	v_or_b32_e32 v26, 20, v13
	v_or_b32_e32 v27, 22, v13
	v_or_b32_e32 v28, 24, v13
	v_or_b32_e32 v29, 26, v13
	v_or_b32_e32 v30, 28, v13
	v_or_b32_e32 v31, 30, v13
	v_or_b32_e32 v32, 32, v13
	v_or_b32_e32 v33, 34, v13
	v_or_b32_e32 v34, 36, v13
	v_or_b32_e32 v35, 38, v13
	v_or_b32_e32 v36, 40, v13
	v_or_b32_e32 v37, 42, v13
	v_or_b32_e32 v38, 44, v13
	v_or_b32_e32 v39, 46, v13
	v_or_b32_e32 v40, 48, v13
	v_or_b32_e32 v41, 50, v13
	v_or_b32_e32 v42, 52, v13
	v_or_b32_e32 v43, 54, v13
	v_or_b32_e32 v44, 56, v13
	v_or_b32_e32 v45, 58, v13
	v_or_b32_e32 v46, 60, v13
	v_or_b32_e32 v47, 62, v13
	s_ashr_i64 s[2:3], s[4:5], 2
	v_or_b32_e32 v48, 1, v17
	v_or_b32_e32 v49, 2, v17
	v_or_b32_e32 v50, 3, v17
	v_or_b32_e32 v51, 4, v17
	v_or_b32_e32 v52, 5, v17
	v_or_b32_e32 v53, 6, v17
	v_or_b32_e32 v54, 7, v17
	s_lshl_b32 s10, s100, 5
	s_lshl_b32 s11, s20, 5
	v_add_u32_e32 v55, v8, v0
	v_mov_b32_e32 v56, v12
	v_mov_b32_e32 v57, v14
	s_mov_b32 s12, s100
	s_branch .LBB0_197

; DI unsigned cvtpk(float lo, float hi) { f32x2 v = {lo, hi}; bf16x2_t b = __builtin_convertvector(v, bf16x2_t); return __builtin_bit_cast(unsigned, b); }
; #define PIN(i) gptr(lds, (i))
; DI void norm_rows(const float* src, const float* gain, bf16_t* HN, int gw, int NGW, int lane) {
;     for (int mrow_ = gw; mrow_ < MTOK * REP_NORM; mrow_ += NGW) {
;         const int mrow = mrow_ & (MTOK - 1);
;         const f32x4* xr = (const f32x4*)(src + (size_t)mrow * DM) + lane;
;         f32x4 v[4]; float ss = 0.f;
; #pragma unroll
;         for (int j = 0; j < 4; ++j) { v[j] = xr[64 * j]; ss += (v[j].x * v[j].x + v[j].y * v[j].y) + (v[j].z * v[j].z + v[j].w * v[j].w); }
;         const float r = rsqrtf(wave_sum(ss) * (1.f / DM) + EPS);
;         u32x2* o8 = (u32x2*)(HN + (size_t)mrow * DM) + lane;
; #pragma unroll
;         for (int j = 0; j < 4; ++j) { const f32x4 gg = ((const f32x4*)gain)[lane + 64 * j]; u32x2 w; w.x = cvtpk(v[j].x * r * gg.x, v[j].y * r * gg.y); w.y = cvtpk(v[j].z * r * gg.z, v[j].w * r * gg.w); o8[64 * j] = w; }
;     }
; __global__ void __launch_bounds__(512) mega_fwd(Params P) {
;     ...
;         norm_rows(X, PIN(5) + L * DM, HN, gw, NGW, lane);
.LBB0_536:
	s_or_b64 exec, exec, s[0:1]
	v_readlane_b32 s0, v254, 11
	v_readlane_b32 s1, v254, 12
	s_mov_b32 s0, s1
	s_waitcnt lgkmcnt(0)
	s_barrier
	s_add_i32 s0, s0, 0x20040
	v_mov_b32_e32 v0, s0
	ds_read_b32 v2, v0 offset:200
	ds_read_b32 v0, v0 offset:204
	s_mov_b32 s0, 0
	v_readlane_b32 s3, v254, 14
	s_add_i32 s0, s0, 0x20040
	s_waitcnt lgkmcnt(0)
	v_readfirstlane_b32 s3, v0
	v_mov_b32_e32 v0, s0
	v_readlane_b32 s2, v254, 13
	v_readfirstlane_b32 s2, v2
	ds_read_b32 v2, v0 offset:192
	ds_read_b32 v0, v0 offset:196
	s_mov_b32 s4, s82
	s_mov_b32 s5, s75
	s_mov_b32 s8, 0
	s_mov_b32 s9, 0
	s_waitcnt lgkmcnt(0)
	v_readfirstlane_b32 s1, v0
	v_mov_b32_e32 v0, v1
	s_mov_b32 s9, 0
	v_mbcnt_lo_u32_b32 v0, -1, v0
	s_add_i32 s9, s9, 0x20040
	v_mbcnt_hi_u32_b32 v11, -1, v0
	v_mov_b32_e32 v0, s9
	v_readfirstlane_b32 s0, v2
	ds_read_b32 v2, v0 offset:40
	ds_read_b32 v0, v0 offset:44
	s_lshl_b32 s7, s5, 3
	s_lshl_b32 s6, s4, 3
	v_and_b32_e32 v10, 63, v11
	s_add_i32 s7, s7, s74
	s_waitcnt lgkmcnt(0)
	v_readfirstlane_b32 s9, v2
	v_readfirstlane_b32 s10, v0
	s_cmpk_gt_i32 s7, 0x3fff
	v_lshlrev_b32_e32 v2, 3, v10
	s_movk_i32 s72, 0x300
	s_movk_i32 s73, 0x100
	s_cbranch_scc1 .LBB0_540
	v_readlane_b32 s12, v254, 25
	v_readlane_b32 s13, v254, 26
	s_lshl_b64 s[12:13], s[12:13], 2
	s_add_u32 s12, s9, s12
	v_lshlrev_b32_e32 v0, 4, v10
	v_mov_b32_e32 v3, v1
	s_addc_u32 s13, s10, s13
	v_lshl_add_u64 v[4:5], s[0:1], 0, v[0:1]
	v_lshl_add_u64 v[6:7], s[2:3], 0, v[2:3]
	s_mov_b64 s[0:1], 0x1c00000
	v_lshl_add_u64 v[6:7], v[6:7], 0, s[0:1]
	v_lshl_add_u64 v[8:9], s[12:13], 0, v[0:1]
	s_lshl_b32 s0, s5, 13
	v_readlane_b32 s1, v254, 8
	v_readlane_b32 s12, v254, 11
	s_add_i32 s0, s1, s0
	s_lshl_b32 s1, s4, 13
	s_mov_b32 s4, s7
	s_mov_b32 s9, 0x800000
	v_readlane_b32 s13, v254, 12
	v_readlane_b32 s14, v254, 13
	v_readlane_b32 s15, v254, 14
	global_load_dwordx4 v[40:43], v[8:9], off
	global_load_dwordx4 v[44:47], v[8:9], off offset:1024
	global_load_dwordx4 v[48:51], v[8:9], off offset:2048
	global_load_dwordx4 v[52:55], v[8:9], off offset:3072
.LBB0_538:
	s_and_b32 s5, s0, 0xfffc00
	s_lshl_b32 s12, s5, 2
	v_lshl_add_u64 v[24:25], v[4:5], 0, s[12:13]
	global_load_dwordx4 v[12:15], v[24:25], off
	global_load_dwordx4 v[16:19], v[24:25], off offset:1024
	global_load_dwordx4 v[20:23], v[24:25], off offset:2048
	s_nop 0
	global_load_dwordx4 v[24:27], v[24:25], off offset:3072
.Ln2_top:
	s_lshl_b32 s12, s5, 1
	v_lshl_add_u64 v[32:33], v[6:7], 0, s[12:13]
	s_add_i32 s4, s4, s6
	s_add_i32 s0, s0, s1
	s_cmpk_lt_i32 s4, 0x4000
	s_cbranch_scc0 .Ln2_lastA
	s_and_b32 s5, s0, 0xfffc00
	s_lshl_b32 s12, s5, 2
	v_lshl_add_u64 v[68:69], v[4:5], 0, s[12:13]
	global_load_dwordx4 v[56:59], v[68:69], off
	global_load_dwordx4 v[60:63], v[68:69], off offset:1024
	global_load_dwordx4 v[64:67], v[68:69], off offset:2048
	s_nop 0
	global_load_dwordx4 v[68:71], v[68:69], off offset:3072
	s_waitcnt vmcnt(4)
	v_mul_f32_e32 v0, v13, v13
	v_mul_f32_e32 v3, v15, v15
	v_mul_f32_e32 v34, v17, v17
	v_mul_f32_e32 v35, v19, v19
	v_mul_f32_e32 v36, v21, v21
	v_mul_f32_e32 v37, v23, v23
	v_fmac_f32_e32 v0, v12, v12
	v_fmac_f32_e32 v3, v14, v14
	v_fmac_f32_e32 v34, v16, v16
	v_fmac_f32_e32 v35, v18, v18
	v_mul_f32_e32 v38, v25, v25
	v_mul_f32_e32 v39, v27, v27
	v_fmac_f32_e32 v36, v20, v20
	v_fmac_f32_e32 v37, v22, v22
	v_add_f32_e32 v0, v0, v3
	v_add_f32_e32 v3, v34, v35
	v_fmac_f32_e32 v38, v24, v24
	v_fmac_f32_e32 v39, v26, v26
	v_add_f32_e32 v34, v36, v37
	v_add_f32_e32 v0, v0, v3
	v_add_f32_e32 v35, v38, v39
	v_add_f32_e32 v0, v0, v34
	v_add_f32_e32 v0, v0, v35
	ds_swizzle_b32 v3, v0 offset:swizzle(SWAP,1)
	s_waitcnt lgkmcnt(0)
	v_add_f32_e32 v0, v0, v3
	ds_swizzle_b32 v3, v0 offset:swizzle(SWAP,2)
	s_waitcnt lgkmcnt(0)
	v_add_f32_e32 v0, v0, v3
	ds_swizzle_b32 v3, v0 offset:swizzle(SWAP,4)
	s_waitcnt lgkmcnt(0)
	v_add_f32_e32 v0, v0, v3
	ds_swizzle_b32 v3, v0 offset:swizzle(SWAP,8)
	s_waitcnt lgkmcnt(0)
	v_add_f32_e32 v0, v0, v3
	ds_swizzle_b32 v3, v0 offset:swizzle(SWAP,16)
	s_waitcnt lgkmcnt(0)
	v_add_f32_e32 v0, v0, v3
	v_mov_b32_e32 v3, v0
	s_nop 1
	v_permlane32_swap_b32_e32 v0, v3
	v_add_f32_e32 v0, v0, v3
	v_fmamk_f32 v0, v0, 0x3a800000, v156
	v_mul_f32_e32 v3, 0x4b800000, v0
	v_cmp_gt_f32_e32 vcc, s9, v0
	s_nop 1
	v_cndmask_b32_e32 v0, v0, v3, vcc
	v_rsq_f32_e32 v0, v0
	s_nop 0
	v_mul_f32_e32 v3, 0x45800000, v0
	v_cndmask_b32_e32 v0, v0, v3, vcc
	v_pk_mul_f32 v[12:13], v[12:13], v[0:1] op_sel_hi:[1,0]
	v_pk_mul_f32 v[14:15], v[14:15], v[0:1] op_sel_hi:[1,0]
	v_pk_mul_f32 v[12:13], v[40:41], v[12:13]
	v_pk_mul_f32 v[14:15], v[42:43], v[14:15]
	v_cvt_pk_bf16_f32 v12, v12, v13
	v_cvt_pk_bf16_f32 v13, v14, v15
	global_store_dwordx2 v[32:33], v[12:13], off
	v_pk_mul_f32 v[16:17], v[16:17], v[0:1] op_sel_hi:[1,0]
	v_pk_mul_f32 v[18:19], v[18:19], v[0:1] op_sel_hi:[1,0]
	v_pk_mul_f32 v[16:17], v[44:45], v[16:17]
	v_pk_mul_f32 v[18:19], v[46:47], v[18:19]
	v_cvt_pk_bf16_f32 v16, v16, v17
	v_cvt_pk_bf16_f32 v17, v18, v19
	global_store_dwordx2 v[32:33], v[16:17], off offset:512
	v_pk_mul_f32 v[20:21], v[20:21], v[0:1] op_sel_hi:[1,0]
	v_pk_mul_f32 v[22:23], v[22:23], v[0:1] op_sel_hi:[1,0]
	v_pk_mul_f32 v[20:21], v[48:49], v[20:21]
	v_pk_mul_f32 v[22:23], v[50:51], v[22:23]
	v_cvt_pk_bf16_f32 v20, v20, v21
	v_cvt_pk_bf16_f32 v21, v22, v23
	global_store_dwordx2 v[32:33], v[20:21], off offset:1024
	v_pk_mul_f32 v[24:25], v[24:25], v[0:1] op_sel_hi:[1,0]
	v_pk_mul_f32 v[26:27], v[26:27], v[0:1] op_sel_hi:[1,0]
	v_pk_mul_f32 v[24:25], v[52:53], v[24:25]
	v_pk_mul_f32 v[26:27], v[54:55], v[26:27]
	v_cvt_pk_bf16_f32 v24, v24, v25
	v_cvt_pk_bf16_f32 v25, v26, v27
	global_store_dwordx2 v[32:33], v[24:25], off offset:1536
	s_lshl_b32 s12, s5, 1
	v_lshl_add_u64 v[72:73], v[6:7], 0, s[12:13]
	s_add_i32 s4, s4, s6
	s_add_i32 s0, s0, s1
	s_cmpk_lt_i32 s4, 0x4000
	s_cbranch_scc0 .Ln2_lastB
; DI unsigned cvtpk(float lo, float hi) { f32x2 v = {lo, hi}; bf16x2_t b = __builtin_convertvector(v, bf16x2_t); return __builtin_bit_cast(unsigned, b); }
; DI void norm_rows(const float* src, const float* gain, bf16_t* HN, int gw, int NGW, int lane) {
;     for (int mrow_ = gw; mrow_ < MTOK * REP_NORM; mrow_ += NGW) {
;         const int mrow = mrow_ & (MTOK - 1);
;         const f32x4* xr = (const f32x4*)(src + (size_t)mrow * DM) + lane;
;         f32x4 v[4]; float ss = 0.f;
; #pragma unroll
;         for (int j = 0; j < 4; ++j) { v[j] = xr[64 * j]; ss += (v[j].x * v[j].x + v[j].y * v[j].y) + (v[j].z * v[j].z + v[j].w * v[j].w); }
;         const float r = rsqrtf(wave_sum(ss) * (1.f / DM) + EPS);
;         u32x2* o8 = (u32x2*)(HN + (size_t)mrow * DM) + lane;
; #pragma unroll
;         for (int j = 0; j < 4; ++j) { const f32x4 gg = ((const f32x4*)gain)[lane + 64 * j]; u32x2 w; w.x = cvtpk(v[j].x * r * gg.x, v[j].y * r * gg.y); w.y = cvtpk(v[j].z * r * gg.z, v[j].w * r * gg.w); o8[64 * j] = w; }
;     }
	s_and_b32 s5, s0, 0xfffc00
	s_lshl_b32 s12, s5, 2
	v_lshl_add_u64 v[24:25], v[4:5], 0, s[12:13]
	global_load_dwordx4 v[12:15], v[24:25], off
	global_load_dwordx4 v[16:19], v[24:25], off offset:1024
	global_load_dwordx4 v[20:23], v[24:25], off offset:2048
	s_nop 0
	global_load_dwordx4 v[24:27], v[24:25], off offset:3072
	s_waitcnt vmcnt(4)
	v_mul_f32_e32 v0, v57, v57
	v_mul_f32_e32 v3, v59, v59
	v_mul_f32_e32 v34, v61, v61
	v_mul_f32_e32 v35, v63, v63
	v_mul_f32_e32 v36, v65, v65
	v_mul_f32_e32 v37, v67, v67
	v_fmac_f32_e32 v0, v56, v56
	v_fmac_f32_e32 v3, v58, v58
	v_fmac_f32_e32 v34, v60, v60
	v_fmac_f32_e32 v35, v62, v62
	v_mul_f32_e32 v38, v69, v69
	v_mul_f32_e32 v39, v71, v71
	v_fmac_f32_e32 v36, v64, v64
	v_fmac_f32_e32 v37, v66, v66
	v_add_f32_e32 v0, v0, v3
	v_add_f32_e32 v3, v34, v35
	v_fmac_f32_e32 v38, v68, v68
	v_fmac_f32_e32 v39, v70, v70
	v_add_f32_e32 v34, v36, v37
	v_add_f32_e32 v0, v0, v3
	v_add_f32_e32 v35, v38, v39
	v_add_f32_e32 v0, v0, v34
	v_add_f32_e32 v0, v0, v35
	ds_swizzle_b32 v3, v0 offset:swizzle(SWAP,1)
	s_waitcnt lgkmcnt(0)
	v_add_f32_e32 v0, v0, v3
	ds_swizzle_b32 v3, v0 offset:swizzle(SWAP,2)
	s_waitcnt lgkmcnt(0)
	v_add_f32_e32 v0, v0, v3
	ds_swizzle_b32 v3, v0 offset:swizzle(SWAP,4)
	s_waitcnt lgkmcnt(0)
	v_add_f32_e32 v0, v0, v3
	ds_swizzle_b32 v3, v0 offset:swizzle(SWAP,8)
	s_waitcnt lgkmcnt(0)
	v_add_f32_e32 v0, v0, v3
	ds_swizzle_b32 v3, v0 offset:swizzle(SWAP,16)
	s_waitcnt lgkmcnt(0)
	v_add_f32_e32 v0, v0, v3
	v_mov_b32_e32 v3, v0
	s_nop 1
	v_permlane32_swap_b32_e32 v0, v3
	v_add_f32_e32 v0, v0, v3
	v_fmamk_f32 v0, v0, 0x3a800000, v156
	v_mul_f32_e32 v3, 0x4b800000, v0
	v_cmp_gt_f32_e32 vcc, s9, v0
	s_nop 1
	v_cndmask_b32_e32 v0, v0, v3, vcc
	v_rsq_f32_e32 v0, v0
	s_nop 0
	v_mul_f32_e32 v3, 0x45800000, v0
	v_cndmask_b32_e32 v0, v0, v3, vcc
	v_pk_mul_f32 v[56:57], v[56:57], v[0:1] op_sel_hi:[1,0]
	v_pk_mul_f32 v[58:59], v[58:59], v[0:1] op_sel_hi:[1,0]
	v_pk_mul_f32 v[56:57], v[40:41], v[56:57]
	v_pk_mul_f32 v[58:59], v[42:43], v[58:59]
	v_cvt_pk_bf16_f32 v56, v56, v57
	v_cvt_pk_bf16_f32 v57, v58, v59
	global_store_dwordx2 v[72:73], v[56:57], off
	v_pk_mul_f32 v[60:61], v[60:61], v[0:1] op_sel_hi:[1,0]
	v_pk_mul_f32 v[62:63], v[62:63], v[0:1] op_sel_hi:[1,0]
	v_pk_mul_f32 v[60:61], v[44:45], v[60:61]
	v_pk_mul_f32 v[62:63], v[46:47], v[62:63]
	v_cvt_pk_bf16_f32 v60, v60, v61
	v_cvt_pk_bf16_f32 v61, v62, v63
	global_store_dwordx2 v[72:73], v[60:61], off offset:512
	v_pk_mul_f32 v[64:65], v[64:65], v[0:1] op_sel_hi:[1,0]
	v_pk_mul_f32 v[66:67], v[66:67], v[0:1] op_sel_hi:[1,0]
	v_pk_mul_f32 v[64:65], v[48:49], v[64:65]
	v_pk_mul_f32 v[66:67], v[50:51], v[66:67]
	v_cvt_pk_bf16_f32 v64, v64, v65
	v_cvt_pk_bf16_f32 v65, v66, v67
	global_store_dwordx2 v[72:73], v[64:65], off offset:1024
	v_pk_mul_f32 v[68:69], v[68:69], v[0:1] op_sel_hi:[1,0]
	v_pk_mul_f32 v[70:71], v[70:71], v[0:1] op_sel_hi:[1,0]
	v_pk_mul_f32 v[68:69], v[52:53], v[68:69]
	v_pk_mul_f32 v[70:71], v[54:55], v[70:71]
	v_cvt_pk_bf16_f32 v68, v68, v69
	v_cvt_pk_bf16_f32 v69, v70, v71
	global_store_dwordx2 v[72:73], v[68:69], off offset:1536
	s_branch .Ln2_top
; DI unsigned cvtpk(float lo, float hi) { f32x2 v = {lo, hi}; bf16x2_t b = __builtin_convertvector(v, bf16x2_t); return __builtin_bit_cast(unsigned, b); }
; DI void norm_rows(const float* src, const float* gain, bf16_t* HN, int gw, int NGW, int lane) {
;     for (int mrow_ = gw; mrow_ < MTOK * REP_NORM; mrow_ += NGW) {
;         const int mrow = mrow_ & (MTOK - 1);
;         const f32x4* xr = (const f32x4*)(src + (size_t)mrow * DM) + lane;
;         f32x4 v[4]; float ss = 0.f;
; #pragma unroll
;         for (int j = 0; j < 4; ++j) { v[j] = xr[64 * j]; ss += (v[j].x * v[j].x + v[j].y * v[j].y) + (v[j].z * v[j].z + v[j].w * v[j].w); }
;         const float r = rsqrtf(wave_sum(ss) * (1.f / DM) + EPS);
;         u32x2* o8 = (u32x2*)(HN + (size_t)mrow * DM) + lane;
; #pragma unroll
;         for (int j = 0; j < 4; ++j) { const f32x4 gg = ((const f32x4*)gain)[lane + 64 * j]; u32x2 w; w.x = cvtpk(v[j].x * r * gg.x, v[j].y * r * gg.y); w.y = cvtpk(v[j].z * r * gg.z, v[j].w * r * gg.w); o8[64 * j] = w; }
;     }
.Ln2_lastA:
	s_waitcnt vmcnt(0)
	v_mul_f32_e32 v0, v13, v13
	v_mul_f32_e32 v3, v15, v15
	v_mul_f32_e32 v34, v17, v17
	v_mul_f32_e32 v35, v19, v19
	v_mul_f32_e32 v36, v21, v21
	v_mul_f32_e32 v37, v23, v23
	v_fmac_f32_e32 v0, v12, v12
	v_fmac_f32_e32 v3, v14, v14
	v_fmac_f32_e32 v34, v16, v16
	v_fmac_f32_e32 v35, v18, v18
	v_mul_f32_e32 v38, v25, v25
	v_mul_f32_e32 v39, v27, v27
	v_fmac_f32_e32 v36, v20, v20
	v_fmac_f32_e32 v37, v22, v22
	v_add_f32_e32 v0, v0, v3
	v_add_f32_e32 v3, v34, v35
	v_fmac_f32_e32 v38, v24, v24
	v_fmac_f32_e32 v39, v26, v26
	v_add_f32_e32 v34, v36, v37
	v_add_f32_e32 v0, v0, v3
	v_add_f32_e32 v35, v38, v39
	v_add_f32_e32 v0, v0, v34
	v_add_f32_e32 v0, v0, v35
	ds_swizzle_b32 v3, v0 offset:swizzle(SWAP,1)
	s_waitcnt lgkmcnt(0)
	v_add_f32_e32 v0, v0, v3
	ds_swizzle_b32 v3, v0 offset:swizzle(SWAP,2)
	s_waitcnt lgkmcnt(0)
	v_add_f32_e32 v0, v0, v3
	ds_swizzle_b32 v3, v0 offset:swizzle(SWAP,4)
	s_waitcnt lgkmcnt(0)
	v_add_f32_e32 v0, v0, v3
	ds_swizzle_b32 v3, v0 offset:swizzle(SWAP,8)
	s_waitcnt lgkmcnt(0)
	v_add_f32_e32 v0, v0, v3
	ds_swizzle_b32 v3, v0 offset:swizzle(SWAP,16)
	s_waitcnt lgkmcnt(0)
	v_add_f32_e32 v0, v0, v3
	v_mov_b32_e32 v3, v0
	s_nop 1
	v_permlane32_swap_b32_e32 v0, v3
	v_add_f32_e32 v0, v0, v3
	v_fmamk_f32 v0, v0, 0x3a800000, v156
	v_mul_f32_e32 v3, 0x4b800000, v0
	v_cmp_gt_f32_e32 vcc, s9, v0
	s_nop 1
	v_cndmask_b32_e32 v0, v0, v3, vcc
	v_rsq_f32_e32 v0, v0
	s_nop 0
	v_mul_f32_e32 v3, 0x45800000, v0
	v_cndmask_b32_e32 v0, v0, v3, vcc
	v_pk_mul_f32 v[12:13], v[12:13], v[0:1] op_sel_hi:[1,0]
	v_pk_mul_f32 v[14:15], v[14:15], v[0:1] op_sel_hi:[1,0]
	v_pk_mul_f32 v[12:13], v[40:41], v[12:13]
	v_pk_mul_f32 v[14:15], v[42:43], v[14:15]
	v_cvt_pk_bf16_f32 v12, v12, v13
	v_cvt_pk_bf16_f32 v13, v14, v15
	global_store_dwordx2 v[32:33], v[12:13], off
	v_pk_mul_f32 v[16:17], v[16:17], v[0:1] op_sel_hi:[1,0]
	v_pk_mul_f32 v[18:19], v[18:19], v[0:1] op_sel_hi:[1,0]
	v_pk_mul_f32 v[16:17], v[44:45], v[16:17]
	v_pk_mul_f32 v[18:19], v[46:47], v[18:19]
	v_cvt_pk_bf16_f32 v16, v16, v17
	v_cvt_pk_bf16_f32 v17, v18, v19
	global_store_dwordx2 v[32:33], v[16:17], off offset:512
	v_pk_mul_f32 v[20:21], v[20:21], v[0:1] op_sel_hi:[1,0]
	v_pk_mul_f32 v[22:23], v[22:23], v[0:1] op_sel_hi:[1,0]
	v_pk_mul_f32 v[20:21], v[48:49], v[20:21]
	v_pk_mul_f32 v[22:23], v[50:51], v[22:23]
	v_cvt_pk_bf16_f32 v20, v20, v21
	v_cvt_pk_bf16_f32 v21, v22, v23
	global_store_dwordx2 v[32:33], v[20:21], off offset:1024
	v_pk_mul_f32 v[24:25], v[24:25], v[0:1] op_sel_hi:[1,0]
	v_pk_mul_f32 v[26:27], v[26:27], v[0:1] op_sel_hi:[1,0]
	v_pk_mul_f32 v[24:25], v[52:53], v[24:25]
	v_pk_mul_f32 v[26:27], v[54:55], v[26:27]
	v_cvt_pk_bf16_f32 v24, v24, v25
	v_cvt_pk_bf16_f32 v25, v26, v27
	global_store_dwordx2 v[32:33], v[24:25], off offset:1536
	s_branch .Ln2_done
.Ln2_lastB:
	s_waitcnt vmcnt(0)
	v_mul_f32_e32 v0, v57, v57
	v_mul_f32_e32 v3, v59, v59
	v_mul_f32_e32 v34, v61, v61
	v_mul_f32_e32 v35, v63, v63
	v_mul_f32_e32 v36, v65, v65
	v_mul_f32_e32 v37, v67, v67
	v_fmac_f32_e32 v0, v56, v56
	v_fmac_f32_e32 v3, v58, v58
	v_fmac_f32_e32 v34, v60, v60
	v_fmac_f32_e32 v35, v62, v62
	v_mul_f32_e32 v38, v69, v69
	v_mul_f32_e32 v39, v71, v71
	v_fmac_f32_e32 v36, v64, v64
	v_fmac_f32_e32 v37, v66, v66
	v_add_f32_e32 v0, v0, v3
	v_add_f32_e32 v3, v34, v35
	v_fmac_f32_e32 v38, v68, v68
	v_fmac_f32_e32 v39, v70, v70
	v_add_f32_e32 v34, v36, v37
	v_add_f32_e32 v0, v0, v3
	v_add_f32_e32 v35, v38, v39
	v_add_f32_e32 v0, v0, v34
	v_add_f32_e32 v0, v0, v35
	ds_swizzle_b32 v3, v0 offset:swizzle(SWAP,1)
	s_waitcnt lgkmcnt(0)
	v_add_f32_e32 v0, v0, v3
	ds_swizzle_b32 v3, v0 offset:swizzle(SWAP,2)
	s_waitcnt lgkmcnt(0)
	v_add_f32_e32 v0, v0, v3
	ds_swizzle_b32 v3, v0 offset:swizzle(SWAP,4)
	s_waitcnt lgkmcnt(0)
	v_add_f32_e32 v0, v0, v3
	ds_swizzle_b32 v3, v0 offset:swizzle(SWAP,8)
	s_waitcnt lgkmcnt(0)
	v_add_f32_e32 v0, v0, v3
	ds_swizzle_b32 v3, v0 offset:swizzle(SWAP,16)
	s_waitcnt lgkmcnt(0)
	v_add_f32_e32 v0, v0, v3
	v_mov_b32_e32 v3, v0
	s_nop 1
	v_permlane32_swap_b32_e32 v0, v3
	v_add_f32_e32 v0, v0, v3
	v_fmamk_f32 v0, v0, 0x3a800000, v156
	v_mul_f32_e32 v3, 0x4b800000, v0
	v_cmp_gt_f32_e32 vcc, s9, v0
	s_nop 1
	v_cndmask_b32_e32 v0, v0, v3, vcc
	v_rsq_f32_e32 v0, v0
	s_nop 0
	v_mul_f32_e32 v3, 0x45800000, v0
	v_cndmask_b32_e32 v0, v0, v3, vcc
	v_pk_mul_f32 v[56:57], v[56:57], v[0:1] op_sel_hi:[1,0]
	v_pk_mul_f32 v[58:59], v[58:59], v[0:1] op_sel_hi:[1,0]
	v_pk_mul_f32 v[56:57], v[40:41], v[56:57]
	v_pk_mul_f32 v[58:59], v[42:43], v[58:59]
	v_cvt_pk_bf16_f32 v56, v56, v57
	v_cvt_pk_bf16_f32 v57, v58, v59
	global_store_dwordx2 v[72:73], v[56:57], off
	v_pk_mul_f32 v[60:61], v[60:61], v[0:1] op_sel_hi:[1,0]
	v_pk_mul_f32 v[62:63], v[62:63], v[0:1] op_sel_hi:[1,0]
	v_pk_mul_f32 v[60:61], v[44:45], v[60:61]
	v_pk_mul_f32 v[62:63], v[46:47], v[62:63]
	v_cvt_pk_bf16_f32 v60, v60, v61
	v_cvt_pk_bf16_f32 v61, v62, v63
	global_store_dwordx2 v[72:73], v[60:61], off offset:512
	v_pk_mul_f32 v[64:65], v[64:65], v[0:1] op_sel_hi:[1,0]
	v_pk_mul_f32 v[66:67], v[66:67], v[0:1] op_sel_hi:[1,0]
	v_pk_mul_f32 v[64:65], v[48:49], v[64:65]
	v_pk_mul_f32 v[66:67], v[50:51], v[66:67]
	v_cvt_pk_bf16_f32 v64, v64, v65
	v_cvt_pk_bf16_f32 v65, v66, v67
	global_store_dwordx2 v[72:73], v[64:65], off offset:1024
	v_pk_mul_f32 v[68:69], v[68:69], v[0:1] op_sel_hi:[1,0]
	v_pk_mul_f32 v[70:71], v[70:71], v[0:1] op_sel_hi:[1,0]
	v_pk_mul_f32 v[68:69], v[52:53], v[68:69]
	v_pk_mul_f32 v[70:71], v[54:55], v[70:71]
	v_cvt_pk_bf16_f32 v68, v68, v69
	v_cvt_pk_bf16_f32 v69, v70, v71
	global_store_dwordx2 v[72:73], v[68:69], off offset:1536
.Ln2_done:
	v_writelane_b32 v254, s12, 11
	s_nop 1
	v_writelane_b32 v254, s13, 12
	v_writelane_b32 v254, s14, 13
	v_writelane_b32 v254, s15, 14

; #define LSE WSP(float, WS_LSE)
; #define S1 WSP(float, WS_S1)
; #define S2 WSP(float, WS_S2)
; __global__ void __launch_bounds__(512) mega_fwd(Params P) {
;     ...
;             for (int it_ = bid; it_ < 256 * REP_A2; it_ += G) {
;                 const int thalf = it_ & 1, it = (it_ >> 1) & 127;
;                 const int qb = it >> 2, b = (it >> 1) & 1, g = it & 1, q0 = qb * 256;
;                 const size_t rb = (size_t)b * SEQ;
;                 const int qpos = q0 + 32 * wid + r32, qmaxw = q0 + 32 * wid + 31;
;                 const int cmax = (q0 + 224) >> 4, t1 = (cmax >> 6) + 1;
;                 bf16x8 qf[3][4]; float lse[3];
; #pragma unroll
;                 for (int r = 0; r < 3; ++r) {
;                     const int h = 3 * g + r;
; #pragma unroll
;                     for (int ks = 0; ks < 4; ++ks) qf[r][ks] = *(const bf16x8*)(PROJ + (rb + qpos) * NPROJ + PC_NQ + 64 * h + 16 * ks + 8 * hi);
;                     lse[r] = LSE[(size_t)(b * 6 + h) * SEQ + qpos];
;                 }
;                 const bf16_t* K1 = KCVC + ((size_t)(b * NCMP) * 2 + g) * 256;
;                 const int srow = tid >> 3, sch = tid & 7;
;                 float* s1row = S1 + ((size_t)(b * 2 + g) * SEQ + qpos) * 128; float* s2row = S2 + ((size_t)(b * 2 + g) * SEQ + qpos) * 128;
.LBB0_1133:
	s_and_b32 s10, s1, 1
	s_bfe_u32 s11, s1, 0x30005
	s_cmp_gt_u32 s10, s11
	s_cbranch_scc1 .LBB0_1132
	s_bfe_u32 s13, s1, 0x10002
	s_bfe_u32 s16, s1, 0x10001
	s_mul_i32 s12, s13, 0x7fc00
	s_lshl_b32 s14, s16, 9
	s_or_b32 s20, s14, s12
	s_lshl_b32 s12, s1, 5
	v_cndmask_b32_e64 v12, 0, 1, s[6:7]
	s_and_b32 s12, s12, 0x1f00
	v_lshlrev_b32_e32 v0, 16, v12
	s_mov_b32 s21, s81
	v_add_u32_e32 v4, s12, v99
	s_lshl_b32 s12, s13, 14
	s_lshl_b32 s14, s16, 13
	v_lshl_add_u64 v[2:3], s[20:21], 0, v[0:1]
	s_or_b32 s20, s12, s14
	s_and_b32 s12, s1, 0xf8
	s_add_i32 s12, s12, s74
	s_lshl_b32 s12, s12, 5
	v_ashrrev_i32_e32 v5, 31, v4
	v_or_b32_e32 v86, s12, v96
	v_lshl_add_u64 v[4:5], v[4:5], 0, s[20:21]
	s_lshl_b32 s20, s13, 13
	v_ashrrev_i32_e32 v87, 31, v86
	v_lshl_add_u64 v[6:7], v[86:87], 0, s[20:21]
	v_mov_b64_e32 v[8:9], s[2:3]
	v_mad_u64_u32 v[8:9], s[14:15], v6, s69, v[8:9]
	v_mad_i32_i24 v9, v7, s69, v9
	v_mov_b32_e32 v85, v1
	s_mul_i32 s17, s16, 3
	v_lshl_add_u64 v[6:7], v[8:9], 0, v[84:85]
	s_mov_b64 s[14:15], 0x3c00340
	s_mul_i32 s13, s13, 6
	v_lshl_add_u64 v[6:7], v[6:7], 0, s[14:15]
	s_mul_i32 s20, s16, 0x180
	s_add_i32 s14, s17, s13
	v_lshl_add_u64 v[8:9], v[86:87], 2, s[4:5]
	v_lshl_add_u64 v[10:11], v[6:7], 0, s[20:21]
	s_lshl_b32 s20, s14, 15
	s_add_i32 s14, s17, 1
	flat_load_dwordx4 v[18:21], v[10:11]
	flat_load_dwordx4 v[22:25], v[10:11] offset:32
	flat_load_dwordx4 v[26:29], v[10:11] offset:64
	flat_load_dwordx4 v[30:33], v[10:11] offset:96
	v_lshl_add_u64 v[10:11], v[8:9], 0, s[20:21]
	s_lshl_b32 s20, s14, 7
	s_add_i32 s14, s14, s13
	flat_load_dword v0, v[10:11]
	v_lshl_add_u64 v[10:11], v[6:7], 0, s[20:21]
	s_lshl_b32 s20, s14, 15
	s_add_i32 s14, s17, 2
	flat_load_dwordx4 v[34:37], v[10:11]
	flat_load_dwordx4 v[38:41], v[10:11] offset:32
	flat_load_dwordx4 v[42:45], v[10:11] offset:64
	flat_load_dwordx4 v[46:49], v[10:11] offset:96
	v_lshl_add_u64 v[10:11], v[8:9], 0, s[20:21]
	s_lshl_b32 s20, s14, 7
	v_lshl_add_u64 v[6:7], v[6:7], 0, s[20:21]
	s_add_i32 s14, s14, s13
	flat_load_dword v85, v[10:11]
	flat_load_dwordx4 v[50:53], v[6:7]
	flat_load_dwordx4 v[54:57], v[6:7] offset:32
	flat_load_dwordx4 v[58:61], v[6:7] offset:64
	flat_load_dwordx4 v[62:65], v[6:7] offset:96
	s_lshl_b32 s20, s14, 15
	v_lshl_add_u64 v[6:7], v[8:9], 0, s[20:21]
	flat_load_dword v87, v[6:7]
	v_lshl_add_u64 v[88:89], v[2:3], 0, v[82:83]
	v_readfirstlane_b32 s13, v12
	v_lshlrev_b64 v[90:91], 9, v[4:5]
	v_lshlrev_b32_e32 v2, 2, v97
	v_lshlrev_b32_e32 v3, 6, v12
	s_lshl_b32 s13, s13, 10
	v_or3_b32 v90, v3, v2, v90
	v_lshl_add_u64 v[184:185], s[2:3], 0, v[88:89]
	global_load_dwordx4 v[180:183], v[184:185], off
	s_branch .LBB0_1136

; #define LAS __attribute__((address_space(3)))
; DI int crow(int r, int hi) { return (r & 3) + 8 * (r >> 2) + 4 * hi; }
; #define MFMA32(a, b, c) __builtin_amdgcn_mfma_f32_32x32x16_bf16((a), (b), (c), 0, 0, 0)
; __global__ void __launch_bounds__(512) mega_fwd(Params P) {
;     ...
;                 for (int t = thalf; t < t1; t += 2) {
;                     __syncthreads();
;                     *(LAS u32x4*)(Ks + srow * 144 + sch * 16) = *(const u32x4*)(K1 + ((size_t)64 * t + srow) * 512 + sch * 8);
;                     __syncthreads();
;                     if (16 * (64 * t) + 31 > qmaxw) continue;
; #pragma unroll
;                     for (int kb = 0; kb < 2; ++kb) {
;                         f32x16 ps = (f32x16){};
; #pragma unroll
;                         for (int r = 0; r < 3; ++r) {
;                             f32x16 s = (f32x16){};
; #pragma unroll
;                             for (int ks = 0; ks < 4; ++ks) { const bf16x8 a = *(const LAS bf16x8*)(Ks + (32 * kb + r32) * 144 + ks * 32 + hi * 16); s = MFMA32(a, qf[r][ks], s); }
; #pragma unroll
;                             for (int i = 0; i < 16; ++i) { const int c = 64 * t + 32 * kb + crow(i, hi); const bool valid = (16 * c + 31 <= qpos); ps[i] += valid ? exp2f(s[i] * (0.125f * LOG2E) - lse[r]) : 0.f; }
;                         }
.LBB0_1136:
	s_waitcnt lgkmcnt(0)
	s_barrier
	s_waitcnt vmcnt(0)
	ds_write_b128 v100, v[180:183]
	s_add_i32 s14, s10, 2
	s_cmp_gt_u32 s14, s11
	s_cbranch_scc1 .La2a_nopf
	s_mov_b64 s[14:15], 0x20000
	v_lshl_add_u64 v[184:185], v[88:89], 0, s[14:15]
	v_lshl_add_u64 v[184:185], s[2:3], 0, v[184:185]
	global_load_dwordx4 v[180:183], v[184:185], off
.La2a_nopf:
	s_cmp_gt_i32 s13, s12
	s_waitcnt lgkmcnt(0)
	s_barrier
	s_cbranch_scc1 .LBB0_1135
	ds_read_b128 v[78:81], v101
	ds_read_b128 v[74:77], v101 offset:32
	ds_read_b128 v[70:73], v101 offset:64
	ds_read_b128 v[66:69], v101 offset:96
	v_add_u32_e32 v102, s13, v98
	s_waitcnt lgkmcnt(3)
	v_mfma_f32_32x32x16_bf16 v[2:17], v[78:81], v[18:21], 0
	v_add_u32_e32 v92, 31, v102
	v_add_u32_e32 v94, 63, v102
	v_add_u32_e32 v95, 0x4f, v102
	v_add_u32_e32 v103, 0x9f, v102
	v_add_u32_e32 v104, 0xaf, v102
	v_add_u32_e32 v114, 0xbf, v102
	v_add_u32_e32 v113, 0xcf, v102
	s_waitcnt lgkmcnt(2)
	v_mfma_f32_32x32x16_bf16 v[2:17], v[74:77], v[22:25], v[2:17]
	v_add_u32_e32 v112, 0x11f, v102
	v_add_u32_e32 v111, 0x12f, v102
	v_add_u32_e32 v110, 0x13f, v102
	v_add_u32_e32 v109, 0x14f, v102
	v_add_u32_e32 v108, 0x19f, v102
	v_add_u32_e32 v107, 0x1af, v102
	v_add_u32_e32 v106, 0x1bf, v102
	s_waitcnt lgkmcnt(1)
	v_mfma_f32_32x32x16_bf16 v[2:17], v[70:73], v[26:29], v[2:17]
	v_add_u32_e32 v105, 0x1cf, v102
	s_mov_b32 s14, 0xca00000
	s_waitcnt lgkmcnt(0)
	v_mfma_f32_32x32x16_bf16 v[2:17], v[66:69], v[30:33], v[2:17]
	s_nop 11
	v_fma_f32 v2, v2, s78, -v0
	v_cmp_gt_f32_e32 vcc, s33, v2
	s_nop 1
	v_cndmask_b32_e32 v93, 0, v177, vcc
	v_add_f32_e32 v2, v2, v93
	v_exp_f32_e32 v2, v2
	v_cndmask_b32_e32 v93, 0, v200, vcc
	v_ldexp_f32 v115, v2, v93
	v_fma_f32 v2, v3, s78, -v0
	v_cmp_gt_f32_e32 vcc, s33, v2
	v_add_u32_e32 v93, 47, v102
	s_nop 0
	v_cndmask_b32_e32 v3, 0, v177, vcc
	v_add_f32_e32 v2, v2, v3
	v_exp_f32_e32 v2, v2
	v_cndmask_b32_e32 v3, 0, v200, vcc
	v_ldexp_f32 v116, v2, v3
	v_fma_f32 v2, v4, s78, -v0
	v_cmp_gt_f32_e32 vcc, s33, v2
	s_nop 1
	v_cndmask_b32_e32 v3, 0, v177, vcc
	v_add_f32_e32 v2, v2, v3
	v_exp_f32_e32 v2, v2
	v_cndmask_b32_e32 v3, 0, v200, vcc
	v_ldexp_f32 v117, v2, v3
	v_fma_f32 v2, v5, s78, -v0
	v_cmp_gt_f32_e32 vcc, s33, v2
	s_nop 1
	v_cndmask_b32_e32 v3, 0, v177, vcc
	v_add_f32_e32 v2, v2, v3
	v_exp_f32_e32 v2, v2
	v_cndmask_b32_e32 v3, 0, v200, vcc
	v_ldexp_f32 v118, v2, v3
	v_fma_f32 v2, v6, s78, -v0
	v_cmp_gt_f32_e32 vcc, s33, v2
	s_nop 1
	v_cndmask_b32_e32 v3, 0, v177, vcc
	v_add_f32_e32 v2, v2, v3
	v_exp_f32_e32 v2, v2
	v_cndmask_b32_e32 v3, 0, v200, vcc
	v_ldexp_f32 v119, v2, v3
	v_fma_f32 v2, v7, s78, -v0
	v_cmp_gt_f32_e32 vcc, s33, v2
	s_nop 1
	v_cndmask_b32_e32 v3, 0, v177, vcc
	v_add_f32_e32 v2, v2, v3
	v_exp_f32_e32 v2, v2
	v_cndmask_b32_e32 v3, 0, v200, vcc
	v_ldexp_f32 v120, v2, v3
	v_fma_f32 v2, v8, s78, -v0
	v_cmp_gt_f32_e32 vcc, s33, v2
	s_nop 1
	v_cndmask_b32_e32 v3, 0, v177, vcc
	v_add_f32_e32 v2, v2, v3
	v_exp_f32_e32 v2, v2
	v_cndmask_b32_e32 v3, 0, v200, vcc
	v_ldexp_f32 v121, v2, v3
	v_fma_f32 v2, v9, s78, -v0
	v_cmp_gt_f32_e32 vcc, s33, v2
	s_nop 1
	v_cndmask_b32_e32 v3, 0, v177, vcc
	v_add_f32_e32 v2, v2, v3
	v_exp_f32_e32 v2, v2
	v_cndmask_b32_e32 v3, 0, v200, vcc
	v_ldexp_f32 v122, v2, v3
	v_fma_f32 v2, v10, s78, -v0
	v_cmp_gt_f32_e32 vcc, s33, v2
	s_nop 1
	v_cndmask_b32_e32 v3, 0, v177, vcc
	v_add_f32_e32 v2, v2, v3
	v_exp_f32_e32 v2, v2
	v_cndmask_b32_e32 v3, 0, v200, vcc
	v_ldexp_f32 v123, v2, v3
	v_fma_f32 v2, v11, s78, -v0
	v_cmp_gt_f32_e32 vcc, s33, v2
	s_nop 1
	v_cndmask_b32_e32 v3, 0, v177, vcc
	v_add_f32_e32 v2, v2, v3
	v_exp_f32_e32 v2, v2
	v_cndmask_b32_e32 v3, 0, v200, vcc
	v_ldexp_f32 v124, v2, v3
	v_fma_f32 v2, v12, s78, -v0
	v_cmp_gt_f32_e32 vcc, s33, v2
	s_nop 1
	v_cndmask_b32_e32 v3, 0, v177, vcc
	v_add_f32_e32 v2, v2, v3
	v_exp_f32_e32 v2, v2
	v_cndmask_b32_e32 v3, 0, v200, vcc
	v_ldexp_f32 v125, v2, v3
	v_fma_f32 v2, v13, s78, -v0
	v_cmp_gt_f32_e32 vcc, s33, v2
	s_nop 1
	v_cndmask_b32_e32 v3, 0, v177, vcc
	v_add_f32_e32 v2, v2, v3
	v_exp_f32_e32 v2, v2
	v_cndmask_b32_e32 v3, 0, v200, vcc
	v_ldexp_f32 v126, v2, v3
	v_fma_f32 v2, v14, s78, -v0
	v_cmp_gt_f32_e32 vcc, s33, v2
	s_nop 1
	v_cndmask_b32_e32 v3, 0, v177, vcc
	v_add_f32_e32 v2, v2, v3
	v_exp_f32_e32 v2, v2
	v_cndmask_b32_e32 v3, 0, v200, vcc
	v_ldexp_f32 v127, v2, v3
	v_fma_f32 v2, v15, s78, -v0
	v_cmp_gt_f32_e32 vcc, s33, v2
	s_nop 1
	v_cndmask_b32_e32 v3, 0, v177, vcc
	v_add_f32_e32 v2, v2, v3
	v_exp_f32_e32 v2, v2
	v_cndmask_b32_e32 v3, 0, v200, vcc
	v_ldexp_f32 v128, v2, v3
	v_fma_f32 v2, v16, s78, -v0
	v_cmp_gt_f32_e32 vcc, s33, v2
	s_nop 1
	v_cndmask_b32_e32 v3, 0, v177, vcc
	v_add_f32_e32 v2, v2, v3
	v_exp_f32_e32 v2, v2
	v_cndmask_b32_e32 v3, 0, v200, vcc
	v_ldexp_f32 v129, v2, v3
	v_fma_f32 v2, v17, s78, -v0
	v_cmp_gt_f32_e32 vcc, s33, v2
	s_nop 1
	v_cndmask_b32_e32 v3, 0, v177, vcc
	v_add_f32_e32 v2, v2, v3
	v_exp_f32_e32 v2, v2
	v_cndmask_b32_e32 v3, 0, v200, vcc
	v_ldexp_f32 v130, v2, v3
	v_mfma_f32_32x32x16_bf16 v[2:17], v[78:81], v[34:37], 0
	v_mfma_f32_32x32x16_bf16 v[2:17], v[74:77], v[38:41], v[2:17]
	v_mfma_f32_32x32x16_bf16 v[2:17], v[70:73], v[42:45], v[2:17]
	v_mfma_f32_32x32x16_bf16 v[2:17], v[66:69], v[46:49], v[2:17]
	s_nop 11
	v_fma_f32 v2, v2, s78, -v85
	v_cmp_gt_f32_e32 vcc, s33, v2
	s_nop 1
	v_cndmask_b32_e32 v131, 0, v177, vcc
	v_add_f32_e32 v2, v2, v131
	v_exp_f32_e32 v2, v2
	v_cndmask_b32_e32 v131, 0, v200, vcc
	v_ldexp_f32 v2, v2, v131
	v_add_f32_e32 v131, v115, v2
	v_fma_f32 v2, v3, s78, -v85
	v_cmp_gt_f32_e32 vcc, s33, v2
	s_nop 1
	v_cndmask_b32_e32 v3, 0, v177, vcc
	v_add_f32_e32 v2, v2, v3
	v_exp_f32_e32 v2, v2
	v_cndmask_b32_e32 v3, 0, v200, vcc
; #define LAS __attribute__((address_space(3)))
; DI int crow(int r, int hi) { return (r & 3) + 8 * (r >> 2) + 4 * hi; }
; #define MFMA32(a, b, c) __builtin_amdgcn_mfma_f32_32x32x16_bf16((a), (b), (c), 0, 0, 0)
; __global__ void __launch_bounds__(512) mega_fwd(Params P) {
;     ...
;                     for (int kb = 0; kb < 2; ++kb) {
;                         f32x16 ps = (f32x16){};
; #pragma unroll
;                         for (int r = 0; r < 3; ++r) {
;                             f32x16 s = (f32x16){};
; #pragma unroll
;                             for (int ks = 0; ks < 4; ++ks) { const bf16x8 a = *(const LAS bf16x8*)(Ks + (32 * kb + r32) * 144 + ks * 32 + hi * 16); s = MFMA32(a, qf[r][ks], s); }
; #pragma unroll
;                             for (int i = 0; i < 16; ++i) { const int c = 64 * t + 32 * kb + crow(i, hi); const bool valid = (16 * c + 31 <= qpos); ps[i] += valid ? exp2f(s[i] * (0.125f * LOG2E) - lse[r]) : 0.f; }
;                         }
	v_ldexp_f32 v2, v2, v3
	v_add_f32_e32 v132, v116, v2
	v_fma_f32 v2, v4, s78, -v85
	v_cmp_gt_f32_e32 vcc, s33, v2
	s_nop 1
	v_cndmask_b32_e32 v3, 0, v177, vcc
	v_add_f32_e32 v2, v2, v3
	v_exp_f32_e32 v2, v2
	v_cndmask_b32_e32 v3, 0, v200, vcc
	v_ldexp_f32 v2, v2, v3
	v_add_f32_e32 v133, v117, v2
	v_fma_f32 v2, v5, s78, -v85
	v_cmp_gt_f32_e32 vcc, s33, v2
	s_nop 1
	v_cndmask_b32_e32 v3, 0, v177, vcc
	v_add_f32_e32 v2, v2, v3
	v_exp_f32_e32 v2, v2
	v_cndmask_b32_e32 v3, 0, v200, vcc
	v_ldexp_f32 v2, v2, v3
	v_add_f32_e32 v134, v118, v2
	v_fma_f32 v2, v6, s78, -v85
	v_cmp_gt_f32_e32 vcc, s33, v2
	s_nop 1
	v_cndmask_b32_e32 v3, 0, v177, vcc
	v_add_f32_e32 v2, v2, v3
	v_exp_f32_e32 v2, v2
	v_cndmask_b32_e32 v3, 0, v200, vcc
	v_ldexp_f32 v2, v2, v3
	v_add_f32_e32 v135, v119, v2
	v_fma_f32 v2, v7, s78, -v85
	v_cmp_gt_f32_e32 vcc, s33, v2
	s_nop 1
	v_cndmask_b32_e32 v3, 0, v177, vcc
	v_add_f32_e32 v2, v2, v3
	v_exp_f32_e32 v2, v2
	v_cndmask_b32_e32 v3, 0, v200, vcc
	v_ldexp_f32 v2, v2, v3
	v_add_f32_e32 v136, v120, v2
	v_fma_f32 v2, v8, s78, -v85
	v_cmp_gt_f32_e32 vcc, s33, v2
	s_nop 1
	v_cndmask_b32_e32 v3, 0, v177, vcc
	v_add_f32_e32 v2, v2, v3
	v_exp_f32_e32 v2, v2
	v_cndmask_b32_e32 v3, 0, v200, vcc
	v_ldexp_f32 v2, v2, v3
	v_add_f32_e32 v137, v121, v2
	v_fma_f32 v2, v9, s78, -v85
	v_cmp_gt_f32_e32 vcc, s33, v2
	s_nop 1
	v_cndmask_b32_e32 v3, 0, v177, vcc
	v_add_f32_e32 v2, v2, v3
	v_exp_f32_e32 v2, v2
	v_cndmask_b32_e32 v3, 0, v200, vcc
	v_ldexp_f32 v2, v2, v3
	v_add_f32_e32 v122, v122, v2
	v_fma_f32 v2, v10, s78, -v85
	v_cmp_gt_f32_e32 vcc, s33, v2
	s_nop 1
	v_cndmask_b32_e32 v3, 0, v177, vcc
	v_add_f32_e32 v2, v2, v3
	v_exp_f32_e32 v2, v2
	v_cndmask_b32_e32 v3, 0, v200, vcc
	v_ldexp_f32 v2, v2, v3
	v_add_f32_e32 v123, v123, v2
	v_fma_f32 v2, v11, s78, -v85
	v_cmp_gt_f32_e32 vcc, s33, v2
	s_nop 1
	v_cndmask_b32_e32 v3, 0, v177, vcc
	v_add_f32_e32 v2, v2, v3
	v_exp_f32_e32 v2, v2
	v_cndmask_b32_e32 v3, 0, v200, vcc
	v_ldexp_f32 v2, v2, v3
	v_add_f32_e32 v121, v124, v2
	v_fma_f32 v2, v12, s78, -v85
	v_cmp_gt_f32_e32 vcc, s33, v2
	s_nop 1
	v_cndmask_b32_e32 v3, 0, v177, vcc
	v_add_f32_e32 v2, v2, v3
	v_exp_f32_e32 v2, v2
	v_cndmask_b32_e32 v3, 0, v200, vcc
	v_ldexp_f32 v2, v2, v3
	v_add_f32_e32 v120, v125, v2
	v_fma_f32 v2, v13, s78, -v85
	v_cmp_gt_f32_e32 vcc, s33, v2
	s_nop 1
	v_cndmask_b32_e32 v3, 0, v177, vcc
	v_add_f32_e32 v2, v2, v3
	v_exp_f32_e32 v2, v2
	v_cndmask_b32_e32 v3, 0, v200, vcc
	v_ldexp_f32 v2, v2, v3
	v_add_f32_e32 v119, v126, v2
	v_fma_f32 v2, v14, s78, -v85
	v_cmp_gt_f32_e32 vcc, s33, v2
	s_nop 1
	v_cndmask_b32_e32 v3, 0, v177, vcc
	v_add_f32_e32 v2, v2, v3
	v_exp_f32_e32 v2, v2
	v_cndmask_b32_e32 v3, 0, v200, vcc
	v_ldexp_f32 v2, v2, v3
	v_add_f32_e32 v118, v127, v2
	v_fma_f32 v2, v15, s78, -v85
	v_cmp_gt_f32_e32 vcc, s33, v2
	s_nop 1
	v_cndmask_b32_e32 v3, 0, v177, vcc
	v_add_f32_e32 v2, v2, v3
	v_exp_f32_e32 v2, v2
	v_cndmask_b32_e32 v3, 0, v200, vcc
	v_ldexp_f32 v2, v2, v3
	v_add_f32_e32 v117, v128, v2
	v_fma_f32 v2, v16, s78, -v85
	v_cmp_gt_f32_e32 vcc, s33, v2
	s_nop 1
	v_cndmask_b32_e32 v3, 0, v177, vcc
	v_add_f32_e32 v2, v2, v3
	v_exp_f32_e32 v2, v2
	v_cndmask_b32_e32 v3, 0, v200, vcc
	v_ldexp_f32 v2, v2, v3
	v_add_f32_e32 v116, v129, v2
	v_fma_f32 v2, v17, s78, -v85
	v_cmp_gt_f32_e32 vcc, s33, v2
	s_nop 1
	v_cndmask_b32_e32 v3, 0, v177, vcc
	v_add_f32_e32 v2, v2, v3
	v_exp_f32_e32 v2, v2
	v_cndmask_b32_e32 v3, 0, v200, vcc
	v_ldexp_f32 v2, v2, v3
	v_add_f32_e32 v115, v130, v2
	v_mfma_f32_32x32x16_bf16 v[2:17], v[78:81], v[50:53], 0
	v_mfma_f32_32x32x16_bf16 v[2:17], v[74:77], v[54:57], v[2:17]
	v_mfma_f32_32x32x16_bf16 v[2:17], v[70:73], v[58:61], v[2:17]
	v_mfma_f32_32x32x16_bf16 v[2:17], v[66:69], v[62:65], v[2:17]
	s_nop 11
	v_fma_f32 v2, v2, s78, -v87
	v_cmp_gt_f32_e32 vcc, s33, v2
	v_fma_f32 v3, v3, s78, -v87
	v_fma_f32 v4, v4, s78, -v87
	v_cndmask_b32_e32 v66, 0, v177, vcc
	v_add_f32_e32 v2, v2, v66
	v_exp_f32_e32 v2, v2
	v_cndmask_b32_e32 v66, 0, v200, vcc
	v_cmp_le_i32_e32 vcc, v92, v86
	v_fma_f32 v5, v5, s78, -v87
	v_ldexp_f32 v2, v2, v66
	v_add_f32_e32 v2, v131, v2
	v_cndmask_b32_e32 v2, 0, v2, vcc
	v_cmp_gt_f32_e32 vcc, s33, v3
	v_fma_f32 v6, v6, s78, -v87
	v_fma_f32 v7, v7, s78, -v87
	v_cndmask_b32_e32 v66, 0, v177, vcc
	v_add_f32_e32 v3, v3, v66
	v_exp_f32_e32 v3, v3
	v_cndmask_b32_e32 v66, 0, v200, vcc
	v_cmp_le_i32_e32 vcc, v93, v86
	v_fma_f32 v8, v8, s78, -v87
	v_ldexp_f32 v3, v3, v66
	v_add_f32_e32 v3, v132, v3
	v_cndmask_b32_e32 v3, 0, v3, vcc
	v_cmp_gt_f32_e32 vcc, s33, v4
	v_fma_f32 v9, v9, s78, -v87
	v_fma_f32 v10, v10, s78, -v87
	v_cndmask_b32_e32 v66, 0, v177, vcc
	v_add_f32_e32 v4, v4, v66
	v_exp_f32_e32 v4, v4
	v_cndmask_b32_e32 v66, 0, v200, vcc
	v_cmp_le_i32_e32 vcc, v94, v86
	v_fma_f32 v11, v11, s78, -v87
	v_ldexp_f32 v4, v4, v66
	v_add_f32_e32 v4, v133, v4
	v_cndmask_b32_e32 v4, 0, v4, vcc
	v_cmp_gt_f32_e32 vcc, s33, v5
	v_fma_f32 v12, v12, s78, -v87
	v_fma_f32 v13, v13, s78, -v87
	v_cndmask_b32_e32 v66, 0, v177, vcc
	v_add_f32_e32 v5, v5, v66
	v_exp_f32_e32 v5, v5
	v_cndmask_b32_e32 v66, 0, v200, vcc
	v_cmp_le_i32_e32 vcc, v95, v86
	v_fma_f32 v14, v14, s78, -v87
	v_ldexp_f32 v5, v5, v66
	v_add_f32_e32 v5, v134, v5
	v_cndmask_b32_e32 v5, 0, v5, vcc
	v_cmp_gt_f32_e32 vcc, s33, v6
	v_fma_f32 v15, v15, s78, -v87
	v_fma_f32 v16, v16, s78, -v87
	v_cndmask_b32_e32 v66, 0, v177, vcc
	v_add_f32_e32 v6, v6, v66
	v_exp_f32_e32 v6, v6
	v_cndmask_b32_e32 v66, 0, v200, vcc
	v_cmp_le_i32_e32 vcc, v103, v86
	v_fma_f32 v17, v17, s78, -v87
	v_ldexp_f32 v6, v6, v66
	v_add_f32_e32 v6, v135, v6
	v_cndmask_b32_e32 v6, 0, v6, vcc
	v_cmp_gt_f32_e32 vcc, s33, v7
	v_add_f32_e32 v2, v2, v3
	v_add_f32_e32 v3, v4, v5
; DI int crow(int r, int hi) { return (r & 3) + 8 * (r >> 2) + 4 * hi; }
; __global__ void __launch_bounds__(512) mega_fwd(Params P) {
;     ...
; #pragma unroll
;                             for (int i = 0; i < 16; ++i) { const int c = 64 * t + 32 * kb + crow(i, hi); const bool valid = (16 * c + 31 <= qpos); ps[i] += valid ? exp2f(s[i] * (0.125f * LOG2E) - lse[r]) : 0.f; }
;                         }
; #pragma unroll
;                         for (int j = 0; j < 4; ++j) { const int n = 16 * t + 8 * kb + 2 * j + hi; s1row[n] = (ps[4 * j] + ps[4 * j + 1]) + (ps[4 * j + 2] + ps[4 * j + 3]); s2row[n] = ps[4 * j + 3]; }
	v_cndmask_b32_e32 v66, 0, v177, vcc
	v_add_f32_e32 v7, v7, v66
	v_exp_f32_e32 v7, v7
	v_cndmask_b32_e32 v66, 0, v200, vcc
	v_cmp_le_i32_e32 vcc, v104, v86
	v_add_f32_e32 v4, v2, v3
	v_ldexp_f32 v7, v7, v66
	v_add_f32_e32 v7, v136, v7
	v_cndmask_b32_e32 v7, 0, v7, vcc
	v_cmp_gt_f32_e32 vcc, s33, v8
	v_lshl_add_u64 v[2:3], s[2:3], 0, v[90:91]
	v_add_u32_e32 v104, 0x3af, v102
	v_cndmask_b32_e32 v66, 0, v177, vcc
	v_add_f32_e32 v8, v8, v66
	v_exp_f32_e32 v8, v8
	v_cndmask_b32_e32 v66, 0, v200, vcc
	v_cmp_le_i32_e32 vcc, v114, v86
	v_add_u32_e32 v114, 0x24f, v102
	v_ldexp_f32 v8, v8, v66
	v_add_f32_e32 v8, v137, v8
	v_cndmask_b32_e32 v8, 0, v8, vcc
	v_cmp_gt_f32_e32 vcc, s33, v9
	s_nop 1
	v_cndmask_b32_e32 v66, 0, v177, vcc
	v_add_f32_e32 v9, v9, v66
	v_exp_f32_e32 v9, v9
	v_cndmask_b32_e32 v66, 0, v200, vcc
	v_cmp_le_i32_e32 vcc, v113, v86
	v_add_u32_e32 v113, 0x29f, v102
	v_ldexp_f32 v9, v9, v66
	v_add_f32_e32 v9, v122, v9
	v_cndmask_b32_e32 v9, 0, v9, vcc
	v_cmp_gt_f32_e32 vcc, s33, v10
	s_nop 1
	v_cndmask_b32_e32 v66, 0, v177, vcc
	v_add_f32_e32 v10, v10, v66
	v_exp_f32_e32 v10, v10
	v_cndmask_b32_e32 v66, 0, v200, vcc
	v_cmp_le_i32_e32 vcc, v112, v86
	v_add_u32_e32 v112, 0x2af, v102
	v_ldexp_f32 v10, v10, v66
	v_add_f32_e32 v10, v123, v10
	v_cndmask_b32_e32 v10, 0, v10, vcc
	v_cmp_gt_f32_e32 vcc, s33, v11
	s_nop 1
	v_cndmask_b32_e32 v66, 0, v177, vcc
	v_add_f32_e32 v11, v11, v66
	v_exp_f32_e32 v11, v11
	v_cndmask_b32_e32 v66, 0, v200, vcc
	v_cmp_le_i32_e32 vcc, v111, v86
	v_add_u32_e32 v111, 0x2bf, v102
	v_ldexp_f32 v11, v11, v66
	v_add_f32_e32 v11, v121, v11
	v_cndmask_b32_e32 v11, 0, v11, vcc
	v_cmp_gt_f32_e32 vcc, s33, v12
	s_nop 1
	v_cndmask_b32_e32 v66, 0, v177, vcc
	v_add_f32_e32 v12, v12, v66
	v_exp_f32_e32 v12, v12
	v_cndmask_b32_e32 v66, 0, v200, vcc
	v_cmp_le_i32_e32 vcc, v110, v86
	v_add_u32_e32 v110, 0x2cf, v102
	v_ldexp_f32 v12, v12, v66
	v_add_f32_e32 v12, v120, v12
	v_cndmask_b32_e32 v12, 0, v12, vcc
	v_cmp_gt_f32_e32 vcc, s33, v13
	s_nop 1
	v_cndmask_b32_e32 v66, 0, v177, vcc
	v_add_f32_e32 v13, v13, v66
	v_exp_f32_e32 v13, v13
	v_cndmask_b32_e32 v66, 0, v200, vcc
	v_cmp_le_i32_e32 vcc, v109, v86
	v_add_u32_e32 v109, 0x31f, v102
	v_ldexp_f32 v13, v13, v66
	v_add_f32_e32 v13, v119, v13
	v_cndmask_b32_e32 v13, 0, v13, vcc
	v_cmp_gt_f32_e32 vcc, s33, v14
	s_nop 1
	v_cndmask_b32_e32 v66, 0, v177, vcc
	v_add_f32_e32 v14, v14, v66
	v_exp_f32_e32 v14, v14
	v_cndmask_b32_e32 v66, 0, v200, vcc
	v_cmp_le_i32_e32 vcc, v108, v86
	v_add_u32_e32 v108, 0x32f, v102
	v_ldexp_f32 v14, v14, v66
	v_add_f32_e32 v14, v118, v14
	v_cndmask_b32_e32 v14, 0, v14, vcc
	v_cmp_gt_f32_e32 vcc, s33, v15
	s_nop 1
	v_cndmask_b32_e32 v66, 0, v177, vcc
	v_add_f32_e32 v15, v15, v66
	v_exp_f32_e32 v15, v15
	v_cndmask_b32_e32 v66, 0, v200, vcc
	v_cmp_le_i32_e32 vcc, v107, v86
	v_add_u32_e32 v107, 0x33f, v102
	v_ldexp_f32 v15, v15, v66
	v_add_f32_e32 v15, v117, v15
	v_cndmask_b32_e32 v15, 0, v15, vcc
	v_cmp_gt_f32_e32 vcc, s33, v16
	v_add_u32_e32 v117, 0x21f, v102
	s_nop 0
	v_cndmask_b32_e32 v66, 0, v177, vcc
	v_add_f32_e32 v16, v16, v66
	v_exp_f32_e32 v16, v16
	v_cndmask_b32_e32 v66, 0, v200, vcc
	v_cmp_le_i32_e32 vcc, v106, v86
	v_add_u32_e32 v106, 0x34f, v102
	v_ldexp_f32 v16, v16, v66
	v_add_f32_e32 v16, v116, v16
	v_cndmask_b32_e32 v16, 0, v16, vcc
	v_cmp_gt_f32_e32 vcc, s33, v17
	v_add_u32_e32 v116, 0x22f, v102
	s_nop 0
	v_cndmask_b32_e32 v66, 0, v177, vcc
	v_add_f32_e32 v17, v17, v66
	v_exp_f32_e32 v17, v17
	v_cndmask_b32_e32 v66, 0, v200, vcc
	v_cmp_le_i32_e32 vcc, v105, v86
	v_add_u32_e32 v105, 0x39f, v102
	v_ldexp_f32 v17, v17, v66
	v_add_f32_e32 v17, v115, v17
	v_cndmask_b32_e32 v17, 0, v17, vcc
	v_add_co_u32_e32 v92, vcc, s14, v2
	s_mov_b32 s14, 0xda00000
	s_nop 0
	v_addc_co_u32_e32 v93, vcc, 0, v3, vcc
	v_add_co_u32_e32 v94, vcc, s14, v2
	v_add_f32_e32 v2, v6, v7
	s_nop 0
	v_addc_co_u32_e32 v95, vcc, 0, v3, vcc
	v_add_f32_e32 v3, v8, v9
	v_add_f32_e32 v2, v2, v3
	flat_store_dword v[92:93], v4
	flat_store_dword v[94:95], v5
	flat_store_dword v[92:93], v2 offset:8
	flat_store_dword v[94:95], v9 offset:8
	v_add_f32_e32 v2, v10, v11
	v_add_f32_e32 v3, v12, v13
	v_add_f32_e32 v2, v2, v3
	flat_store_dword v[92:93], v2 offset:16
	flat_store_dword v[94:95], v13 offset:16
	v_add_f32_e32 v2, v14, v15
	v_add_f32_e32 v3, v16, v17
	v_add_f32_e32 v2, v2, v3
	flat_store_dword v[92:93], v2 offset:24
	flat_store_dword v[94:95], v17 offset:24
	ds_read_b128 v[78:81], v101 offset:4608
	ds_read_b128 v[74:77], v101 offset:4640
	s_waitcnt lgkmcnt(0)
	v_mfma_f32_32x32x16_bf16 v[2:17], v[78:81], v[18:21], 0
	ds_read_b128 v[70:73], v101 offset:4672
	ds_read_b128 v[66:69], v101 offset:4704
	v_add_u32_e32 v115, 0x23f, v102
	v_mfma_f32_32x32x16_bf16 v[2:17], v[74:77], v[22:25], v[2:17]
	s_waitcnt lgkmcnt(0)
; #define LAS __attribute__((address_space(3)))
; DI int crow(int r, int hi) { return (r & 3) + 8 * (r >> 2) + 4 * hi; }
; #define MFMA32(a, b, c) __builtin_amdgcn_mfma_f32_32x32x16_bf16((a), (b), (c), 0, 0, 0)
; __global__ void __launch_bounds__(512) mega_fwd(Params P) {
;     ...
;                     for (int kb = 0; kb < 2; ++kb) {
;                         f32x16 ps = (f32x16){};
; #pragma unroll
;                         for (int r = 0; r < 3; ++r) {
;                             f32x16 s = (f32x16){};
; #pragma unroll
;                             for (int ks = 0; ks < 4; ++ks) { const bf16x8 a = *(const LAS bf16x8*)(Ks + (32 * kb + r32) * 144 + ks * 32 + hi * 16); s = MFMA32(a, qf[r][ks], s); }
; #pragma unroll
;                             for (int i = 0; i < 16; ++i) { const int c = 64 * t + 32 * kb + crow(i, hi); const bool valid = (16 * c + 31 <= qpos); ps[i] += valid ? exp2f(s[i] * (0.125f * LOG2E) - lse[r]) : 0.f; }
;                         }
	v_mfma_f32_32x32x16_bf16 v[2:17], v[70:73], v[26:29], v[2:17]
	v_mfma_f32_32x32x16_bf16 v[2:17], v[66:69], v[30:33], v[2:17]
	s_nop 11
	v_fma_f32 v2, v2, s78, -v0
	v_cmp_gt_f32_e32 vcc, s33, v2
	s_nop 1
	v_cndmask_b32_e32 v103, 0, v177, vcc
	v_add_f32_e32 v2, v2, v103
	v_exp_f32_e32 v2, v2
	v_cndmask_b32_e32 v103, 0, v200, vcc
	v_ldexp_f32 v118, v2, v103
	v_fma_f32 v2, v3, s78, -v0
	v_cmp_gt_f32_e32 vcc, s33, v2
	v_add_u32_e32 v103, 0x3bf, v102
	v_add_u32_e32 v102, 0x3cf, v102
	v_cndmask_b32_e32 v3, 0, v177, vcc
	v_add_f32_e32 v2, v2, v3
	v_exp_f32_e32 v2, v2
	v_cndmask_b32_e32 v3, 0, v200, vcc
	v_ldexp_f32 v119, v2, v3
	v_fma_f32 v2, v4, s78, -v0
	v_cmp_gt_f32_e32 vcc, s33, v2
	s_nop 1
	v_cndmask_b32_e32 v3, 0, v177, vcc
	v_add_f32_e32 v2, v2, v3
	v_exp_f32_e32 v2, v2
	v_cndmask_b32_e32 v3, 0, v200, vcc
	v_ldexp_f32 v120, v2, v3
	v_fma_f32 v2, v5, s78, -v0
	v_cmp_gt_f32_e32 vcc, s33, v2
	s_nop 1
	v_cndmask_b32_e32 v3, 0, v177, vcc
	v_add_f32_e32 v2, v2, v3
	v_exp_f32_e32 v2, v2
	v_cndmask_b32_e32 v3, 0, v200, vcc
	v_ldexp_f32 v121, v2, v3
	v_fma_f32 v2, v6, s78, -v0
	v_cmp_gt_f32_e32 vcc, s33, v2
	s_nop 1
	v_cndmask_b32_e32 v3, 0, v177, vcc
	v_add_f32_e32 v2, v2, v3
	v_exp_f32_e32 v2, v2
	v_cndmask_b32_e32 v3, 0, v200, vcc
	v_ldexp_f32 v122, v2, v3
	v_fma_f32 v2, v7, s78, -v0
	v_cmp_gt_f32_e32 vcc, s33, v2
	s_nop 1
	v_cndmask_b32_e32 v3, 0, v177, vcc
	v_add_f32_e32 v2, v2, v3
	v_exp_f32_e32 v2, v2
	v_cndmask_b32_e32 v3, 0, v200, vcc
	v_ldexp_f32 v123, v2, v3
	v_fma_f32 v2, v8, s78, -v0
	v_cmp_gt_f32_e32 vcc, s33, v2
	s_nop 1
	v_cndmask_b32_e32 v3, 0, v177, vcc
	v_add_f32_e32 v2, v2, v3
	v_exp_f32_e32 v2, v2
	v_cndmask_b32_e32 v3, 0, v200, vcc
	v_ldexp_f32 v124, v2, v3
	v_fma_f32 v2, v9, s78, -v0
	v_cmp_gt_f32_e32 vcc, s33, v2
	s_nop 1
	v_cndmask_b32_e32 v3, 0, v177, vcc
	v_add_f32_e32 v2, v2, v3
	v_exp_f32_e32 v2, v2
	v_cndmask_b32_e32 v3, 0, v200, vcc
	v_ldexp_f32 v125, v2, v3
	v_fma_f32 v2, v10, s78, -v0
	v_cmp_gt_f32_e32 vcc, s33, v2
	s_nop 1
	v_cndmask_b32_e32 v3, 0, v177, vcc
	v_add_f32_e32 v2, v2, v3
	v_exp_f32_e32 v2, v2
	v_cndmask_b32_e32 v3, 0, v200, vcc
	v_ldexp_f32 v126, v2, v3
	v_fma_f32 v2, v11, s78, -v0
	v_cmp_gt_f32_e32 vcc, s33, v2
	s_nop 1
	v_cndmask_b32_e32 v3, 0, v177, vcc
	v_add_f32_e32 v2, v2, v3
	v_exp_f32_e32 v2, v2
	v_cndmask_b32_e32 v3, 0, v200, vcc
	v_ldexp_f32 v127, v2, v3
	v_fma_f32 v2, v12, s78, -v0
	v_cmp_gt_f32_e32 vcc, s33, v2
	s_nop 1
	v_cndmask_b32_e32 v3, 0, v177, vcc
	v_add_f32_e32 v2, v2, v3
	v_exp_f32_e32 v2, v2
	v_cndmask_b32_e32 v3, 0, v200, vcc
	v_ldexp_f32 v128, v2, v3
	v_fma_f32 v2, v13, s78, -v0
	v_cmp_gt_f32_e32 vcc, s33, v2
	s_nop 1
	v_cndmask_b32_e32 v3, 0, v177, vcc
	v_add_f32_e32 v2, v2, v3
	v_exp_f32_e32 v2, v2
	v_cndmask_b32_e32 v3, 0, v200, vcc
	v_ldexp_f32 v129, v2, v3
	v_fma_f32 v2, v14, s78, -v0
	v_cmp_gt_f32_e32 vcc, s33, v2
	s_nop 1
	v_cndmask_b32_e32 v3, 0, v177, vcc
	v_add_f32_e32 v2, v2, v3
	v_exp_f32_e32 v2, v2
	v_cndmask_b32_e32 v3, 0, v200, vcc
	v_ldexp_f32 v130, v2, v3
	v_fma_f32 v2, v15, s78, -v0
	v_cmp_gt_f32_e32 vcc, s33, v2
	s_nop 1
	v_cndmask_b32_e32 v3, 0, v177, vcc
	v_add_f32_e32 v2, v2, v3
	v_exp_f32_e32 v2, v2
	v_cndmask_b32_e32 v3, 0, v200, vcc
	v_ldexp_f32 v131, v2, v3
	v_fma_f32 v2, v16, s78, -v0
	v_cmp_gt_f32_e32 vcc, s33, v2
	s_nop 1
	v_cndmask_b32_e32 v3, 0, v177, vcc
	v_add_f32_e32 v2, v2, v3
	v_exp_f32_e32 v2, v2
	v_cndmask_b32_e32 v3, 0, v200, vcc
	v_ldexp_f32 v132, v2, v3
	v_fma_f32 v2, v17, s78, -v0
	v_cmp_gt_f32_e32 vcc, s33, v2
	s_nop 1
	v_cndmask_b32_e32 v3, 0, v177, vcc
	v_add_f32_e32 v2, v2, v3
	v_exp_f32_e32 v2, v2
	v_cndmask_b32_e32 v3, 0, v200, vcc
	v_ldexp_f32 v133, v2, v3
	v_mfma_f32_32x32x16_bf16 v[2:17], v[78:81], v[34:37], 0
	v_mfma_f32_32x32x16_bf16 v[2:17], v[74:77], v[38:41], v[2:17]
	v_mfma_f32_32x32x16_bf16 v[2:17], v[70:73], v[42:45], v[2:17]
	v_mfma_f32_32x32x16_bf16 v[2:17], v[66:69], v[46:49], v[2:17]
	s_nop 11
	v_fma_f32 v2, v2, s78, -v85
	v_cmp_gt_f32_e32 vcc, s33, v2
	s_nop 1
	v_cndmask_b32_e32 v134, 0, v177, vcc
	v_add_f32_e32 v2, v2, v134
	v_exp_f32_e32 v2, v2
	v_cndmask_b32_e32 v134, 0, v200, vcc
	v_ldexp_f32 v2, v2, v134
	v_add_f32_e32 v134, v118, v2
	v_fma_f32 v2, v3, s78, -v85
	v_cmp_gt_f32_e32 vcc, s33, v2
	s_nop 1
	v_cndmask_b32_e32 v3, 0, v177, vcc
	v_add_f32_e32 v2, v2, v3
	v_exp_f32_e32 v2, v2
	v_cndmask_b32_e32 v3, 0, v200, vcc
	v_ldexp_f32 v2, v2, v3
	v_add_f32_e32 v135, v119, v2
	v_fma_f32 v2, v4, s78, -v85
	v_cmp_gt_f32_e32 vcc, s33, v2
	s_nop 1
	v_cndmask_b32_e32 v3, 0, v177, vcc
	v_add_f32_e32 v2, v2, v3
	v_exp_f32_e32 v2, v2
	v_cndmask_b32_e32 v3, 0, v200, vcc
	v_ldexp_f32 v2, v2, v3
	v_add_f32_e32 v136, v120, v2
	v_fma_f32 v2, v5, s78, -v85
	v_cmp_gt_f32_e32 vcc, s33, v2
	s_nop 1
	v_cndmask_b32_e32 v3, 0, v177, vcc
	v_add_f32_e32 v2, v2, v3
	v_exp_f32_e32 v2, v2
	v_cndmask_b32_e32 v3, 0, v200, vcc
	v_ldexp_f32 v2, v2, v3
	v_add_f32_e32 v137, v121, v2
	v_fma_f32 v2, v6, s78, -v85
	v_cmp_gt_f32_e32 vcc, s33, v2
	s_nop 1
	v_cndmask_b32_e32 v3, 0, v177, vcc
	v_add_f32_e32 v2, v2, v3
	v_exp_f32_e32 v2, v2
	v_cndmask_b32_e32 v3, 0, v200, vcc
	v_ldexp_f32 v2, v2, v3
	v_add_f32_e32 v138, v122, v2
	v_fma_f32 v2, v7, s78, -v85
	v_cmp_gt_f32_e32 vcc, s33, v2
	s_nop 1
	v_cndmask_b32_e32 v3, 0, v177, vcc
	v_add_f32_e32 v2, v2, v3
	v_exp_f32_e32 v2, v2
	v_cndmask_b32_e32 v3, 0, v200, vcc
	v_ldexp_f32 v2, v2, v3
	v_add_f32_e32 v139, v123, v2
	v_fma_f32 v2, v8, s78, -v85
	v_cmp_gt_f32_e32 vcc, s33, v2
	s_nop 1
	v_cndmask_b32_e32 v3, 0, v177, vcc
	v_add_f32_e32 v2, v2, v3
	v_exp_f32_e32 v2, v2
	v_cndmask_b32_e32 v3, 0, v200, vcc
	v_ldexp_f32 v2, v2, v3
	v_add_f32_e32 v140, v124, v2
	v_fma_f32 v2, v9, s78, -v85
; #define LAS __attribute__((address_space(3)))
; DI int crow(int r, int hi) { return (r & 3) + 8 * (r >> 2) + 4 * hi; }
; #define MFMA32(a, b, c) __builtin_amdgcn_mfma_f32_32x32x16_bf16((a), (b), (c), 0, 0, 0)
; __global__ void __launch_bounds__(512) mega_fwd(Params P) {
;     ...
;                     for (int kb = 0; kb < 2; ++kb) {
;                         f32x16 ps = (f32x16){};
; #pragma unroll
;                         for (int r = 0; r < 3; ++r) {
;                             f32x16 s = (f32x16){};
; #pragma unroll
;                             for (int ks = 0; ks < 4; ++ks) { const bf16x8 a = *(const LAS bf16x8*)(Ks + (32 * kb + r32) * 144 + ks * 32 + hi * 16); s = MFMA32(a, qf[r][ks], s); }
; #pragma unroll
;                             for (int i = 0; i < 16; ++i) { const int c = 64 * t + 32 * kb + crow(i, hi); const bool valid = (16 * c + 31 <= qpos); ps[i] += valid ? exp2f(s[i] * (0.125f * LOG2E) - lse[r]) : 0.f; }
;                         }
	v_cmp_gt_f32_e32 vcc, s33, v2
	s_nop 1
	v_cndmask_b32_e32 v3, 0, v177, vcc
	v_add_f32_e32 v2, v2, v3
	v_exp_f32_e32 v2, v2
	v_cndmask_b32_e32 v3, 0, v200, vcc
	v_ldexp_f32 v2, v2, v3
	v_add_f32_e32 v125, v125, v2
	v_fma_f32 v2, v10, s78, -v85
	v_cmp_gt_f32_e32 vcc, s33, v2
	s_nop 1
	v_cndmask_b32_e32 v3, 0, v177, vcc
	v_add_f32_e32 v2, v2, v3
	v_exp_f32_e32 v2, v2
	v_cndmask_b32_e32 v3, 0, v200, vcc
	v_ldexp_f32 v2, v2, v3
	v_add_f32_e32 v126, v126, v2
	v_fma_f32 v2, v11, s78, -v85
	v_cmp_gt_f32_e32 vcc, s33, v2
	s_nop 1
	v_cndmask_b32_e32 v3, 0, v177, vcc
	v_add_f32_e32 v2, v2, v3
	v_exp_f32_e32 v2, v2
	v_cndmask_b32_e32 v3, 0, v200, vcc
	v_ldexp_f32 v2, v2, v3
	v_add_f32_e32 v124, v127, v2
	v_fma_f32 v2, v12, s78, -v85
	v_cmp_gt_f32_e32 vcc, s33, v2
	s_nop 1
	v_cndmask_b32_e32 v3, 0, v177, vcc
	v_add_f32_e32 v2, v2, v3
	v_exp_f32_e32 v2, v2
	v_cndmask_b32_e32 v3, 0, v200, vcc
	v_ldexp_f32 v2, v2, v3
	v_add_f32_e32 v123, v128, v2
	v_fma_f32 v2, v13, s78, -v85
	v_cmp_gt_f32_e32 vcc, s33, v2
	s_nop 1
	v_cndmask_b32_e32 v3, 0, v177, vcc
	v_add_f32_e32 v2, v2, v3
	v_exp_f32_e32 v2, v2
	v_cndmask_b32_e32 v3, 0, v200, vcc
	v_ldexp_f32 v2, v2, v3
	v_add_f32_e32 v122, v129, v2
	v_fma_f32 v2, v14, s78, -v85
	v_cmp_gt_f32_e32 vcc, s33, v2
	s_nop 1
	v_cndmask_b32_e32 v3, 0, v177, vcc
	v_add_f32_e32 v2, v2, v3
	v_exp_f32_e32 v2, v2
	v_cndmask_b32_e32 v3, 0, v200, vcc
	v_ldexp_f32 v2, v2, v3
	v_add_f32_e32 v121, v130, v2
	v_fma_f32 v2, v15, s78, -v85
	v_cmp_gt_f32_e32 vcc, s33, v2
	s_nop 1
	v_cndmask_b32_e32 v3, 0, v177, vcc
	v_add_f32_e32 v2, v2, v3
	v_exp_f32_e32 v2, v2
	v_cndmask_b32_e32 v3, 0, v200, vcc
	v_ldexp_f32 v2, v2, v3
	v_add_f32_e32 v120, v131, v2
	v_fma_f32 v2, v16, s78, -v85
	v_cmp_gt_f32_e32 vcc, s33, v2
	s_nop 1
	v_cndmask_b32_e32 v3, 0, v177, vcc
	v_add_f32_e32 v2, v2, v3
	v_exp_f32_e32 v2, v2
	v_cndmask_b32_e32 v3, 0, v200, vcc
	v_ldexp_f32 v2, v2, v3
	v_add_f32_e32 v119, v132, v2
	v_fma_f32 v2, v17, s78, -v85
	v_cmp_gt_f32_e32 vcc, s33, v2
	s_nop 1
	v_cndmask_b32_e32 v3, 0, v177, vcc
	v_add_f32_e32 v2, v2, v3
	v_exp_f32_e32 v2, v2
	v_cndmask_b32_e32 v3, 0, v200, vcc
	v_ldexp_f32 v2, v2, v3
	v_add_f32_e32 v118, v133, v2
	v_mfma_f32_32x32x16_bf16 v[2:17], v[78:81], v[50:53], 0
	v_mfma_f32_32x32x16_bf16 v[2:17], v[74:77], v[54:57], v[2:17]
	v_mfma_f32_32x32x16_bf16 v[2:17], v[70:73], v[58:61], v[2:17]
	v_mfma_f32_32x32x16_bf16 v[2:17], v[66:69], v[62:65], v[2:17]
	s_nop 11
	v_fma_f32 v2, v2, s78, -v87
	v_cmp_gt_f32_e32 vcc, s33, v2
	v_fma_f32 v3, v3, s78, -v87
	v_fma_f32 v4, v4, s78, -v87
	v_cndmask_b32_e32 v66, 0, v177, vcc
	v_add_f32_e32 v2, v2, v66
	v_exp_f32_e32 v2, v2
	v_cndmask_b32_e32 v66, 0, v200, vcc
	v_cmp_le_i32_e32 vcc, v117, v86
	v_fma_f32 v5, v5, s78, -v87
	v_ldexp_f32 v2, v2, v66
	v_add_f32_e32 v2, v134, v2
	v_cndmask_b32_e32 v2, 0, v2, vcc
	v_cmp_gt_f32_e32 vcc, s33, v3
	v_fma_f32 v6, v6, s78, -v87
	v_fma_f32 v7, v7, s78, -v87
	v_cndmask_b32_e32 v66, 0, v177, vcc
	v_add_f32_e32 v3, v3, v66
	v_exp_f32_e32 v3, v3
	v_cndmask_b32_e32 v66, 0, v200, vcc
	v_cmp_le_i32_e32 vcc, v116, v86
	v_fma_f32 v8, v8, s78, -v87
	v_ldexp_f32 v3, v3, v66
	v_add_f32_e32 v3, v135, v3
	v_cndmask_b32_e32 v3, 0, v3, vcc
	v_cmp_gt_f32_e32 vcc, s33, v4
	v_fma_f32 v9, v9, s78, -v87
	v_fma_f32 v10, v10, s78, -v87
	v_cndmask_b32_e32 v66, 0, v177, vcc
	v_add_f32_e32 v4, v4, v66
	v_exp_f32_e32 v4, v4
	v_cndmask_b32_e32 v66, 0, v200, vcc
	v_cmp_le_i32_e32 vcc, v115, v86
	v_fma_f32 v11, v11, s78, -v87
	v_ldexp_f32 v4, v4, v66
	v_add_f32_e32 v4, v136, v4
	v_cndmask_b32_e32 v4, 0, v4, vcc
	v_cmp_gt_f32_e32 vcc, s33, v5
	v_fma_f32 v12, v12, s78, -v87
	v_fma_f32 v13, v13, s78, -v87
	v_cndmask_b32_e32 v66, 0, v177, vcc
	v_add_f32_e32 v5, v5, v66
	v_exp_f32_e32 v5, v5
	v_cndmask_b32_e32 v66, 0, v200, vcc
	v_cmp_le_i32_e32 vcc, v114, v86
	v_fma_f32 v14, v14, s78, -v87
	v_ldexp_f32 v5, v5, v66
	v_add_f32_e32 v5, v137, v5
	v_cndmask_b32_e32 v5, 0, v5, vcc
	v_cmp_gt_f32_e32 vcc, s33, v6
	v_fma_f32 v15, v15, s78, -v87
	v_fma_f32 v16, v16, s78, -v87
	v_cndmask_b32_e32 v66, 0, v177, vcc
	v_add_f32_e32 v6, v6, v66
; DI int crow(int r, int hi) { return (r & 3) + 8 * (r >> 2) + 4 * hi; }
; __global__ void __launch_bounds__(512) mega_fwd(Params P) {
;     ...
; #pragma unroll
;                             for (int i = 0; i < 16; ++i) { const int c = 64 * t + 32 * kb + crow(i, hi); const bool valid = (16 * c + 31 <= qpos); ps[i] += valid ? exp2f(s[i] * (0.125f * LOG2E) - lse[r]) : 0.f; }
;                         }
; #pragma unroll
;                         for (int j = 0; j < 4; ++j) { const int n = 16 * t + 8 * kb + 2 * j + hi; s1row[n] = (ps[4 * j] + ps[4 * j + 1]) + (ps[4 * j + 2] + ps[4 * j + 3]); s2row[n] = ps[4 * j + 3]; }
	v_exp_f32_e32 v6, v6
	v_cndmask_b32_e32 v66, 0, v200, vcc
	v_cmp_le_i32_e32 vcc, v113, v86
	v_fma_f32 v17, v17, s78, -v87
	v_ldexp_f32 v6, v6, v66
	v_add_f32_e32 v6, v138, v6
	v_cndmask_b32_e32 v6, 0, v6, vcc
	v_cmp_gt_f32_e32 vcc, s33, v7
	v_add_f32_e32 v2, v2, v3
	v_add_f32_e32 v3, v4, v5
	v_cndmask_b32_e32 v66, 0, v177, vcc
	v_add_f32_e32 v7, v7, v66
	v_exp_f32_e32 v7, v7
	v_cndmask_b32_e32 v66, 0, v200, vcc
	v_cmp_le_i32_e32 vcc, v112, v86
	v_add_f32_e32 v2, v2, v3
	v_ldexp_f32 v7, v7, v66
	v_add_f32_e32 v7, v139, v7
	v_cndmask_b32_e32 v7, 0, v7, vcc
	v_cmp_gt_f32_e32 vcc, s33, v8
	flat_store_dword v[92:93], v2 offset:32
	flat_store_dword v[94:95], v5 offset:32
	v_cndmask_b32_e32 v66, 0, v177, vcc
	v_add_f32_e32 v8, v8, v66
	v_exp_f32_e32 v8, v8
	v_cndmask_b32_e32 v66, 0, v200, vcc
	v_cmp_le_i32_e32 vcc, v111, v86
	v_add_f32_e32 v2, v6, v7
	v_ldexp_f32 v8, v8, v66
	v_add_f32_e32 v8, v140, v8
	v_cndmask_b32_e32 v8, 0, v8, vcc
	v_cmp_gt_f32_e32 vcc, s33, v9
	s_nop 1
	v_cndmask_b32_e32 v66, 0, v177, vcc
	v_add_f32_e32 v9, v9, v66
	v_exp_f32_e32 v9, v9
	v_cndmask_b32_e32 v66, 0, v200, vcc
	v_cmp_le_i32_e32 vcc, v110, v86
	v_ldexp_f32 v9, v9, v66
	v_add_f32_e32 v9, v125, v9
	v_cndmask_b32_e32 v9, 0, v9, vcc
	v_cmp_gt_f32_e32 vcc, s33, v10
	v_add_f32_e32 v3, v8, v9
	v_add_f32_e32 v2, v2, v3
	v_cndmask_b32_e32 v66, 0, v177, vcc
	v_add_f32_e32 v10, v10, v66
	v_exp_f32_e32 v10, v10
	v_cndmask_b32_e32 v66, 0, v200, vcc
	v_cmp_le_i32_e32 vcc, v109, v86
	flat_store_dword v[92:93], v2 offset:40
	flat_store_dword v[94:95], v9 offset:40
	v_ldexp_f32 v10, v10, v66
	v_add_f32_e32 v10, v126, v10
	v_cndmask_b32_e32 v10, 0, v10, vcc
	v_cmp_gt_f32_e32 vcc, s33, v11
	s_nop 1
	v_cndmask_b32_e32 v66, 0, v177, vcc
	v_add_f32_e32 v11, v11, v66
	v_exp_f32_e32 v11, v11
	v_cndmask_b32_e32 v66, 0, v200, vcc
	v_cmp_le_i32_e32 vcc, v108, v86
	v_ldexp_f32 v11, v11, v66
	v_add_f32_e32 v11, v124, v11
	v_cndmask_b32_e32 v11, 0, v11, vcc
	v_cmp_gt_f32_e32 vcc, s33, v12
	v_add_f32_e32 v2, v10, v11
	s_nop 0
	v_cndmask_b32_e32 v66, 0, v177, vcc
	v_add_f32_e32 v12, v12, v66
	v_exp_f32_e32 v12, v12
	v_cndmask_b32_e32 v66, 0, v200, vcc
	v_cmp_le_i32_e32 vcc, v107, v86
	v_ldexp_f32 v12, v12, v66
	v_add_f32_e32 v12, v123, v12
	v_cndmask_b32_e32 v12, 0, v12, vcc
	v_cmp_gt_f32_e32 vcc, s33, v13
	s_nop 1
	v_cndmask_b32_e32 v66, 0, v177, vcc
	v_add_f32_e32 v13, v13, v66
	v_exp_f32_e32 v13, v13
	v_cndmask_b32_e32 v66, 0, v200, vcc
	v_cmp_le_i32_e32 vcc, v106, v86
	v_ldexp_f32 v13, v13, v66
	v_add_f32_e32 v13, v122, v13
	v_cndmask_b32_e32 v13, 0, v13, vcc
	v_cmp_gt_f32_e32 vcc, s33, v14
	v_add_f32_e32 v3, v12, v13
	v_add_f32_e32 v2, v2, v3
	v_cndmask_b32_e32 v66, 0, v177, vcc
	v_add_f32_e32 v14, v14, v66
	v_exp_f32_e32 v14, v14
	v_cndmask_b32_e32 v66, 0, v200, vcc
	v_cmp_le_i32_e32 vcc, v105, v86
	flat_store_dword v[92:93], v2 offset:48
	flat_store_dword v[94:95], v13 offset:48
	v_ldexp_f32 v14, v14, v66
	v_add_f32_e32 v14, v121, v14
	v_cndmask_b32_e32 v14, 0, v14, vcc
	v_cmp_gt_f32_e32 vcc, s33, v15
	s_nop 1
	v_cndmask_b32_e32 v66, 0, v177, vcc
	v_add_f32_e32 v15, v15, v66
	v_exp_f32_e32 v15, v15
	v_cndmask_b32_e32 v66, 0, v200, vcc
	v_cmp_le_i32_e32 vcc, v104, v86
	v_ldexp_f32 v15, v15, v66
	v_add_f32_e32 v15, v120, v15
	v_cndmask_b32_e32 v15, 0, v15, vcc
	v_cmp_gt_f32_e32 vcc, s33, v16
	v_add_f32_e32 v2, v14, v15
	s_nop 0
	v_cndmask_b32_e32 v66, 0, v177, vcc
	v_add_f32_e32 v16, v16, v66
	v_exp_f32_e32 v16, v16
	v_cndmask_b32_e32 v66, 0, v200, vcc
	v_cmp_le_i32_e32 vcc, v103, v86
	v_ldexp_f32 v16, v16, v66
	v_add_f32_e32 v16, v119, v16
	v_cndmask_b32_e32 v16, 0, v16, vcc
	v_cmp_gt_f32_e32 vcc, s33, v17
	s_nop 1
	v_cndmask_b32_e32 v66, 0, v177, vcc
	v_add_f32_e32 v17, v17, v66
	v_exp_f32_e32 v17, v17
	v_cndmask_b32_e32 v66, 0, v200, vcc
	v_cmp_le_i32_e32 vcc, v102, v86
	v_ldexp_f32 v17, v17, v66
	v_add_f32_e32 v17, v118, v17
	v_cndmask_b32_e32 v17, 0, v17, vcc
	v_add_f32_e32 v3, v16, v17
	v_add_f32_e32 v2, v2, v3
	flat_store_dword v[92:93], v2 offset:56
	flat_store_dword v[94:95], v17 offset:56
	s_branch .LBB0_1135

; DI unsigned cvtpk(float lo, float hi) { f32x2 v = {lo, hi}; bf16x2_t b = __builtin_convertvector(v, bf16x2_t); return __builtin_bit_cast(unsigned, b); }
; DI void norm_rows(const float* src, const float* gain, bf16_t* HN, int gw, int NGW, int lane) {
;     for (int mrow_ = gw; mrow_ < MTOK * REP_NORM; mrow_ += NGW) {
;         const int mrow = mrow_ & (MTOK - 1);
;         const f32x4* xr = (const f32x4*)(src + (size_t)mrow * DM) + lane;
;         f32x4 v[4]; float ss = 0.f;
; #pragma unroll
;         for (int j = 0; j < 4; ++j) { v[j] = xr[64 * j]; ss += (v[j].x * v[j].x + v[j].y * v[j].y) + (v[j].z * v[j].z + v[j].w * v[j].w); }
;         const float r = rsqrtf(wave_sum(ss) * (1.f / DM) + EPS);
;         u32x2* o8 = (u32x2*)(HN + (size_t)mrow * DM) + lane;
; #pragma unroll
;         for (int j = 0; j < 4; ++j) { const f32x4 gg = ((const f32x4*)gain)[lane + 64 * j]; u32x2 w; w.x = cvtpk(v[j].x * r * gg.x, v[j].y * r * gg.y); w.y = cvtpk(v[j].z * r * gg.z, v[j].w * r * gg.w); o8[64 * j] = w; }
;     }
.LBB0_1507:
	s_or_b64 exec, exec, s[0:1]
	s_mov_b32 s0, s81
	s_waitcnt lgkmcnt(0)
	s_barrier
	s_add_i32 s0, s0, 0x20040
	v_mov_b32_e32 v0, s0
	ds_read_b32 v2, v0 offset:200
	ds_read_b32 v0, v0 offset:204
	s_mov_b32 s0, 0
	s_add_i32 s0, s0, 0x20040
	v_mov_b32_e32 v3, s0
	s_waitcnt lgkmcnt(0)
	v_readfirstlane_b32 s1, v0
	s_mov_b32 s6, s82
	s_mov_b32 s7, s75
	v_mov_b32_e32 v0, v1
	s_mov_b32 s3, 0
	ds_read_b32 v4, v3 offset:192
	v_readfirstlane_b32 s0, v2
	ds_read_b32 v2, v3 offset:196
	s_mov_b32 s3, 0
	s_mov_b32 s3, 0
	s_add_i32 s3, s3, 0x20040
	v_mov_b32_e32 v3, s3
	s_waitcnt lgkmcnt(0)
	v_readfirstlane_b32 s2, v4
	ds_read_b32 v4, v3 offset:152
	v_readfirstlane_b32 s3, v2
	ds_read_b32 v2, v3 offset:156
	s_lshl_b32 s4, s7, 3
	s_add_i32 s4, s4, s74
	s_waitcnt lgkmcnt(0)
	v_readfirstlane_b32 s8, v4
	s_cmpk_gt_i32 s4, 0x3fff
	v_readfirstlane_b32 s9, v2
	s_mov_b32 s12, 0x800000
	s_cbranch_scc1 .LBB0_1510
	v_mbcnt_lo_u32_b32 v0, -1, v0
	v_readlane_b32 s10, v254, 25
	v_mbcnt_hi_u32_b32 v0, -1, v0
	v_readlane_b32 s11, v254, 26
	v_and_b32_e32 v4, 63, v0
	s_lshl_b32 s5, s6, 3
	s_lshl_b64 s[10:11], s[10:11], 2
	v_lshlrev_b32_e32 v0, 4, v4
	v_lshlrev_b32_e32 v4, 3, v4
	v_mov_b32_e32 v5, v1
	s_add_u32 s8, s8, s10
	v_lshl_add_u64 v[4:5], s[0:1], 0, v[4:5]
	s_mov_b64 s[0:1], 0x1c00000
	s_addc_u32 s9, s9, s11
	v_lshl_add_u64 v[4:5], v[4:5], 0, s[0:1]
	s_lshl_b32 s0, s7, 13
	v_readlane_b32 s1, v254, 8
	v_lshl_add_u64 v[2:3], s[2:3], 0, v[0:1]
	v_lshl_add_u64 v[6:7], s[8:9], 0, v[0:1]
	s_add_i32 s0, s1, s0
	s_lshl_b32 s1, s6, 13
	global_load_dwordx4 v[40:43], v[6:7], off
	global_load_dwordx4 v[44:47], v[6:7], off offset:1024
	global_load_dwordx4 v[48:51], v[6:7], off offset:2048
	global_load_dwordx4 v[52:55], v[6:7], off offset:3072
.LBB0_1509:
	s_and_b32 s2, s0, 0xfffc00
	s_lshl_b32 s80, s2, 2
	v_lshl_add_u64 v[20:21], v[2:3], 0, s[80:81]
	global_load_dwordx4 v[8:11], v[20:21], off
	global_load_dwordx4 v[12:15], v[20:21], off offset:1024
	global_load_dwordx4 v[16:19], v[20:21], off offset:2048
	s_nop 0
	global_load_dwordx4 v[20:23], v[20:21], off offset:3072
.Ln3_top:
	s_lshl_b32 s80, s2, 1
	v_lshl_add_u64 v[28:29], v[4:5], 0, s[80:81]
	s_add_i32 s4, s4, s5
	s_add_i32 s0, s0, s1
	s_cmpk_lt_i32 s4, 0x4000
	s_cbranch_scc0 .Ln3_lastA
	s_and_b32 s2, s0, 0xfffc00
	s_lshl_b32 s80, s2, 2
	v_lshl_add_u64 v[68:69], v[2:3], 0, s[80:81]
	global_load_dwordx4 v[56:59], v[68:69], off
	global_load_dwordx4 v[60:63], v[68:69], off offset:1024
	global_load_dwordx4 v[64:67], v[68:69], off offset:2048
	s_nop 0
	global_load_dwordx4 v[68:71], v[68:69], off offset:3072
	s_waitcnt vmcnt(4)
	v_mul_f32_e32 v0, v9, v9
	v_mul_f32_e32 v30, v11, v11
	v_mul_f32_e32 v31, v13, v13
	v_mul_f32_e32 v32, v15, v15
	v_mul_f32_e32 v33, v17, v17
	v_mul_f32_e32 v34, v19, v19
	v_fmac_f32_e32 v0, v8, v8
	v_fmac_f32_e32 v30, v10, v10
	v_fmac_f32_e32 v31, v12, v12
	v_fmac_f32_e32 v32, v14, v14
	v_mul_f32_e32 v35, v21, v21
	v_mul_f32_e32 v36, v23, v23
	v_fmac_f32_e32 v33, v16, v16
	v_fmac_f32_e32 v34, v18, v18
	v_add_f32_e32 v0, v0, v30
	v_add_f32_e32 v30, v31, v32
	v_fmac_f32_e32 v35, v20, v20
	v_fmac_f32_e32 v36, v22, v22
	v_add_f32_e32 v31, v33, v34
	v_add_f32_e32 v0, v0, v30
	v_add_f32_e32 v32, v35, v36
	v_add_f32_e32 v0, v0, v31
	v_add_f32_e32 v0, v0, v32
	ds_swizzle_b32 v30, v0 offset:swizzle(SWAP,1)
	s_waitcnt lgkmcnt(0)
	v_add_f32_e32 v0, v0, v30
	ds_swizzle_b32 v30, v0 offset:swizzle(SWAP,2)
	s_waitcnt lgkmcnt(0)
	v_add_f32_e32 v0, v0, v30
	ds_swizzle_b32 v30, v0 offset:swizzle(SWAP,4)
	s_waitcnt lgkmcnt(0)
	v_add_f32_e32 v0, v0, v30
	ds_swizzle_b32 v30, v0 offset:swizzle(SWAP,8)
	s_waitcnt lgkmcnt(0)
	v_add_f32_e32 v0, v0, v30
	ds_swizzle_b32 v30, v0 offset:swizzle(SWAP,16)
	s_waitcnt lgkmcnt(0)
	v_add_f32_e32 v0, v0, v30
	v_mov_b32_e32 v30, v0
	s_nop 1
	v_permlane32_swap_b32_e32 v0, v30
	v_add_f32_e32 v0, v0, v30
	v_fmamk_f32 v0, v0, 0x3a800000, v156
	v_mul_f32_e32 v30, 0x4b800000, v0
	v_cmp_gt_f32_e32 vcc, s12, v0
	s_nop 1
	v_cndmask_b32_e32 v0, v0, v30, vcc
	v_rsq_f32_e32 v0, v0
	s_nop 0
	v_mul_f32_e32 v30, 0x45800000, v0
	v_cndmask_b32_e32 v0, v0, v30, vcc
	v_pk_mul_f32 v[8:9], v[8:9], v[0:1] op_sel_hi:[1,0]
	v_pk_mul_f32 v[10:11], v[10:11], v[0:1] op_sel_hi:[1,0]
	v_pk_mul_f32 v[8:9], v[40:41], v[8:9]
	v_pk_mul_f32 v[10:11], v[42:43], v[10:11]
	v_cvt_pk_bf16_f32 v8, v8, v9
	v_cvt_pk_bf16_f32 v9, v10, v11
	global_store_dwordx2 v[28:29], v[8:9], off
	v_pk_mul_f32 v[12:13], v[12:13], v[0:1] op_sel_hi:[1,0]
	v_pk_mul_f32 v[14:15], v[14:15], v[0:1] op_sel_hi:[1,0]
	v_pk_mul_f32 v[12:13], v[44:45], v[12:13]
	v_pk_mul_f32 v[14:15], v[46:47], v[14:15]
	v_cvt_pk_bf16_f32 v12, v12, v13
	v_cvt_pk_bf16_f32 v13, v14, v15
	global_store_dwordx2 v[28:29], v[12:13], off offset:512
	v_pk_mul_f32 v[16:17], v[16:17], v[0:1] op_sel_hi:[1,0]
	v_pk_mul_f32 v[18:19], v[18:19], v[0:1] op_sel_hi:[1,0]
	v_pk_mul_f32 v[16:17], v[48:49], v[16:17]
	v_pk_mul_f32 v[18:19], v[50:51], v[18:19]
	v_cvt_pk_bf16_f32 v16, v16, v17
	v_cvt_pk_bf16_f32 v17, v18, v19
	global_store_dwordx2 v[28:29], v[16:17], off offset:1024
	v_pk_mul_f32 v[20:21], v[20:21], v[0:1] op_sel_hi:[1,0]
	v_pk_mul_f32 v[22:23], v[22:23], v[0:1] op_sel_hi:[1,0]
	v_pk_mul_f32 v[20:21], v[52:53], v[20:21]
	v_pk_mul_f32 v[22:23], v[54:55], v[22:23]
	v_cvt_pk_bf16_f32 v20, v20, v21
	v_cvt_pk_bf16_f32 v21, v22, v23
	global_store_dwordx2 v[28:29], v[20:21], off offset:1536
	s_lshl_b32 s80, s2, 1
	v_lshl_add_u64 v[72:73], v[4:5], 0, s[80:81]
	s_add_i32 s4, s4, s5
	s_add_i32 s0, s0, s1
	s_cmpk_lt_i32 s4, 0x4000
	s_cbranch_scc0 .Ln3_lastB
; DI unsigned cvtpk(float lo, float hi) { f32x2 v = {lo, hi}; bf16x2_t b = __builtin_convertvector(v, bf16x2_t); return __builtin_bit_cast(unsigned, b); }
; DI void norm_rows(const float* src, const float* gain, bf16_t* HN, int gw, int NGW, int lane) {
;     for (int mrow_ = gw; mrow_ < MTOK * REP_NORM; mrow_ += NGW) {
;         const int mrow = mrow_ & (MTOK - 1);
;         const f32x4* xr = (const f32x4*)(src + (size_t)mrow * DM) + lane;
;         f32x4 v[4]; float ss = 0.f;
; #pragma unroll
;         for (int j = 0; j < 4; ++j) { v[j] = xr[64 * j]; ss += (v[j].x * v[j].x + v[j].y * v[j].y) + (v[j].z * v[j].z + v[j].w * v[j].w); }
;         const float r = rsqrtf(wave_sum(ss) * (1.f / DM) + EPS);
;         u32x2* o8 = (u32x2*)(HN + (size_t)mrow * DM) + lane;
; #pragma unroll
;         for (int j = 0; j < 4; ++j) { const f32x4 gg = ((const f32x4*)gain)[lane + 64 * j]; u32x2 w; w.x = cvtpk(v[j].x * r * gg.x, v[j].y * r * gg.y); w.y = cvtpk(v[j].z * r * gg.z, v[j].w * r * gg.w); o8[64 * j] = w; }
;     }
	s_and_b32 s2, s0, 0xfffc00
	s_lshl_b32 s80, s2, 2
	v_lshl_add_u64 v[20:21], v[2:3], 0, s[80:81]
	global_load_dwordx4 v[8:11], v[20:21], off
	global_load_dwordx4 v[12:15], v[20:21], off offset:1024
	global_load_dwordx4 v[16:19], v[20:21], off offset:2048
	s_nop 0
	global_load_dwordx4 v[20:23], v[20:21], off offset:3072
	s_waitcnt vmcnt(4)
	v_mul_f32_e32 v0, v57, v57
	v_mul_f32_e32 v30, v59, v59
	v_mul_f32_e32 v31, v61, v61
	v_mul_f32_e32 v32, v63, v63
	v_mul_f32_e32 v33, v65, v65
	v_mul_f32_e32 v34, v67, v67
	v_fmac_f32_e32 v0, v56, v56
	v_fmac_f32_e32 v30, v58, v58
	v_fmac_f32_e32 v31, v60, v60
	v_fmac_f32_e32 v32, v62, v62
	v_mul_f32_e32 v35, v69, v69
	v_mul_f32_e32 v36, v71, v71
	v_fmac_f32_e32 v33, v64, v64
	v_fmac_f32_e32 v34, v66, v66
	v_add_f32_e32 v0, v0, v30
	v_add_f32_e32 v30, v31, v32
	v_fmac_f32_e32 v35, v68, v68
	v_fmac_f32_e32 v36, v70, v70
	v_add_f32_e32 v31, v33, v34
	v_add_f32_e32 v0, v0, v30
	v_add_f32_e32 v32, v35, v36
	v_add_f32_e32 v0, v0, v31
	v_add_f32_e32 v0, v0, v32
	ds_swizzle_b32 v30, v0 offset:swizzle(SWAP,1)
	s_waitcnt lgkmcnt(0)
	v_add_f32_e32 v0, v0, v30
	ds_swizzle_b32 v30, v0 offset:swizzle(SWAP,2)
	s_waitcnt lgkmcnt(0)
	v_add_f32_e32 v0, v0, v30
	ds_swizzle_b32 v30, v0 offset:swizzle(SWAP,4)
	s_waitcnt lgkmcnt(0)
	v_add_f32_e32 v0, v0, v30
	ds_swizzle_b32 v30, v0 offset:swizzle(SWAP,8)
	s_waitcnt lgkmcnt(0)
	v_add_f32_e32 v0, v0, v30
	ds_swizzle_b32 v30, v0 offset:swizzle(SWAP,16)
	s_waitcnt lgkmcnt(0)
	v_add_f32_e32 v0, v0, v30
	v_mov_b32_e32 v30, v0
	s_nop 1
	v_permlane32_swap_b32_e32 v0, v30
	v_add_f32_e32 v0, v0, v30
	v_fmamk_f32 v0, v0, 0x3a800000, v156
	v_mul_f32_e32 v30, 0x4b800000, v0
	v_cmp_gt_f32_e32 vcc, s12, v0
	s_nop 1
	v_cndmask_b32_e32 v0, v0, v30, vcc
	v_rsq_f32_e32 v0, v0
	s_nop 0
	v_mul_f32_e32 v30, 0x45800000, v0
	v_cndmask_b32_e32 v0, v0, v30, vcc
	v_pk_mul_f32 v[56:57], v[56:57], v[0:1] op_sel_hi:[1,0]
	v_pk_mul_f32 v[58:59], v[58:59], v[0:1] op_sel_hi:[1,0]
	v_pk_mul_f32 v[56:57], v[40:41], v[56:57]
	v_pk_mul_f32 v[58:59], v[42:43], v[58:59]
	v_cvt_pk_bf16_f32 v56, v56, v57
	v_cvt_pk_bf16_f32 v57, v58, v59
	global_store_dwordx2 v[72:73], v[56:57], off
	v_pk_mul_f32 v[60:61], v[60:61], v[0:1] op_sel_hi:[1,0]
	v_pk_mul_f32 v[62:63], v[62:63], v[0:1] op_sel_hi:[1,0]
	v_pk_mul_f32 v[60:61], v[44:45], v[60:61]
	v_pk_mul_f32 v[62:63], v[46:47], v[62:63]
	v_cvt_pk_bf16_f32 v60, v60, v61
	v_cvt_pk_bf16_f32 v61, v62, v63
	global_store_dwordx2 v[72:73], v[60:61], off offset:512
	v_pk_mul_f32 v[64:65], v[64:65], v[0:1] op_sel_hi:[1,0]
	v_pk_mul_f32 v[66:67], v[66:67], v[0:1] op_sel_hi:[1,0]
	v_pk_mul_f32 v[64:65], v[48:49], v[64:65]
	v_pk_mul_f32 v[66:67], v[50:51], v[66:67]
	v_cvt_pk_bf16_f32 v64, v64, v65
	v_cvt_pk_bf16_f32 v65, v66, v67
	global_store_dwordx2 v[72:73], v[64:65], off offset:1024
	v_pk_mul_f32 v[68:69], v[68:69], v[0:1] op_sel_hi:[1,0]
	v_pk_mul_f32 v[70:71], v[70:71], v[0:1] op_sel_hi:[1,0]
	v_pk_mul_f32 v[68:69], v[52:53], v[68:69]
	v_pk_mul_f32 v[70:71], v[54:55], v[70:71]
	v_cvt_pk_bf16_f32 v68, v68, v69
	v_cvt_pk_bf16_f32 v69, v70, v71
	global_store_dwordx2 v[72:73], v[68:69], off offset:1536
	s_branch .Ln3_top
.Ln3_lastA:
	s_waitcnt vmcnt(0)
	v_mul_f32_e32 v0, v9, v9
	v_mul_f32_e32 v30, v11, v11
	v_mul_f32_e32 v31, v13, v13
	v_mul_f32_e32 v32, v15, v15
	v_mul_f32_e32 v33, v17, v17
	v_mul_f32_e32 v34, v19, v19
	v_fmac_f32_e32 v0, v8, v8
	v_fmac_f32_e32 v30, v10, v10
	v_fmac_f32_e32 v31, v12, v12
	v_fmac_f32_e32 v32, v14, v14
	v_mul_f32_e32 v35, v21, v21
	v_mul_f32_e32 v36, v23, v23
	v_fmac_f32_e32 v33, v16, v16
	v_fmac_f32_e32 v34, v18, v18
	v_add_f32_e32 v0, v0, v30
	v_add_f32_e32 v30, v31, v32
	v_fmac_f32_e32 v35, v20, v20
	v_fmac_f32_e32 v36, v22, v22
	v_add_f32_e32 v31, v33, v34
	v_add_f32_e32 v0, v0, v30
	v_add_f32_e32 v32, v35, v36
	v_add_f32_e32 v0, v0, v31
	v_add_f32_e32 v0, v0, v32
	ds_swizzle_b32 v30, v0 offset:swizzle(SWAP,1)
	s_waitcnt lgkmcnt(0)
	v_add_f32_e32 v0, v0, v30
	ds_swizzle_b32 v30, v0 offset:swizzle(SWAP,2)
	s_waitcnt lgkmcnt(0)
	v_add_f32_e32 v0, v0, v30
	ds_swizzle_b32 v30, v0 offset:swizzle(SWAP,4)
	s_waitcnt lgkmcnt(0)
	v_add_f32_e32 v0, v0, v30
	ds_swizzle_b32 v30, v0 offset:swizzle(SWAP,8)
	s_waitcnt lgkmcnt(0)
	v_add_f32_e32 v0, v0, v30
	ds_swizzle_b32 v30, v0 offset:swizzle(SWAP,16)
	s_waitcnt lgkmcnt(0)
	v_add_f32_e32 v0, v0, v30
	v_mov_b32_e32 v30, v0
	s_nop 1
	v_permlane32_swap_b32_e32 v0, v30
	v_add_f32_e32 v0, v0, v30
	v_fmamk_f32 v0, v0, 0x3a800000, v156
	v_mul_f32_e32 v30, 0x4b800000, v0
	v_cmp_gt_f32_e32 vcc, s12, v0
	s_nop 1
	v_cndmask_b32_e32 v0, v0, v30, vcc
	v_rsq_f32_e32 v0, v0
	s_nop 0
	v_mul_f32_e32 v30, 0x45800000, v0
	v_cndmask_b32_e32 v0, v0, v30, vcc
	v_pk_mul_f32 v[8:9], v[8:9], v[0:1] op_sel_hi:[1,0]
	v_pk_mul_f32 v[10:11], v[10:11], v[0:1] op_sel_hi:[1,0]
	v_pk_mul_f32 v[8:9], v[40:41], v[8:9]
	v_pk_mul_f32 v[10:11], v[42:43], v[10:11]
	v_cvt_pk_bf16_f32 v8, v8, v9
	v_cvt_pk_bf16_f32 v9, v10, v11
	global_store_dwordx2 v[28:29], v[8:9], off
	v_pk_mul_f32 v[12:13], v[12:13], v[0:1] op_sel_hi:[1,0]
	v_pk_mul_f32 v[14:15], v[14:15], v[0:1] op_sel_hi:[1,0]
	v_pk_mul_f32 v[12:13], v[44:45], v[12:13]
	v_pk_mul_f32 v[14:15], v[46:47], v[14:15]
	v_cvt_pk_bf16_f32 v12, v12, v13
	v_cvt_pk_bf16_f32 v13, v14, v15
	global_store_dwordx2 v[28:29], v[12:13], off offset:512
	v_pk_mul_f32 v[16:17], v[16:17], v[0:1] op_sel_hi:[1,0]
	v_pk_mul_f32 v[18:19], v[18:19], v[0:1] op_sel_hi:[1,0]
	v_pk_mul_f32 v[16:17], v[48:49], v[16:17]
	v_pk_mul_f32 v[18:19], v[50:51], v[18:19]
	v_cvt_pk_bf16_f32 v16, v16, v17
	v_cvt_pk_bf16_f32 v17, v18, v19
	global_store_dwordx2 v[28:29], v[16:17], off offset:1024
	v_pk_mul_f32 v[20:21], v[20:21], v[0:1] op_sel_hi:[1,0]
	v_pk_mul_f32 v[22:23], v[22:23], v[0:1] op_sel_hi:[1,0]
	v_pk_mul_f32 v[20:21], v[52:53], v[20:21]
	v_pk_mul_f32 v[22:23], v[54:55], v[22:23]
	v_cvt_pk_bf16_f32 v20, v20, v21
	v_cvt_pk_bf16_f32 v21, v22, v23
	global_store_dwordx2 v[28:29], v[20:21], off offset:1536
	s_branch .Ln3_done
; DI unsigned cvtpk(float lo, float hi) { f32x2 v = {lo, hi}; bf16x2_t b = __builtin_convertvector(v, bf16x2_t); return __builtin_bit_cast(unsigned, b); }
; DI void xcd_barrier(const XcdBarrier& b) {
;     asm volatile("s_waitcnt vmcnt(0)" ::: "memory");
;     __syncthreads();
;     if (threadIdx.x == 0) {
;         unsigned* bar = b.bar;
;         __builtin_amdgcn_s_waitcnt(0);
;         unsigned nloc = b.st[0], nx = b.st[1];
;         if (nloc == 0u) { xcd_barrier_complete(bar, b.x, nloc, nx); b.st[0] = nloc; b.st[1] = nx; }
; DI void norm_rows(const float* src, const float* gain, bf16_t* HN, int gw, int NGW, int lane) {
;     for (int mrow_ = gw; mrow_ < MTOK * REP_NORM; mrow_ += NGW) {
;         const int mrow = mrow_ & (MTOK - 1);
;         const f32x4* xr = (const f32x4*)(src + (size_t)mrow * DM) + lane;
;         f32x4 v[4]; float ss = 0.f;
; #pragma unroll
;         for (int j = 0; j < 4; ++j) { v[j] = xr[64 * j]; ss += (v[j].x * v[j].x + v[j].y * v[j].y) + (v[j].z * v[j].z + v[j].w * v[j].w); }
;         const float r = rsqrtf(wave_sum(ss) * (1.f / DM) + EPS);
;         u32x2* o8 = (u32x2*)(HN + (size_t)mrow * DM) + lane;
; #pragma unroll
;         for (int j = 0; j < 4; ++j) { const f32x4 gg = ((const f32x4*)gain)[lane + 64 * j]; u32x2 w; w.x = cvtpk(v[j].x * r * gg.x, v[j].y * r * gg.y); w.y = cvtpk(v[j].z * r * gg.z, v[j].w * r * gg.w); o8[64 * j] = w; }
;     }
.Ln3_lastB:
	s_waitcnt vmcnt(0)
	v_mul_f32_e32 v0, v57, v57
	v_mul_f32_e32 v30, v59, v59
	v_mul_f32_e32 v31, v61, v61
	v_mul_f32_e32 v32, v63, v63
	v_mul_f32_e32 v33, v65, v65
	v_mul_f32_e32 v34, v67, v67
	v_fmac_f32_e32 v0, v56, v56
	v_fmac_f32_e32 v30, v58, v58
	v_fmac_f32_e32 v31, v60, v60
	v_fmac_f32_e32 v32, v62, v62
	v_mul_f32_e32 v35, v69, v69
	v_mul_f32_e32 v36, v71, v71
	v_fmac_f32_e32 v33, v64, v64
	v_fmac_f32_e32 v34, v66, v66
	v_add_f32_e32 v0, v0, v30
	v_add_f32_e32 v30, v31, v32
	v_fmac_f32_e32 v35, v68, v68
	v_fmac_f32_e32 v36, v70, v70
	v_add_f32_e32 v31, v33, v34
	v_add_f32_e32 v0, v0, v30
	v_add_f32_e32 v32, v35, v36
	v_add_f32_e32 v0, v0, v31
	v_add_f32_e32 v0, v0, v32
	ds_swizzle_b32 v30, v0 offset:swizzle(SWAP,1)
	s_waitcnt lgkmcnt(0)
	v_add_f32_e32 v0, v0, v30
	ds_swizzle_b32 v30, v0 offset:swizzle(SWAP,2)
	s_waitcnt lgkmcnt(0)
	v_add_f32_e32 v0, v0, v30
	ds_swizzle_b32 v30, v0 offset:swizzle(SWAP,4)
	s_waitcnt lgkmcnt(0)
	v_add_f32_e32 v0, v0, v30
	ds_swizzle_b32 v30, v0 offset:swizzle(SWAP,8)
	s_waitcnt lgkmcnt(0)
	v_add_f32_e32 v0, v0, v30
	ds_swizzle_b32 v30, v0 offset:swizzle(SWAP,16)
	s_waitcnt lgkmcnt(0)
	v_add_f32_e32 v0, v0, v30
	v_mov_b32_e32 v30, v0
	s_nop 1
	v_permlane32_swap_b32_e32 v0, v30
	v_add_f32_e32 v0, v0, v30
	v_fmamk_f32 v0, v0, 0x3a800000, v156
	v_mul_f32_e32 v30, 0x4b800000, v0
	v_cmp_gt_f32_e32 vcc, s12, v0
	s_nop 1
	v_cndmask_b32_e32 v0, v0, v30, vcc
	v_rsq_f32_e32 v0, v0
	s_nop 0
	v_mul_f32_e32 v30, 0x45800000, v0
	v_cndmask_b32_e32 v0, v0, v30, vcc
	v_pk_mul_f32 v[56:57], v[56:57], v[0:1] op_sel_hi:[1,0]
	v_pk_mul_f32 v[58:59], v[58:59], v[0:1] op_sel_hi:[1,0]
	v_pk_mul_f32 v[56:57], v[40:41], v[56:57]
	v_pk_mul_f32 v[58:59], v[42:43], v[58:59]
	v_cvt_pk_bf16_f32 v56, v56, v57
	v_cvt_pk_bf16_f32 v57, v58, v59
	global_store_dwordx2 v[72:73], v[56:57], off
	v_pk_mul_f32 v[60:61], v[60:61], v[0:1] op_sel_hi:[1,0]
	v_pk_mul_f32 v[62:63], v[62:63], v[0:1] op_sel_hi:[1,0]
	v_pk_mul_f32 v[60:61], v[44:45], v[60:61]
	v_pk_mul_f32 v[62:63], v[46:47], v[62:63]
	v_cvt_pk_bf16_f32 v60, v60, v61
	v_cvt_pk_bf16_f32 v61, v62, v63
	global_store_dwordx2 v[72:73], v[60:61], off offset:512
	v_pk_mul_f32 v[64:65], v[64:65], v[0:1] op_sel_hi:[1,0]
	v_pk_mul_f32 v[66:67], v[66:67], v[0:1] op_sel_hi:[1,0]
	v_pk_mul_f32 v[64:65], v[48:49], v[64:65]
	v_pk_mul_f32 v[66:67], v[50:51], v[66:67]
	v_cvt_pk_bf16_f32 v64, v64, v65
	v_cvt_pk_bf16_f32 v65, v66, v67
	global_store_dwordx2 v[72:73], v[64:65], off offset:1024
	v_pk_mul_f32 v[68:69], v[68:69], v[0:1] op_sel_hi:[1,0]
	v_pk_mul_f32 v[70:71], v[70:71], v[0:1] op_sel_hi:[1,0]
	v_pk_mul_f32 v[68:69], v[52:53], v[68:69]
	v_pk_mul_f32 v[70:71], v[54:55], v[70:71]
	v_cvt_pk_bf16_f32 v68, v68, v69
	v_cvt_pk_bf16_f32 v69, v70, v71
	global_store_dwordx2 v[72:73], v[68:69], off offset:1536
.Ln3_done:
.LBB0_1510:
	s_mov_b32 s60, s81
	s_add_i32 s0, s60, 0x20040
	v_mov_b32_e32 v0, s0
	ds_read_b32 v2, v0 offset:200
	ds_read_b32 v0, v0 offset:204
	s_getreg_b32 s2, hwreg(HW_REG_XCC_ID, 0, 4)
	s_waitcnt vmcnt(0)
	s_waitcnt lgkmcnt(0)
	v_readfirstlane_b32 s56, v2
	v_readfirstlane_b32 s57, v0
	s_barrier
	s_mov_b64 s[0:1], exec
	v_readlane_b32 s4, v254, 9
	v_readlane_b32 s5, v254, 10
	s_and_b64 s[4:5], s[0:1], s[4:5]
	s_mov_b64 exec, s[4:5]
	s_cbranch_execz .LBB0_1554
	s_add_i32 s59, s60, 0x20020
	v_mov_b32_e32 v0, s59
	s_waitcnt vmcnt(0) expcnt(0) lgkmcnt(0)
	ds_read_b32 v2, v0
	s_add_i32 s60, s60, 0x20024
	v_mov_b32_e32 v0, s60
	ds_read_b32 v0, v0
	s_and_b32 s58, s2, 15
	s_waitcnt lgkmcnt(1)
	v_cmp_ne_u32_e32 vcc, 0, v2
	s_cbranch_vccnz .LBB0_1525
	s_add_u32 s2, s56, 0x4200
	s_addc_u32 s3, s57, 0
	s_add_u32 s4, s56, 0x4400
	s_addc_u32 s5, s57, 0
	s_add_u32 s6, s56, 0x4500
	s_addc_u32 s7, s57, 0
	s_add_u32 s8, s56, 0x4600
	s_addc_u32 s9, s57, 0
	s_add_u32 s10, s56, 0x4700
	s_addc_u32 s11, s57, 0
	s_add_u32 s12, s56, 0x4800
	s_addc_u32 s13, s57, 0
	s_add_u32 s14, s56, 0x4900
	s_addc_u32 s15, s57, 0
	s_add_u32 s16, s56, 0x4a00
	s_addc_u32 s17, s57, 0
	s_add_u32 s18, s56, 0x4b00
	s_addc_u32 s19, s57, 0
	s_add_u32 s20, s56, 0x4c00
	s_addc_u32 s21, s57, 0
	s_add_u32 s22, s56, 0x4d00
	s_addc_u32 s23, s57, 0
	s_add_u32 s24, s56, 0x4e00
	s_addc_u32 s25, s57, 0
	s_add_u32 s26, s56, 0x4f00
	s_addc_u32 s27, s57, 0
	s_add_u32 s28, s56, 0x5000
	s_addc_u32 s29, s57, 0
	s_add_u32 s30, s56, 0x5100
	s_addc_u32 s31, s57, 0
	s_add_u32 s34, s56, 0x5200
	s_addc_u32 s35, s57, 0
	s_add_u32 s36, s56, 0x5300
	s_addc_u32 s37, s57, 0
	s_mov_b32 s61, 1
	s_mov_b64 s[38:39], 0
	s_branch .LBB0_1515

; __global__ void __launch_bounds__(512) mega_fwd(Params P) {
;     ...
;     for (int mrow = gw; mrow < MTOK; mrow += NGW) {
;         f32x4* xr = (f32x4*)(X + (size_t)mrow * DM) + lane;
;         f32x4 v[4]; float ss = 0.f;
; #pragma unroll
;         for (int j = 0; j < 4; ++j) { v[j] = xr[64 * j]; ss += (v[j].x * v[j].x + v[j].y * v[j].y) + (v[j].z * v[j].z + v[j].w * v[j].w); }
;         const float r = rsqrtf(wave_sum(ss) * (1.f / DM) + EPS);
; #pragma unroll
;         for (int j = 0; j < 4; ++j) { const f32x4 gg = ((const f32x4*)fng)[lane + 64 * j]; xr[64 * j] = v[j] * r * gg; }
.LBB0_1681:
	s_mov_b32 s1, 0
	s_add_i32 s1, s1, 0x20040
	v_mov_b32_e32 v0, s1
	s_mov_b32 s0, 0
	ds_read_b32 v1, v0 offset:192
	ds_read_b32 v0, v0 offset:196
	s_add_i32 s0, s0, 0x20040
	v_mov_b32_e32 v2, s0
	ds_read_b32 v3, v2 offset:184
	ds_read_b32 v2, v2 offset:188
	s_lshl_b32 s0, s65, 3
	s_add_i32 s0, s0, s61
	s_waitcnt lgkmcnt(0)
	v_readfirstlane_b32 s3, v1
	v_readfirstlane_b32 s6, v0
	v_readfirstlane_b32 s4, v3
	v_readfirstlane_b32 s5, v2
	v_mov_b32_e32 v3, 0
	v_mov_b32_e32 v0, 0
	s_cmpk_gt_i32 s0, 0x3fff
	s_cbranch_scc1 .LBB0_1684
	v_mbcnt_lo_u32_b32 v0, -1, v0
	v_mbcnt_hi_u32_b32 v0, -1, v0
	v_and_b32_e32 v0, 63, v0
	v_lshlrev_b32_e32 v2, 4, v0
	s_ashr_i32 s1, s0, 31
	s_lshl_b32 s2, s82, 3
	v_lshl_add_u64 v[0:1], s[4:5], 0, v[2:3]
	s_lshl_b64 s[4:5], s[0:1], 12
	s_add_u32 s4, s3, s4
	s_addc_u32 s5, s6, s5
	s_ashr_i32 s3, s2, 31
	v_lshl_add_u64 v[2:3], s[4:5], 0, v[2:3]
	s_lshl_b64 s[4:5], s[2:3], 12
	v_mov_b32_e32 v4, 0x358637bd
	s_mov_b32 s1, 0x800000
	global_load_dwordx4 v[40:43], v[0:1], off
	global_load_dwordx4 v[44:47], v[0:1], off offset:1024
	global_load_dwordx4 v[48:51], v[0:1], off offset:2048
	global_load_dwordx4 v[52:55], v[0:1], off offset:3072
.LBB0_1683:
	global_load_dwordx4 v[6:9], v[2:3], off
	global_load_dwordx4 v[10:13], v[2:3], off offset:1024
	global_load_dwordx4 v[14:17], v[2:3], off offset:2048
	global_load_dwordx4 v[18:21], v[2:3], off offset:3072
.Lfn_top:
	s_add_i32 s0, s0, s2
	s_cmpk_gt_i32 s0, 0x3fff
	s_cbranch_scc1 .Lfn_lastA
	v_lshl_add_u64 v[72:73], v[2:3], 0, s[4:5]
	global_load_dwordx4 v[56:59], v[72:73], off
	global_load_dwordx4 v[60:63], v[72:73], off offset:1024
	global_load_dwordx4 v[64:67], v[72:73], off offset:2048
	global_load_dwordx4 v[68:71], v[72:73], off offset:3072
	s_waitcnt vmcnt(4)
	v_mul_f32_e32 v5, v7, v7
	v_mul_f32_e32 v26, v9, v9
	v_mul_f32_e32 v27, v11, v11
	v_mul_f32_e32 v28, v13, v13
	v_mul_f32_e32 v29, v15, v15
	v_mul_f32_e32 v30, v17, v17
	v_fmac_f32_e32 v5, v6, v6
	v_fmac_f32_e32 v26, v8, v8
	v_fmac_f32_e32 v27, v10, v10
	v_fmac_f32_e32 v28, v12, v12
	v_mul_f32_e32 v31, v19, v19
	v_mul_f32_e32 v32, v21, v21
	v_fmac_f32_e32 v29, v14, v14
	v_fmac_f32_e32 v30, v16, v16
	v_add_f32_e32 v5, v5, v26
	v_add_f32_e32 v26, v27, v28
	v_fmac_f32_e32 v31, v18, v18
	v_fmac_f32_e32 v32, v20, v20
	v_add_f32_e32 v27, v29, v30
	v_add_f32_e32 v5, v5, v26
	v_add_f32_e32 v28, v31, v32
	v_add_f32_e32 v5, v5, v27
	v_add_f32_e32 v5, v5, v28
	ds_swizzle_b32 v26, v5 offset:swizzle(SWAP,1)
	s_waitcnt lgkmcnt(0)
	v_add_f32_e32 v5, v5, v26
	ds_swizzle_b32 v26, v5 offset:swizzle(SWAP,2)
	s_waitcnt lgkmcnt(0)
	v_add_f32_e32 v5, v5, v26
	ds_swizzle_b32 v26, v5 offset:swizzle(SWAP,4)
	s_waitcnt lgkmcnt(0)
	v_add_f32_e32 v5, v5, v26
	ds_swizzle_b32 v26, v5 offset:swizzle(SWAP,8)
	s_waitcnt lgkmcnt(0)
	v_add_f32_e32 v5, v5, v26
	ds_swizzle_b32 v26, v5 offset:swizzle(SWAP,16)
	s_waitcnt lgkmcnt(0)
	v_add_f32_e32 v5, v5, v26
	v_mov_b32_e32 v26, v5
	s_nop 1
	v_permlane32_swap_b32_e32 v5, v26
	v_add_f32_e32 v5, v5, v26
	v_fmamk_f32 v5, v5, 0x3a800000, v4
	v_mul_f32_e32 v26, 0x4b800000, v5
	v_cmp_gt_f32_e32 vcc, s1, v5
	s_nop 1
	v_cndmask_b32_e32 v5, v5, v26, vcc
	v_rsq_f32_e32 v5, v5
	s_nop 0
	v_mul_f32_e32 v26, 0x45800000, v5
	v_cndmask_b32_e32 v26, v5, v26, vcc
	v_pk_mul_f32 v[6:7], v[26:27], v[6:7] op_sel_hi:[0,1]
	v_pk_mul_f32 v[8:9], v[26:27], v[8:9] op_sel_hi:[0,1]
	v_pk_mul_f32 v[8:9], v[42:43], v[8:9]
	v_pk_mul_f32 v[6:7], v[40:41], v[6:7]
	global_store_dwordx4 v[2:3], v[6:9], off
	v_pk_mul_f32 v[12:13], v[26:27], v[12:13] op_sel_hi:[0,1]
	v_pk_mul_f32 v[10:11], v[26:27], v[10:11] op_sel_hi:[0,1]
	v_pk_mul_f32 v[10:11], v[44:45], v[10:11]
	v_pk_mul_f32 v[12:13], v[46:47], v[12:13]
	global_store_dwordx4 v[2:3], v[10:13], off offset:1024
	v_pk_mul_f32 v[16:17], v[26:27], v[16:17] op_sel_hi:[0,1]
	v_pk_mul_f32 v[14:15], v[26:27], v[14:15] op_sel_hi:[0,1]
	v_pk_mul_f32 v[14:15], v[48:49], v[14:15]
	v_pk_mul_f32 v[16:17], v[50:51], v[16:17]
	global_store_dwordx4 v[2:3], v[14:17], off offset:2048
	v_pk_mul_f32 v[20:21], v[26:27], v[20:21] op_sel_hi:[0,1]
	v_pk_mul_f32 v[18:19], v[26:27], v[18:19] op_sel_hi:[0,1]
	v_pk_mul_f32 v[18:19], v[52:53], v[18:19]
	v_pk_mul_f32 v[20:21], v[54:55], v[20:21]
	global_store_dwordx4 v[2:3], v[18:21], off offset:3072
	s_add_i32 s0, s0, s2
	s_cmpk_gt_i32 s0, 0x3fff
	s_cbranch_scc1 .Lfn_lastB
; __global__ void __launch_bounds__(512) mega_fwd(Params P) {
;     ...
;     for (int mrow = gw; mrow < MTOK; mrow += NGW) {
;         f32x4* xr = (f32x4*)(X + (size_t)mrow * DM) + lane;
;         f32x4 v[4]; float ss = 0.f;
; #pragma unroll
;         for (int j = 0; j < 4; ++j) { v[j] = xr[64 * j]; ss += (v[j].x * v[j].x + v[j].y * v[j].y) + (v[j].z * v[j].z + v[j].w * v[j].w); }
;         const float r = rsqrtf(wave_sum(ss) * (1.f / DM) + EPS);
; #pragma unroll
;         for (int j = 0; j < 4; ++j) { const f32x4 gg = ((const f32x4*)fng)[lane + 64 * j]; xr[64 * j] = v[j] * r * gg; }
	v_lshl_add_u64 v[2:3], v[72:73], 0, s[4:5]
	global_load_dwordx4 v[6:9], v[2:3], off
	global_load_dwordx4 v[10:13], v[2:3], off offset:1024
	global_load_dwordx4 v[14:17], v[2:3], off offset:2048
	global_load_dwordx4 v[18:21], v[2:3], off offset:3072
	s_waitcnt vmcnt(4)
	v_mul_f32_e32 v5, v57, v57
	v_mul_f32_e32 v26, v59, v59
	v_mul_f32_e32 v27, v61, v61
	v_mul_f32_e32 v28, v63, v63
	v_mul_f32_e32 v29, v65, v65
	v_mul_f32_e32 v30, v67, v67
	v_fmac_f32_e32 v5, v56, v56
	v_fmac_f32_e32 v26, v58, v58
	v_fmac_f32_e32 v27, v60, v60
	v_fmac_f32_e32 v28, v62, v62
	v_mul_f32_e32 v31, v69, v69
	v_mul_f32_e32 v32, v71, v71
	v_fmac_f32_e32 v29, v64, v64
	v_fmac_f32_e32 v30, v66, v66
	v_add_f32_e32 v5, v5, v26
	v_add_f32_e32 v26, v27, v28
	v_fmac_f32_e32 v31, v68, v68
	v_fmac_f32_e32 v32, v70, v70
	v_add_f32_e32 v27, v29, v30
	v_add_f32_e32 v5, v5, v26
	v_add_f32_e32 v28, v31, v32
	v_add_f32_e32 v5, v5, v27
	v_add_f32_e32 v5, v5, v28
	ds_swizzle_b32 v26, v5 offset:swizzle(SWAP,1)
	s_waitcnt lgkmcnt(0)
	v_add_f32_e32 v5, v5, v26
	ds_swizzle_b32 v26, v5 offset:swizzle(SWAP,2)
	s_waitcnt lgkmcnt(0)
	v_add_f32_e32 v5, v5, v26
	ds_swizzle_b32 v26, v5 offset:swizzle(SWAP,4)
	s_waitcnt lgkmcnt(0)
	v_add_f32_e32 v5, v5, v26
	ds_swizzle_b32 v26, v5 offset:swizzle(SWAP,8)
	s_waitcnt lgkmcnt(0)
	v_add_f32_e32 v5, v5, v26
	ds_swizzle_b32 v26, v5 offset:swizzle(SWAP,16)
	s_waitcnt lgkmcnt(0)
	v_add_f32_e32 v5, v5, v26
	v_mov_b32_e32 v26, v5
	s_nop 1
	v_permlane32_swap_b32_e32 v5, v26
	v_add_f32_e32 v5, v5, v26
	v_fmamk_f32 v5, v5, 0x3a800000, v4
	v_mul_f32_e32 v26, 0x4b800000, v5
	v_cmp_gt_f32_e32 vcc, s1, v5
	s_nop 1
	v_cndmask_b32_e32 v5, v5, v26, vcc
	v_rsq_f32_e32 v5, v5
	s_nop 0
	v_mul_f32_e32 v26, 0x45800000, v5
	v_cndmask_b32_e32 v26, v5, v26, vcc
	v_pk_mul_f32 v[56:57], v[26:27], v[56:57] op_sel_hi:[0,1]
	v_pk_mul_f32 v[58:59], v[26:27], v[58:59] op_sel_hi:[0,1]
	v_pk_mul_f32 v[58:59], v[42:43], v[58:59]
	v_pk_mul_f32 v[56:57], v[40:41], v[56:57]
	global_store_dwordx4 v[72:73], v[56:59], off
	v_pk_mul_f32 v[62:63], v[26:27], v[62:63] op_sel_hi:[0,1]
	v_pk_mul_f32 v[60:61], v[26:27], v[60:61] op_sel_hi:[0,1]
	v_pk_mul_f32 v[60:61], v[44:45], v[60:61]
	v_pk_mul_f32 v[62:63], v[46:47], v[62:63]
	global_store_dwordx4 v[72:73], v[60:63], off offset:1024
	v_pk_mul_f32 v[66:67], v[26:27], v[66:67] op_sel_hi:[0,1]
	v_pk_mul_f32 v[64:65], v[26:27], v[64:65] op_sel_hi:[0,1]
	v_pk_mul_f32 v[64:65], v[48:49], v[64:65]
	v_pk_mul_f32 v[66:67], v[50:51], v[66:67]
	global_store_dwordx4 v[72:73], v[64:67], off offset:2048
	v_pk_mul_f32 v[70:71], v[26:27], v[70:71] op_sel_hi:[0,1]
	v_pk_mul_f32 v[68:69], v[26:27], v[68:69] op_sel_hi:[0,1]
	v_pk_mul_f32 v[68:69], v[52:53], v[68:69]
	v_pk_mul_f32 v[70:71], v[54:55], v[70:71]
	global_store_dwordx4 v[72:73], v[68:71], off offset:3072
	s_branch .Lfn_top
; __global__ void __launch_bounds__(512) mega_fwd(Params P) {
;     ...
;     for (int mrow = gw; mrow < MTOK; mrow += NGW) {
;         f32x4* xr = (f32x4*)(X + (size_t)mrow * DM) + lane;
;         f32x4 v[4]; float ss = 0.f;
; #pragma unroll
;         for (int j = 0; j < 4; ++j) { v[j] = xr[64 * j]; ss += (v[j].x * v[j].x + v[j].y * v[j].y) + (v[j].z * v[j].z + v[j].w * v[j].w); }
;         const float r = rsqrtf(wave_sum(ss) * (1.f / DM) + EPS);
; #pragma unroll
;         for (int j = 0; j < 4; ++j) { const f32x4 gg = ((const f32x4*)fng)[lane + 64 * j]; xr[64 * j] = v[j] * r * gg; }
.Lfn_lastA:
	s_waitcnt vmcnt(0)
	v_mul_f32_e32 v5, v7, v7
	v_mul_f32_e32 v26, v9, v9
	v_mul_f32_e32 v27, v11, v11
	v_mul_f32_e32 v28, v13, v13
	v_mul_f32_e32 v29, v15, v15
	v_mul_f32_e32 v30, v17, v17
	v_fmac_f32_e32 v5, v6, v6
	v_fmac_f32_e32 v26, v8, v8
	v_fmac_f32_e32 v27, v10, v10
	v_fmac_f32_e32 v28, v12, v12
	v_mul_f32_e32 v31, v19, v19
	v_mul_f32_e32 v32, v21, v21
	v_fmac_f32_e32 v29, v14, v14
	v_fmac_f32_e32 v30, v16, v16
	v_add_f32_e32 v5, v5, v26
	v_add_f32_e32 v26, v27, v28
	v_fmac_f32_e32 v31, v18, v18
	v_fmac_f32_e32 v32, v20, v20
	v_add_f32_e32 v27, v29, v30
	v_add_f32_e32 v5, v5, v26
	v_add_f32_e32 v28, v31, v32
	v_add_f32_e32 v5, v5, v27
	v_add_f32_e32 v5, v5, v28
	ds_swizzle_b32 v26, v5 offset:swizzle(SWAP,1)
	s_waitcnt lgkmcnt(0)
	v_add_f32_e32 v5, v5, v26
	ds_swizzle_b32 v26, v5 offset:swizzle(SWAP,2)
	s_waitcnt lgkmcnt(0)
	v_add_f32_e32 v5, v5, v26
	ds_swizzle_b32 v26, v5 offset:swizzle(SWAP,4)
	s_waitcnt lgkmcnt(0)
	v_add_f32_e32 v5, v5, v26
	ds_swizzle_b32 v26, v5 offset:swizzle(SWAP,8)
	s_waitcnt lgkmcnt(0)
	v_add_f32_e32 v5, v5, v26
	ds_swizzle_b32 v26, v5 offset:swizzle(SWAP,16)
	s_waitcnt lgkmcnt(0)
	v_add_f32_e32 v5, v5, v26
	v_mov_b32_e32 v26, v5
	s_nop 1
	v_permlane32_swap_b32_e32 v5, v26
	v_add_f32_e32 v5, v5, v26
	v_fmamk_f32 v5, v5, 0x3a800000, v4
	v_mul_f32_e32 v26, 0x4b800000, v5
	v_cmp_gt_f32_e32 vcc, s1, v5
	s_nop 1
	v_cndmask_b32_e32 v5, v5, v26, vcc
	v_rsq_f32_e32 v5, v5
	s_nop 0
	v_mul_f32_e32 v26, 0x45800000, v5
	v_cndmask_b32_e32 v26, v5, v26, vcc
	v_pk_mul_f32 v[6:7], v[26:27], v[6:7] op_sel_hi:[0,1]
	v_pk_mul_f32 v[8:9], v[26:27], v[8:9] op_sel_hi:[0,1]
	v_pk_mul_f32 v[8:9], v[42:43], v[8:9]
	v_pk_mul_f32 v[6:7], v[40:41], v[6:7]
	global_store_dwordx4 v[2:3], v[6:9], off
	v_pk_mul_f32 v[12:13], v[26:27], v[12:13] op_sel_hi:[0,1]
	v_pk_mul_f32 v[10:11], v[26:27], v[10:11] op_sel_hi:[0,1]
	v_pk_mul_f32 v[10:11], v[44:45], v[10:11]
	v_pk_mul_f32 v[12:13], v[46:47], v[12:13]
	global_store_dwordx4 v[2:3], v[10:13], off offset:1024
	v_pk_mul_f32 v[16:17], v[26:27], v[16:17] op_sel_hi:[0,1]
	v_pk_mul_f32 v[14:15], v[26:27], v[14:15] op_sel_hi:[0,1]
	v_pk_mul_f32 v[14:15], v[48:49], v[14:15]
	v_pk_mul_f32 v[16:17], v[50:51], v[16:17]
	global_store_dwordx4 v[2:3], v[14:17], off offset:2048
	v_pk_mul_f32 v[20:21], v[26:27], v[20:21] op_sel_hi:[0,1]
	v_pk_mul_f32 v[18:19], v[26:27], v[18:19] op_sel_hi:[0,1]
	v_pk_mul_f32 v[18:19], v[52:53], v[18:19]
	v_pk_mul_f32 v[20:21], v[54:55], v[20:21]
	global_store_dwordx4 v[2:3], v[18:21], off offset:3072
	s_branch .Lfn_done
.Lfn_lastB:
	s_waitcnt vmcnt(0)
	v_mul_f32_e32 v5, v57, v57
	v_mul_f32_e32 v26, v59, v59
	v_mul_f32_e32 v27, v61, v61
	v_mul_f32_e32 v28, v63, v63
	v_mul_f32_e32 v29, v65, v65
	v_mul_f32_e32 v30, v67, v67
	v_fmac_f32_e32 v5, v56, v56
	v_fmac_f32_e32 v26, v58, v58
	v_fmac_f32_e32 v27, v60, v60
	v_fmac_f32_e32 v28, v62, v62
	v_mul_f32_e32 v31, v69, v69
	v_mul_f32_e32 v32, v71, v71
	v_fmac_f32_e32 v29, v64, v64
	v_fmac_f32_e32 v30, v66, v66
	v_add_f32_e32 v5, v5, v26
	v_add_f32_e32 v26, v27, v28
	v_fmac_f32_e32 v31, v68, v68
	v_fmac_f32_e32 v32, v70, v70
	v_add_f32_e32 v27, v29, v30
	v_add_f32_e32 v5, v5, v26
	v_add_f32_e32 v28, v31, v32
	v_add_f32_e32 v5, v5, v27
	v_add_f32_e32 v5, v5, v28
	ds_swizzle_b32 v26, v5 offset:swizzle(SWAP,1)
	s_waitcnt lgkmcnt(0)
	v_add_f32_e32 v5, v5, v26
	ds_swizzle_b32 v26, v5 offset:swizzle(SWAP,2)
	s_waitcnt lgkmcnt(0)
	v_add_f32_e32 v5, v5, v26
	ds_swizzle_b32 v26, v5 offset:swizzle(SWAP,4)
	s_waitcnt lgkmcnt(0)
	v_add_f32_e32 v5, v5, v26
	ds_swizzle_b32 v26, v5 offset:swizzle(SWAP,8)
	s_waitcnt lgkmcnt(0)
	v_add_f32_e32 v5, v5, v26
	ds_swizzle_b32 v26, v5 offset:swizzle(SWAP,16)
	s_waitcnt lgkmcnt(0)
	v_add_f32_e32 v5, v5, v26
	v_mov_b32_e32 v26, v5
	s_nop 1
	v_permlane32_swap_b32_e32 v5, v26
	v_add_f32_e32 v5, v5, v26
	v_fmamk_f32 v5, v5, 0x3a800000, v4
	v_mul_f32_e32 v26, 0x4b800000, v5
	v_cmp_gt_f32_e32 vcc, s1, v5
	s_nop 1
	v_cndmask_b32_e32 v5, v5, v26, vcc
	v_rsq_f32_e32 v5, v5
	s_nop 0
	v_mul_f32_e32 v26, 0x45800000, v5
	v_cndmask_b32_e32 v26, v5, v26, vcc
	v_pk_mul_f32 v[56:57], v[26:27], v[56:57] op_sel_hi:[0,1]
	v_pk_mul_f32 v[58:59], v[26:27], v[58:59] op_sel_hi:[0,1]
	v_pk_mul_f32 v[58:59], v[42:43], v[58:59]
	v_pk_mul_f32 v[56:57], v[40:41], v[56:57]
	global_store_dwordx4 v[72:73], v[56:59], off
	v_pk_mul_f32 v[62:63], v[26:27], v[62:63] op_sel_hi:[0,1]
	v_pk_mul_f32 v[60:61], v[26:27], v[60:61] op_sel_hi:[0,1]
	v_pk_mul_f32 v[60:61], v[44:45], v[60:61]
	v_pk_mul_f32 v[62:63], v[46:47], v[62:63]
	global_store_dwordx4 v[72:73], v[60:63], off offset:1024
	v_pk_mul_f32 v[66:67], v[26:27], v[66:67] op_sel_hi:[0,1]
	v_pk_mul_f32 v[64:65], v[26:27], v[64:65] op_sel_hi:[0,1]
	v_pk_mul_f32 v[64:65], v[48:49], v[64:65]
	v_pk_mul_f32 v[66:67], v[50:51], v[66:67]
	global_store_dwordx4 v[72:73], v[64:67], off offset:2048
	v_pk_mul_f32 v[70:71], v[26:27], v[70:71] op_sel_hi:[0,1]
	v_pk_mul_f32 v[68:69], v[26:27], v[68:69] op_sel_hi:[0,1]
	v_pk_mul_f32 v[68:69], v[52:53], v[68:69]
	v_pk_mul_f32 v[70:71], v[54:55], v[70:71]
	global_store_dwordx4 v[72:73], v[68:71], off offset:3072
.Lfn_done:
.LBB0_1684:
	s_endpgm

; __global__ void __launch_bounds__(512) mega_fwd(Params P) {
	.amdhsa_kernel _Z8mega_fwd6Params
		.amdhsa_group_segment_fixed_size 0
		.amdhsa_private_segment_fixed_size 0
		.amdhsa_kernarg_size 464
		.amdhsa_user_sgpr_count 2
		.amdhsa_user_sgpr_dispatch_ptr 0
		.amdhsa_user_sgpr_queue_ptr 0
		.amdhsa_user_sgpr_kernarg_segment_ptr 1
		.amdhsa_user_sgpr_dispatch_id 0
		.amdhsa_user_sgpr_kernarg_preload_length 0
		.amdhsa_user_sgpr_kernarg_preload_offset 0
		.amdhsa_user_sgpr_private_segment_size 0
		.amdhsa_uses_dynamic_stack 0
		.amdhsa_enable_private_segment 0
		.amdhsa_system_sgpr_workgroup_id_x 1
		.amdhsa_system_sgpr_workgroup_id_y 0
		.amdhsa_system_sgpr_workgroup_id_z 0
		.amdhsa_system_sgpr_workgroup_info 0
		.amdhsa_system_vgpr_workitem_id 2
		.amdhsa_next_free_vgpr 256
		.amdhsa_next_free_sgpr 102
		.amdhsa_accum_offset 256
		.amdhsa_reserve_vcc 1
		.amdhsa_float_round_mode_32 0
		.amdhsa_float_round_mode_16_64 0
		.amdhsa_float_denorm_mode_32 3
		.amdhsa_float_denorm_mode_16_64 3
		.amdhsa_dx10_clamp 1
		.amdhsa_ieee_mode 1
		.amdhsa_fp16_overflow 0
		.amdhsa_tg_split 0
		.amdhsa_exception_fp_ieee_invalid_op 0
		.amdhsa_exception_fp_denorm_src 0
		.amdhsa_exception_fp_ieee_div_zero 0
		.amdhsa_exception_fp_ieee_overflow 0
		.amdhsa_exception_fp_ieee_underflow 0
		.amdhsa_exception_fp_ieee_inexact 0
		.amdhsa_exception_int_div_zero 0
	.end_amdhsa_kernel

; __global__ void __launch_bounds__(512) mega_fwd(Params P) {
amdhsa.kernels:
  - .agpr_count:     0
    .args:
      - .offset:         0
        .size:           208
        .value_kind:     by_value
      - .offset:         208
        .size:           4
        .value_kind:     hidden_block_count_x
      - .offset:         212
        .size:           4
        .value_kind:     hidden_block_count_y
      - .offset:         216
        .size:           4
        .value_kind:     hidden_block_count_z
      - .offset:         220
        .size:           2
        .value_kind:     hidden_group_size_x
      - .offset:         222
        .size:           2
        .value_kind:     hidden_group_size_y
      - .offset:         224
        .size:           2
        .value_kind:     hidden_group_size_z
      - .offset:         226
        .size:           2
        .value_kind:     hidden_remainder_x
      - .offset:         228
        .size:           2
        .value_kind:     hidden_remainder_y
      - .offset:         230
        .size:           2
        .value_kind:     hidden_remainder_z
      - .offset:         248
        .size:           8
        .value_kind:     hidden_global_offset_x
      - .offset:         256
        .size:           8
        .value_kind:     hidden_global_offset_y
      - .offset:         264
        .size:           8
        .value_kind:     hidden_global_offset_z
      - .offset:         272
        .size:           2
        .value_kind:     hidden_grid_dims
      - .offset:         296
        .size:           8
        .value_kind:     hidden_multigrid_sync_arg
      - .offset:         328
        .size:           4
        .value_kind:     hidden_dynamic_lds_size
    .group_segment_fixed_size: 0
    .kernarg_segment_align: 8
    .kernarg_segment_size: 464
    .language:       OpenCL C
    .language_version:
      - 2
      - 0
    .max_flat_workgroup_size: 512
    .name:           _Z8mega_fwd6Params
    .private_segment_fixed_size: 0
    .sgpr_count:     108
    .sgpr_spill_count: 96
    .symbol:         _Z8mega_fwd6Params.kd
    .uniform_work_group_size: 1
    .uses_dynamic_stack: false
    .vgpr_count:     256
    .vgpr_spill_count: 0
    .wavefront_size: 64
